# peel + plain SwiGLU stores + drop redundant post-barrier lgkmcnt(0) and no-op setprio pairs in K-loops
# baseline (speedup 1.0000x reference)
.LBB0_191:
	s_ashr_i32 s39, s38, 31
	s_lshl_b64 s[40:41], s[38:39], 19
	s_add_u32 s40, s65, s40
	s_addc_u32 s41, s64, s41
	s_and_b64 s[42:43], s[4:5], exec
	s_cselect_b32 s39, s41, s47
	s_cselect_b32 s78, s40, s46
	s_ashr_i32 s37, s36, 31
	s_lshl_b64 s[42:43], s[36:37], 19
	s_add_u32 s42, s67, s42
	s_addc_u32 s43, s66, s43
	s_and_b64 s[80:81], s[4:5], exec
	s_cselect_b32 s37, s43, s49
	s_cselect_b32 s79, s42, s48
	s_add_u32 s46, s46, 0x40080
	s_addc_u32 s47, s47, 0
	s_add_u32 s80, s48, 0x100
	s_addc_u32 s81, s49, 0
	s_mov_b32 s82, -2
	s_add_u32 s48, s46, 0xfffc0080
	s_addc_u32 s49, s47, -1
	s_add_i32 s83, 0, 0x10000
	s_cmp_eq_u32 s82, 12
	s_cselect_b32 s49, s39, s49
	s_cselect_b32 s48, s78, s48
	v_add_u32_e32 v140, s83, v146
	s_cselect_b32 s85, s37, s81
	s_cselect_b32 s84, s79, s80
	s_add_i32 s86, 0, 0x14000
	ds_read_b128 v[136:139], v140
	ds_read_b128 v[152:155], v140 offset:1024
	ds_read_b128 v[156:159], v140 offset:2048
	ds_read_b128 v[160:163], v140 offset:3072
	v_add_u32_e32 v140, s86, v146
	ds_read_b128 v[164:167], v140
	ds_read_b128 v[168:171], v140 offset:1024
	ds_read_b128 v[172:175], v140 offset:2048
	ds_read_b128 v[176:179], v140 offset:3072
	v_lshl_add_u64 v[140:141], s[46:47], 0, v[132:133]
	s_add_i32 m0, s45, 0xc000
	ds_read_b128 v[180:183], v150
	ds_read_b128 v[184:187], v150 offset:1024
	ds_read_b128 v[188:191], v150 offset:2048
	ds_read_b128 v[192:195], v150 offset:3072
	ds_read_b128 v[196:199], v150 offset:4096
	ds_read_b128 v[200:203], v150 offset:5120
	ds_read_b128 v[204:207], v150 offset:6144
	ds_read_b128 v[208:211], v150 offset:7168
	global_load_lds_dwordx4 v[140:141], off
	v_lshl_add_u64 v[140:141], v[140:141], 0, s[12:13]
	s_add_i32 m0, s45, 0xe000
	s_nop 0
	global_load_lds_dwordx4 v[140:141], off
	s_waitcnt vmcnt(8)
	s_waitcnt lgkmcnt(0)
	s_barrier
	s_setprio 1
	v_mfma_f32_16x16x32_bf16 v[124:127], v[136:139], v[180:183], 0
	v_mfma_f32_16x16x32_bf16 v[120:123], v[156:159], v[180:183], 0
	v_mfma_f32_16x16x32_bf16 v[112:115], v[136:139], v[188:191], 0
	v_mfma_f32_16x16x32_bf16 v[104:107], v[156:159], v[188:191], 0
	v_mfma_f32_16x16x32_bf16 v[96:99], v[136:139], v[196:199], 0
	v_mfma_f32_16x16x32_bf16 v[88:91], v[156:159], v[196:199], 0
	v_mfma_f32_16x16x32_bf16 v[80:83], v[136:139], v[204:207], 0
	v_mfma_f32_16x16x32_bf16 v[72:75], v[156:159], v[204:207], 0
	v_mfma_f32_16x16x32_bf16 v[124:127], v[152:155], v[184:187], v[124:127]
	v_mfma_f32_16x16x32_bf16 v[120:123], v[160:163], v[184:187], v[120:123]
	v_mfma_f32_16x16x32_bf16 v[112:115], v[152:155], v[192:195], v[112:115]
	v_mfma_f32_16x16x32_bf16 v[104:107], v[160:163], v[192:195], v[104:107]
	v_mfma_f32_16x16x32_bf16 v[96:99], v[152:155], v[200:203], v[96:99]
	v_mfma_f32_16x16x32_bf16 v[88:91], v[160:163], v[200:203], v[88:91]
	v_mfma_f32_16x16x32_bf16 v[80:83], v[152:155], v[208:211], v[80:83]
	v_mfma_f32_16x16x32_bf16 v[72:75], v[160:163], v[208:211], v[72:75]
	v_mfma_f32_16x16x32_bf16 v[116:119], v[164:167], v[180:183], 0
	v_mfma_f32_16x16x32_bf16 v[108:111], v[172:175], v[180:183], 0
	v_mfma_f32_16x16x32_bf16 v[100:103], v[164:167], v[188:191], 0
	v_mfma_f32_16x16x32_bf16 v[92:95], v[172:175], v[188:191], 0
	v_mfma_f32_16x16x32_bf16 v[84:87], v[164:167], v[196:199], 0
	v_mfma_f32_16x16x32_bf16 v[76:79], v[172:175], v[196:199], 0
	v_mfma_f32_16x16x32_bf16 v[68:71], v[164:167], v[204:207], 0
	v_mfma_f32_16x16x32_bf16 v[64:67], v[172:175], v[204:207], 0
	v_mfma_f32_16x16x32_bf16 v[116:119], v[168:171], v[184:187], v[116:119]
	v_mfma_f32_16x16x32_bf16 v[108:111], v[176:179], v[184:187], v[108:111]
	v_mfma_f32_16x16x32_bf16 v[100:103], v[168:171], v[192:195], v[100:103]
	v_mfma_f32_16x16x32_bf16 v[92:95], v[176:179], v[192:195], v[92:95]
	v_mfma_f32_16x16x32_bf16 v[84:87], v[168:171], v[200:203], v[84:87]
	v_mfma_f32_16x16x32_bf16 v[76:79], v[176:179], v[200:203], v[76:79]
	v_mfma_f32_16x16x32_bf16 v[68:71], v[168:171], v[208:211], v[68:71]
	v_mfma_f32_16x16x32_bf16 v[64:67], v[176:179], v[208:211], v[64:67]
	s_setprio 0
	s_barrier
	s_add_i32 s83, s83, s69
	v_lshl_add_u64 v[140:141], s[84:85], 0, v[128:129]
	s_mov_b32 m0, s83
	ds_read_b128 v[180:183], v150 offset:16384
	ds_read_b128 v[184:187], v150 offset:17408
	ds_read_b128 v[188:191], v150 offset:18432
	ds_read_b128 v[192:195], v150 offset:19456
	ds_read_b128 v[196:199], v150 offset:20480
	ds_read_b128 v[200:203], v150 offset:21504
	ds_read_b128 v[204:207], v150 offset:22528
	ds_read_b128 v[208:211], v150 offset:23552
	global_load_lds_dwordx4 v[140:141], off
	v_lshl_add_u64 v[212:213], v[140:141], 0, s[12:13]
	s_add_i32 m0, s83, 0x2000
	s_add_i32 s83, s86, s69
	global_load_lds_dwordx4 v[212:213], off
	v_lshl_add_u64 v[212:213], v[140:141], 0, s[14:15]
	s_mov_b32 m0, s83
	s_nop 0
	global_load_lds_dwordx4 v[212:213], off
	v_lshl_add_u64 v[212:213], v[140:141], 0, s[16:17]
	s_add_i32 m0, s83, 0x2000
	s_nop 0
	global_load_lds_dwordx4 v[212:213], off
	v_lshl_add_u64 v[212:213], s[48:49], 0, v[130:131]
	s_mov_b32 m0, s45
	v_lshl_add_u64 v[214:215], v[212:213], 0, s[12:13]
	global_load_lds_dwordx4 v[212:213], off
	s_mov_b32 m0, s71
	s_nop 0
	global_load_lds_dwordx4 v[214:215], off
	s_waitcnt vmcnt(8)
	s_waitcnt lgkmcnt(0)
	s_barrier
	s_setprio 1
	v_mfma_f32_16x16x32_bf16 v[60:63], v[136:139], v[180:183], 0
	v_mfma_f32_16x16x32_bf16 v[56:59], v[156:159], v[180:183], 0
	v_mfma_f32_16x16x32_bf16 v[48:51], v[136:139], v[188:191], 0
	v_mfma_f32_16x16x32_bf16 v[40:43], v[156:159], v[188:191], 0
	v_mfma_f32_16x16x32_bf16 v[32:35], v[136:139], v[196:199], 0
	v_mfma_f32_16x16x32_bf16 v[24:27], v[156:159], v[196:199], 0
	v_mfma_f32_16x16x32_bf16 v[16:19], v[136:139], v[204:207], 0
	v_mfma_f32_16x16x32_bf16 v[8:11], v[156:159], v[204:207], 0
	v_mfma_f32_16x16x32_bf16 v[60:63], v[152:155], v[184:187], v[60:63]
	v_mfma_f32_16x16x32_bf16 v[56:59], v[160:163], v[184:187], v[56:59]
	v_mfma_f32_16x16x32_bf16 v[48:51], v[152:155], v[192:195], v[48:51]
	v_mfma_f32_16x16x32_bf16 v[40:43], v[160:163], v[192:195], v[40:43]
	v_mfma_f32_16x16x32_bf16 v[32:35], v[152:155], v[200:203], v[32:35]
	v_mfma_f32_16x16x32_bf16 v[24:27], v[160:163], v[200:203], v[24:27]
	v_mfma_f32_16x16x32_bf16 v[16:19], v[152:155], v[208:211], v[16:19]
	v_mfma_f32_16x16x32_bf16 v[8:11], v[160:163], v[208:211], v[8:11]
	v_mfma_f32_16x16x32_bf16 v[52:55], v[164:167], v[180:183], 0
	v_mfma_f32_16x16x32_bf16 v[44:47], v[172:175], v[180:183], 0
	v_mfma_f32_16x16x32_bf16 v[36:39], v[164:167], v[188:191], 0
	v_mfma_f32_16x16x32_bf16 v[28:31], v[172:175], v[188:191], 0
	v_mfma_f32_16x16x32_bf16 v[20:23], v[164:167], v[196:199], 0
	v_mfma_f32_16x16x32_bf16 v[12:15], v[172:175], v[196:199], 0
	v_mfma_f32_16x16x32_bf16 v[4:7], v[164:167], v[204:207], 0
	v_mfma_f32_16x16x32_bf16 v[0:3], v[172:175], v[204:207], 0
	v_mfma_f32_16x16x32_bf16 v[52:55], v[168:171], v[184:187], v[52:55]
	v_mfma_f32_16x16x32_bf16 v[44:47], v[176:179], v[184:187], v[44:47]
	v_mfma_f32_16x16x32_bf16 v[36:39], v[168:171], v[192:195], v[36:39]
	v_mfma_f32_16x16x32_bf16 v[28:31], v[176:179], v[192:195], v[28:31]
	v_mfma_f32_16x16x32_bf16 v[20:23], v[168:171], v[200:203], v[20:23]
	v_mfma_f32_16x16x32_bf16 v[12:15], v[176:179], v[200:203], v[12:15]
	v_mfma_f32_16x16x32_bf16 v[4:7], v[168:171], v[208:211], v[4:7]
	v_mfma_f32_16x16x32_bf16 v[0:3], v[176:179], v[208:211], v[0:3]
	s_setprio 0
	s_barrier
	s_add_i32 s48, 0, 0x18000
	v_add_u32_e32 v151, s48, v146
	s_add_i32 s49, 0, 0x1c000
	ds_read_b128 v[136:139], v151
	ds_read_b128 v[152:155], v151 offset:1024
	ds_read_b128 v[156:159], v151 offset:2048
	ds_read_b128 v[160:163], v151 offset:3072
	v_add_u32_e32 v151, s49, v146
	ds_read_b128 v[164:167], v151
	ds_read_b128 v[168:171], v151 offset:1024
	ds_read_b128 v[172:175], v151 offset:2048
	ds_read_b128 v[176:179], v151 offset:3072
	s_mov_b32 m0, s72
	v_lshl_add_u64 v[214:215], v[212:213], 0, s[14:15]
	ds_read_b128 v[180:183], v150 offset:32768
	ds_read_b128 v[184:187], v150 offset:33792
	ds_read_b128 v[188:191], v150 offset:34816
	ds_read_b128 v[192:195], v150 offset:35840
	ds_read_b128 v[196:199], v150 offset:36864
	ds_read_b128 v[200:203], v150 offset:37888
	ds_read_b128 v[204:207], v150 offset:38912
	ds_read_b128 v[208:211], v150 offset:39936
	global_load_lds_dwordx4 v[214:215], off
	v_lshl_add_u64 v[214:215], v[212:213], 0, s[16:17]
	s_mov_b32 m0, s73
	s_nop 0
	global_load_lds_dwordx4 v[214:215], off
	s_waitcnt vmcnt(8)
	s_waitcnt lgkmcnt(0)
	s_barrier
	s_setprio 1
	v_mfma_f32_16x16x32_bf16 v[124:127], v[136:139], v[180:183], v[124:127]
	v_mfma_f32_16x16x32_bf16 v[120:123], v[156:159], v[180:183], v[120:123]
	v_mfma_f32_16x16x32_bf16 v[112:115], v[136:139], v[188:191], v[112:115]
	v_mfma_f32_16x16x32_bf16 v[104:107], v[156:159], v[188:191], v[104:107]
	v_mfma_f32_16x16x32_bf16 v[96:99], v[136:139], v[196:199], v[96:99]
	v_mfma_f32_16x16x32_bf16 v[88:91], v[156:159], v[196:199], v[88:91]
	v_mfma_f32_16x16x32_bf16 v[80:83], v[136:139], v[204:207], v[80:83]
	v_mfma_f32_16x16x32_bf16 v[72:75], v[156:159], v[204:207], v[72:75]
	v_mfma_f32_16x16x32_bf16 v[124:127], v[152:155], v[184:187], v[124:127]
	v_mfma_f32_16x16x32_bf16 v[120:123], v[160:163], v[184:187], v[120:123]
	v_mfma_f32_16x16x32_bf16 v[112:115], v[152:155], v[192:195], v[112:115]
	v_mfma_f32_16x16x32_bf16 v[104:107], v[160:163], v[192:195], v[104:107]
	v_mfma_f32_16x16x32_bf16 v[96:99], v[152:155], v[200:203], v[96:99]
	v_mfma_f32_16x16x32_bf16 v[88:91], v[160:163], v[200:203], v[88:91]
	v_mfma_f32_16x16x32_bf16 v[80:83], v[152:155], v[208:211], v[80:83]
	v_mfma_f32_16x16x32_bf16 v[72:75], v[160:163], v[208:211], v[72:75]
	v_mfma_f32_16x16x32_bf16 v[116:119], v[164:167], v[180:183], v[116:119]
	v_mfma_f32_16x16x32_bf16 v[108:111], v[172:175], v[180:183], v[108:111]
	v_mfma_f32_16x16x32_bf16 v[100:103], v[164:167], v[188:191], v[100:103]
	v_mfma_f32_16x16x32_bf16 v[92:95], v[172:175], v[188:191], v[92:95]
	v_mfma_f32_16x16x32_bf16 v[84:87], v[164:167], v[196:199], v[84:87]
	v_mfma_f32_16x16x32_bf16 v[76:79], v[172:175], v[196:199], v[76:79]
	v_mfma_f32_16x16x32_bf16 v[68:71], v[164:167], v[204:207], v[68:71]
	v_mfma_f32_16x16x32_bf16 v[64:67], v[172:175], v[204:207], v[64:67]
	v_mfma_f32_16x16x32_bf16 v[116:119], v[168:171], v[184:187], v[116:119]
	v_mfma_f32_16x16x32_bf16 v[108:111], v[176:179], v[184:187], v[108:111]
	v_mfma_f32_16x16x32_bf16 v[100:103], v[168:171], v[192:195], v[100:103]
	v_mfma_f32_16x16x32_bf16 v[92:95], v[176:179], v[192:195], v[92:95]
	v_mfma_f32_16x16x32_bf16 v[84:87], v[168:171], v[200:203], v[84:87]
	v_mfma_f32_16x16x32_bf16 v[76:79], v[176:179], v[200:203], v[76:79]
	v_mfma_f32_16x16x32_bf16 v[68:71], v[168:171], v[208:211], v[68:71]
	v_mfma_f32_16x16x32_bf16 v[64:67], v[176:179], v[208:211], v[64:67]
	s_setprio 0
	s_barrier
	s_add_i32 s48, s48, s69
	v_lshl_add_u64 v[214:215], v[140:141], 0, s[18:19]
	s_mov_b32 m0, s48
	ds_read_b128 v[180:183], v150 offset:49152
	ds_read_b128 v[184:187], v150 offset:50176
	ds_read_b128 v[188:191], v150 offset:51200
	ds_read_b128 v[192:195], v150 offset:52224
	ds_read_b128 v[196:199], v150 offset:53248
	ds_read_b128 v[200:203], v150 offset:54272
	ds_read_b128 v[204:207], v150 offset:55296
	ds_read_b128 v[208:211], v150 offset:56320
	global_load_lds_dwordx4 v[214:215], off
	v_lshl_add_u64 v[214:215], v[140:141], 0, s[20:21]
	s_add_i32 m0, s48, 0x2000
	s_add_i32 s48, s49, s69
	global_load_lds_dwordx4 v[214:215], off
	v_lshl_add_u64 v[214:215], v[140:141], 0, s[22:23]
	s_mov_b32 m0, s48
	v_lshl_add_u64 v[140:141], v[140:141], 0, s[24:25]
	global_load_lds_dwordx4 v[214:215], off
	s_add_i32 m0, s48, 0x2000
	s_nop 0
	global_load_lds_dwordx4 v[140:141], off
	v_lshl_add_u64 v[140:141], v[212:213], 0, s[18:19]
	s_mov_b32 m0, s10
	s_nop 0
	global_load_lds_dwordx4 v[140:141], off
	v_lshl_add_u64 v[140:141], v[212:213], 0, s[20:21]
	s_mov_b32 m0, s74
	s_nop 0
	global_load_lds_dwordx4 v[140:141], off
	s_waitcnt vmcnt(8)
	s_waitcnt lgkmcnt(0)
	s_barrier
	s_setprio 1
	v_mfma_f32_16x16x32_bf16 v[60:63], v[136:139], v[180:183], v[60:63]
	v_mfma_f32_16x16x32_bf16 v[56:59], v[156:159], v[180:183], v[56:59]
	v_mfma_f32_16x16x32_bf16 v[48:51], v[136:139], v[188:191], v[48:51]
	v_mfma_f32_16x16x32_bf16 v[40:43], v[156:159], v[188:191], v[40:43]
	v_mfma_f32_16x16x32_bf16 v[32:35], v[136:139], v[196:199], v[32:35]
	v_mfma_f32_16x16x32_bf16 v[24:27], v[156:159], v[196:199], v[24:27]
	v_mfma_f32_16x16x32_bf16 v[16:19], v[136:139], v[204:207], v[16:19]
	v_mfma_f32_16x16x32_bf16 v[8:11], v[156:159], v[204:207], v[8:11]
	v_mfma_f32_16x16x32_bf16 v[60:63], v[152:155], v[184:187], v[60:63]
	v_mfma_f32_16x16x32_bf16 v[56:59], v[160:163], v[184:187], v[56:59]
	v_mfma_f32_16x16x32_bf16 v[48:51], v[152:155], v[192:195], v[48:51]
	v_mfma_f32_16x16x32_bf16 v[40:43], v[160:163], v[192:195], v[40:43]
	v_mfma_f32_16x16x32_bf16 v[32:35], v[152:155], v[200:203], v[32:35]
	v_mfma_f32_16x16x32_bf16 v[24:27], v[160:163], v[200:203], v[24:27]
	v_mfma_f32_16x16x32_bf16 v[16:19], v[152:155], v[208:211], v[16:19]
	v_mfma_f32_16x16x32_bf16 v[8:11], v[160:163], v[208:211], v[8:11]
	v_mfma_f32_16x16x32_bf16 v[52:55], v[164:167], v[180:183], v[52:55]
	v_mfma_f32_16x16x32_bf16 v[44:47], v[172:175], v[180:183], v[44:47]
	v_mfma_f32_16x16x32_bf16 v[36:39], v[164:167], v[188:191], v[36:39]
	v_mfma_f32_16x16x32_bf16 v[28:31], v[172:175], v[188:191], v[28:31]
	v_mfma_f32_16x16x32_bf16 v[20:23], v[164:167], v[196:199], v[20:23]
	v_mfma_f32_16x16x32_bf16 v[12:15], v[172:175], v[196:199], v[12:15]
	v_mfma_f32_16x16x32_bf16 v[4:7], v[164:167], v[204:207], v[4:7]
	v_mfma_f32_16x16x32_bf16 v[0:3], v[172:175], v[204:207], v[0:3]
	v_mfma_f32_16x16x32_bf16 v[52:55], v[168:171], v[184:187], v[52:55]
	v_mfma_f32_16x16x32_bf16 v[44:47], v[176:179], v[184:187], v[44:47]
	v_mfma_f32_16x16x32_bf16 v[36:39], v[168:171], v[192:195], v[36:39]
	v_mfma_f32_16x16x32_bf16 v[28:31], v[176:179], v[192:195], v[28:31]
	v_mfma_f32_16x16x32_bf16 v[20:23], v[168:171], v[200:203], v[20:23]
	v_mfma_f32_16x16x32_bf16 v[12:15], v[176:179], v[200:203], v[12:15]
	v_mfma_f32_16x16x32_bf16 v[4:7], v[168:171], v[208:211], v[4:7]
	v_mfma_f32_16x16x32_bf16 v[0:3], v[176:179], v[208:211], v[0:3]
	s_setprio 0
	s_barrier
	s_add_i32 s82, s82, 2
	s_add_u32 s46, s46, 0x100
	s_addc_u32 s47, s47, 0
	s_add_u32 s80, s80, 0x100
	s_addc_u32 s81, s81, 0
	s_cmp_gt_u32 s82, 13
.LBB0_192:
	s_add_u32 s48, s46, 0xfffc0080
	s_addc_u32 s49, s47, -1
	s_add_i32 s83, 0, 0x10000
	s_cmp_eq_u32 s82, 12
	s_cselect_b32 s49, s39, s49
	s_cselect_b32 s48, s78, s48
	v_add_u32_e32 v140, s83, v146
	s_cselect_b32 s85, s37, s81
	s_cselect_b32 s84, s79, s80
	s_add_i32 s86, 0, 0x14000
	ds_read_b128 v[136:139], v140
	ds_read_b128 v[152:155], v140 offset:1024
	ds_read_b128 v[156:159], v140 offset:2048
	ds_read_b128 v[160:163], v140 offset:3072
	v_add_u32_e32 v140, s86, v146
	ds_read_b128 v[164:167], v140
	ds_read_b128 v[168:171], v140 offset:1024
	ds_read_b128 v[172:175], v140 offset:2048
	ds_read_b128 v[176:179], v140 offset:3072
	v_lshl_add_u64 v[140:141], s[46:47], 0, v[132:133]
	s_add_i32 m0, s45, 0xc000
	ds_read_b128 v[180:183], v150
	ds_read_b128 v[184:187], v150 offset:1024
	ds_read_b128 v[188:191], v150 offset:2048
	ds_read_b128 v[192:195], v150 offset:3072
	ds_read_b128 v[196:199], v150 offset:4096
	ds_read_b128 v[200:203], v150 offset:5120
	ds_read_b128 v[204:207], v150 offset:6144
	ds_read_b128 v[208:211], v150 offset:7168
	global_load_lds_dwordx4 v[140:141], off
	v_lshl_add_u64 v[140:141], v[140:141], 0, s[12:13]
	s_add_i32 m0, s45, 0xe000
	s_nop 0
	global_load_lds_dwordx4 v[140:141], off
	s_waitcnt vmcnt(8)
	s_waitcnt lgkmcnt(0)
	s_barrier
	s_setprio 1
	v_mfma_f32_16x16x32_bf16 v[124:127], v[136:139], v[180:183], v[124:127]
	v_mfma_f32_16x16x32_bf16 v[120:123], v[156:159], v[180:183], v[120:123]
	v_mfma_f32_16x16x32_bf16 v[112:115], v[136:139], v[188:191], v[112:115]
	v_mfma_f32_16x16x32_bf16 v[104:107], v[156:159], v[188:191], v[104:107]
	v_mfma_f32_16x16x32_bf16 v[96:99], v[136:139], v[196:199], v[96:99]
	v_mfma_f32_16x16x32_bf16 v[88:91], v[156:159], v[196:199], v[88:91]
	v_mfma_f32_16x16x32_bf16 v[80:83], v[136:139], v[204:207], v[80:83]
	v_mfma_f32_16x16x32_bf16 v[72:75], v[156:159], v[204:207], v[72:75]
	v_mfma_f32_16x16x32_bf16 v[124:127], v[152:155], v[184:187], v[124:127]
	v_mfma_f32_16x16x32_bf16 v[120:123], v[160:163], v[184:187], v[120:123]
	v_mfma_f32_16x16x32_bf16 v[112:115], v[152:155], v[192:195], v[112:115]
	v_mfma_f32_16x16x32_bf16 v[104:107], v[160:163], v[192:195], v[104:107]
	v_mfma_f32_16x16x32_bf16 v[96:99], v[152:155], v[200:203], v[96:99]
	v_mfma_f32_16x16x32_bf16 v[88:91], v[160:163], v[200:203], v[88:91]
	v_mfma_f32_16x16x32_bf16 v[80:83], v[152:155], v[208:211], v[80:83]
	v_mfma_f32_16x16x32_bf16 v[72:75], v[160:163], v[208:211], v[72:75]
	v_mfma_f32_16x16x32_bf16 v[116:119], v[164:167], v[180:183], v[116:119]
	v_mfma_f32_16x16x32_bf16 v[108:111], v[172:175], v[180:183], v[108:111]
	v_mfma_f32_16x16x32_bf16 v[100:103], v[164:167], v[188:191], v[100:103]
	v_mfma_f32_16x16x32_bf16 v[92:95], v[172:175], v[188:191], v[92:95]
	v_mfma_f32_16x16x32_bf16 v[84:87], v[164:167], v[196:199], v[84:87]
	v_mfma_f32_16x16x32_bf16 v[76:79], v[172:175], v[196:199], v[76:79]
	v_mfma_f32_16x16x32_bf16 v[68:71], v[164:167], v[204:207], v[68:71]
	v_mfma_f32_16x16x32_bf16 v[64:67], v[172:175], v[204:207], v[64:67]
	v_mfma_f32_16x16x32_bf16 v[116:119], v[168:171], v[184:187], v[116:119]
	v_mfma_f32_16x16x32_bf16 v[108:111], v[176:179], v[184:187], v[108:111]
	v_mfma_f32_16x16x32_bf16 v[100:103], v[168:171], v[192:195], v[100:103]
	v_mfma_f32_16x16x32_bf16 v[92:95], v[176:179], v[192:195], v[92:95]
	v_mfma_f32_16x16x32_bf16 v[84:87], v[168:171], v[200:203], v[84:87]
	v_mfma_f32_16x16x32_bf16 v[76:79], v[176:179], v[200:203], v[76:79]
	v_mfma_f32_16x16x32_bf16 v[68:71], v[168:171], v[208:211], v[68:71]
	v_mfma_f32_16x16x32_bf16 v[64:67], v[176:179], v[208:211], v[64:67]
	s_setprio 0
	s_barrier
	s_add_i32 s83, s83, s69
	v_lshl_add_u64 v[140:141], s[84:85], 0, v[128:129]
	s_mov_b32 m0, s83
	ds_read_b128 v[180:183], v150 offset:16384
	ds_read_b128 v[184:187], v150 offset:17408
	ds_read_b128 v[188:191], v150 offset:18432
	ds_read_b128 v[192:195], v150 offset:19456
	ds_read_b128 v[196:199], v150 offset:20480
	ds_read_b128 v[200:203], v150 offset:21504
	ds_read_b128 v[204:207], v150 offset:22528
	ds_read_b128 v[208:211], v150 offset:23552
	global_load_lds_dwordx4 v[140:141], off
	v_lshl_add_u64 v[212:213], v[140:141], 0, s[12:13]
	s_add_i32 m0, s83, 0x2000
	s_add_i32 s83, s86, s69
	global_load_lds_dwordx4 v[212:213], off
	v_lshl_add_u64 v[212:213], v[140:141], 0, s[14:15]
	s_mov_b32 m0, s83
	s_nop 0
	global_load_lds_dwordx4 v[212:213], off
	v_lshl_add_u64 v[212:213], v[140:141], 0, s[16:17]
	s_add_i32 m0, s83, 0x2000
	s_nop 0
	global_load_lds_dwordx4 v[212:213], off
	v_lshl_add_u64 v[212:213], s[48:49], 0, v[130:131]
	s_mov_b32 m0, s45
	v_lshl_add_u64 v[214:215], v[212:213], 0, s[12:13]
	global_load_lds_dwordx4 v[212:213], off
	s_mov_b32 m0, s71
	s_nop 0
	global_load_lds_dwordx4 v[214:215], off
	s_waitcnt vmcnt(8)
	s_waitcnt lgkmcnt(0)
	s_barrier
	s_setprio 1
	v_mfma_f32_16x16x32_bf16 v[60:63], v[136:139], v[180:183], v[60:63]
	v_mfma_f32_16x16x32_bf16 v[56:59], v[156:159], v[180:183], v[56:59]
	v_mfma_f32_16x16x32_bf16 v[48:51], v[136:139], v[188:191], v[48:51]
	v_mfma_f32_16x16x32_bf16 v[40:43], v[156:159], v[188:191], v[40:43]
	v_mfma_f32_16x16x32_bf16 v[32:35], v[136:139], v[196:199], v[32:35]
	v_mfma_f32_16x16x32_bf16 v[24:27], v[156:159], v[196:199], v[24:27]
	v_mfma_f32_16x16x32_bf16 v[16:19], v[136:139], v[204:207], v[16:19]
	v_mfma_f32_16x16x32_bf16 v[8:11], v[156:159], v[204:207], v[8:11]
	v_mfma_f32_16x16x32_bf16 v[60:63], v[152:155], v[184:187], v[60:63]
	v_mfma_f32_16x16x32_bf16 v[56:59], v[160:163], v[184:187], v[56:59]
	v_mfma_f32_16x16x32_bf16 v[48:51], v[152:155], v[192:195], v[48:51]
	v_mfma_f32_16x16x32_bf16 v[40:43], v[160:163], v[192:195], v[40:43]
	v_mfma_f32_16x16x32_bf16 v[32:35], v[152:155], v[200:203], v[32:35]
	v_mfma_f32_16x16x32_bf16 v[24:27], v[160:163], v[200:203], v[24:27]
	v_mfma_f32_16x16x32_bf16 v[16:19], v[152:155], v[208:211], v[16:19]
	v_mfma_f32_16x16x32_bf16 v[8:11], v[160:163], v[208:211], v[8:11]
	v_mfma_f32_16x16x32_bf16 v[52:55], v[164:167], v[180:183], v[52:55]
	v_mfma_f32_16x16x32_bf16 v[44:47], v[172:175], v[180:183], v[44:47]
	v_mfma_f32_16x16x32_bf16 v[36:39], v[164:167], v[188:191], v[36:39]
	v_mfma_f32_16x16x32_bf16 v[28:31], v[172:175], v[188:191], v[28:31]
	v_mfma_f32_16x16x32_bf16 v[20:23], v[164:167], v[196:199], v[20:23]
	v_mfma_f32_16x16x32_bf16 v[12:15], v[172:175], v[196:199], v[12:15]
	v_mfma_f32_16x16x32_bf16 v[4:7], v[164:167], v[204:207], v[4:7]
	v_mfma_f32_16x16x32_bf16 v[0:3], v[172:175], v[204:207], v[0:3]
	v_mfma_f32_16x16x32_bf16 v[52:55], v[168:171], v[184:187], v[52:55]
	v_mfma_f32_16x16x32_bf16 v[44:47], v[176:179], v[184:187], v[44:47]
	v_mfma_f32_16x16x32_bf16 v[36:39], v[168:171], v[192:195], v[36:39]
	v_mfma_f32_16x16x32_bf16 v[28:31], v[176:179], v[192:195], v[28:31]
	v_mfma_f32_16x16x32_bf16 v[20:23], v[168:171], v[200:203], v[20:23]
	v_mfma_f32_16x16x32_bf16 v[12:15], v[176:179], v[200:203], v[12:15]
	v_mfma_f32_16x16x32_bf16 v[4:7], v[168:171], v[208:211], v[4:7]
	v_mfma_f32_16x16x32_bf16 v[0:3], v[176:179], v[208:211], v[0:3]
	s_setprio 0
	s_barrier
	s_add_i32 s48, 0, 0x18000
	v_add_u32_e32 v151, s48, v146
	s_add_i32 s49, 0, 0x1c000
	ds_read_b128 v[136:139], v151
	ds_read_b128 v[152:155], v151 offset:1024
	ds_read_b128 v[156:159], v151 offset:2048
	ds_read_b128 v[160:163], v151 offset:3072
	v_add_u32_e32 v151, s49, v146
	ds_read_b128 v[164:167], v151
	ds_read_b128 v[168:171], v151 offset:1024
	ds_read_b128 v[172:175], v151 offset:2048
	ds_read_b128 v[176:179], v151 offset:3072
	s_mov_b32 m0, s72
	v_lshl_add_u64 v[214:215], v[212:213], 0, s[14:15]
	ds_read_b128 v[180:183], v150 offset:32768
	ds_read_b128 v[184:187], v150 offset:33792
	ds_read_b128 v[188:191], v150 offset:34816
	ds_read_b128 v[192:195], v150 offset:35840
	ds_read_b128 v[196:199], v150 offset:36864
	ds_read_b128 v[200:203], v150 offset:37888
	ds_read_b128 v[204:207], v150 offset:38912
	ds_read_b128 v[208:211], v150 offset:39936
	global_load_lds_dwordx4 v[214:215], off
	v_lshl_add_u64 v[214:215], v[212:213], 0, s[16:17]
	s_mov_b32 m0, s73
	s_nop 0
	global_load_lds_dwordx4 v[214:215], off
	s_waitcnt vmcnt(8)
	s_waitcnt lgkmcnt(0)
	s_barrier
	s_setprio 1
	v_mfma_f32_16x16x32_bf16 v[124:127], v[136:139], v[180:183], v[124:127]
	v_mfma_f32_16x16x32_bf16 v[120:123], v[156:159], v[180:183], v[120:123]
	v_mfma_f32_16x16x32_bf16 v[112:115], v[136:139], v[188:191], v[112:115]
	v_mfma_f32_16x16x32_bf16 v[104:107], v[156:159], v[188:191], v[104:107]
	v_mfma_f32_16x16x32_bf16 v[96:99], v[136:139], v[196:199], v[96:99]
	v_mfma_f32_16x16x32_bf16 v[88:91], v[156:159], v[196:199], v[88:91]
	v_mfma_f32_16x16x32_bf16 v[80:83], v[136:139], v[204:207], v[80:83]
	v_mfma_f32_16x16x32_bf16 v[72:75], v[156:159], v[204:207], v[72:75]
	v_mfma_f32_16x16x32_bf16 v[124:127], v[152:155], v[184:187], v[124:127]
	v_mfma_f32_16x16x32_bf16 v[120:123], v[160:163], v[184:187], v[120:123]
	v_mfma_f32_16x16x32_bf16 v[112:115], v[152:155], v[192:195], v[112:115]
	v_mfma_f32_16x16x32_bf16 v[104:107], v[160:163], v[192:195], v[104:107]
	v_mfma_f32_16x16x32_bf16 v[96:99], v[152:155], v[200:203], v[96:99]
	v_mfma_f32_16x16x32_bf16 v[88:91], v[160:163], v[200:203], v[88:91]
	v_mfma_f32_16x16x32_bf16 v[80:83], v[152:155], v[208:211], v[80:83]
	v_mfma_f32_16x16x32_bf16 v[72:75], v[160:163], v[208:211], v[72:75]
	v_mfma_f32_16x16x32_bf16 v[116:119], v[164:167], v[180:183], v[116:119]
	v_mfma_f32_16x16x32_bf16 v[108:111], v[172:175], v[180:183], v[108:111]
	v_mfma_f32_16x16x32_bf16 v[100:103], v[164:167], v[188:191], v[100:103]
	v_mfma_f32_16x16x32_bf16 v[92:95], v[172:175], v[188:191], v[92:95]
	v_mfma_f32_16x16x32_bf16 v[84:87], v[164:167], v[196:199], v[84:87]
	v_mfma_f32_16x16x32_bf16 v[76:79], v[172:175], v[196:199], v[76:79]
	v_mfma_f32_16x16x32_bf16 v[68:71], v[164:167], v[204:207], v[68:71]
	v_mfma_f32_16x16x32_bf16 v[64:67], v[172:175], v[204:207], v[64:67]
	v_mfma_f32_16x16x32_bf16 v[116:119], v[168:171], v[184:187], v[116:119]
	v_mfma_f32_16x16x32_bf16 v[108:111], v[176:179], v[184:187], v[108:111]
	v_mfma_f32_16x16x32_bf16 v[100:103], v[168:171], v[192:195], v[100:103]
	v_mfma_f32_16x16x32_bf16 v[92:95], v[176:179], v[192:195], v[92:95]
	v_mfma_f32_16x16x32_bf16 v[84:87], v[168:171], v[200:203], v[84:87]
	v_mfma_f32_16x16x32_bf16 v[76:79], v[176:179], v[200:203], v[76:79]
	v_mfma_f32_16x16x32_bf16 v[68:71], v[168:171], v[208:211], v[68:71]
	v_mfma_f32_16x16x32_bf16 v[64:67], v[176:179], v[208:211], v[64:67]
	s_setprio 0
	s_barrier
	s_add_i32 s48, s48, s69
	v_lshl_add_u64 v[214:215], v[140:141], 0, s[18:19]
	s_mov_b32 m0, s48
	ds_read_b128 v[180:183], v150 offset:49152
	ds_read_b128 v[184:187], v150 offset:50176
	ds_read_b128 v[188:191], v150 offset:51200
	ds_read_b128 v[192:195], v150 offset:52224
	ds_read_b128 v[196:199], v150 offset:53248
	ds_read_b128 v[200:203], v150 offset:54272
	ds_read_b128 v[204:207], v150 offset:55296
	ds_read_b128 v[208:211], v150 offset:56320
	global_load_lds_dwordx4 v[214:215], off
	v_lshl_add_u64 v[214:215], v[140:141], 0, s[20:21]
	s_add_i32 m0, s48, 0x2000
	s_add_i32 s48, s49, s69
	global_load_lds_dwordx4 v[214:215], off
	v_lshl_add_u64 v[214:215], v[140:141], 0, s[22:23]
	s_mov_b32 m0, s48
	v_lshl_add_u64 v[140:141], v[140:141], 0, s[24:25]
	global_load_lds_dwordx4 v[214:215], off
	s_add_i32 m0, s48, 0x2000
	s_nop 0
	global_load_lds_dwordx4 v[140:141], off
	v_lshl_add_u64 v[140:141], v[212:213], 0, s[18:19]
	s_mov_b32 m0, s10
	s_nop 0
	global_load_lds_dwordx4 v[140:141], off
	v_lshl_add_u64 v[140:141], v[212:213], 0, s[20:21]
	s_mov_b32 m0, s74
	s_nop 0
	global_load_lds_dwordx4 v[140:141], off
	s_waitcnt vmcnt(8)
	s_waitcnt lgkmcnt(0)
	s_barrier
	s_setprio 1
	v_mfma_f32_16x16x32_bf16 v[60:63], v[136:139], v[180:183], v[60:63]
	v_mfma_f32_16x16x32_bf16 v[56:59], v[156:159], v[180:183], v[56:59]
	v_mfma_f32_16x16x32_bf16 v[48:51], v[136:139], v[188:191], v[48:51]
	v_mfma_f32_16x16x32_bf16 v[40:43], v[156:159], v[188:191], v[40:43]
	v_mfma_f32_16x16x32_bf16 v[32:35], v[136:139], v[196:199], v[32:35]
	v_mfma_f32_16x16x32_bf16 v[24:27], v[156:159], v[196:199], v[24:27]
	v_mfma_f32_16x16x32_bf16 v[16:19], v[136:139], v[204:207], v[16:19]
	v_mfma_f32_16x16x32_bf16 v[8:11], v[156:159], v[204:207], v[8:11]
	v_mfma_f32_16x16x32_bf16 v[60:63], v[152:155], v[184:187], v[60:63]
	v_mfma_f32_16x16x32_bf16 v[56:59], v[160:163], v[184:187], v[56:59]
	v_mfma_f32_16x16x32_bf16 v[48:51], v[152:155], v[192:195], v[48:51]
	v_mfma_f32_16x16x32_bf16 v[40:43], v[160:163], v[192:195], v[40:43]
	v_mfma_f32_16x16x32_bf16 v[32:35], v[152:155], v[200:203], v[32:35]
	v_mfma_f32_16x16x32_bf16 v[24:27], v[160:163], v[200:203], v[24:27]
	v_mfma_f32_16x16x32_bf16 v[16:19], v[152:155], v[208:211], v[16:19]
	v_mfma_f32_16x16x32_bf16 v[8:11], v[160:163], v[208:211], v[8:11]
	v_mfma_f32_16x16x32_bf16 v[52:55], v[164:167], v[180:183], v[52:55]
	v_mfma_f32_16x16x32_bf16 v[44:47], v[172:175], v[180:183], v[44:47]
	v_mfma_f32_16x16x32_bf16 v[36:39], v[164:167], v[188:191], v[36:39]
	v_mfma_f32_16x16x32_bf16 v[28:31], v[172:175], v[188:191], v[28:31]
	v_mfma_f32_16x16x32_bf16 v[20:23], v[164:167], v[196:199], v[20:23]
	v_mfma_f32_16x16x32_bf16 v[12:15], v[172:175], v[196:199], v[12:15]
	v_mfma_f32_16x16x32_bf16 v[4:7], v[164:167], v[204:207], v[4:7]
	v_mfma_f32_16x16x32_bf16 v[0:3], v[172:175], v[204:207], v[0:3]
	v_mfma_f32_16x16x32_bf16 v[52:55], v[168:171], v[184:187], v[52:55]
	v_mfma_f32_16x16x32_bf16 v[44:47], v[176:179], v[184:187], v[44:47]
	v_mfma_f32_16x16x32_bf16 v[36:39], v[168:171], v[192:195], v[36:39]
	v_mfma_f32_16x16x32_bf16 v[28:31], v[176:179], v[192:195], v[28:31]
	v_mfma_f32_16x16x32_bf16 v[20:23], v[168:171], v[200:203], v[20:23]
	v_mfma_f32_16x16x32_bf16 v[12:15], v[176:179], v[200:203], v[12:15]
	v_mfma_f32_16x16x32_bf16 v[4:7], v[168:171], v[208:211], v[4:7]
	v_mfma_f32_16x16x32_bf16 v[0:3], v[176:179], v[208:211], v[0:3]
	s_setprio 0
	s_barrier
	s_add_i32 s82, s82, 2
	s_add_u32 s46, s46, 0x100
	s_addc_u32 s47, s47, 0
	s_add_u32 s80, s80, 0x100
	s_addc_u32 s81, s81, 0
	s_cmp_gt_u32 s82, 13
	s_cbranch_scc0 .LBB0_192
	s_and_b64 vcc, exec, s[30:31]
	s_cbranch_vccz .LBB0_195
	s_barrier

.LBB0_228:
	s_ashr_i32 s45, s44, 31
	s_lshl_b64 s[46:47], s[44:45], 19
	s_add_u32 s46, s64, s46
	s_addc_u32 s47, s65, s47
	s_and_b64 s[48:49], s[38:39], exec
	s_cselect_b32 s22, s47, s15
	s_cselect_b32 s45, s46, s14
	s_ashr_i32 s43, s42, 31
	s_lshl_b64 s[48:49], s[42:43], 19
	s_add_u32 s48, s6, s48
	s_addc_u32 s49, s19, s49
	s_and_b64 s[60:61], s[38:39], exec
	s_cselect_b32 s43, s49, s17
	s_cselect_b32 s84, s48, s16
	s_add_u32 s60, s14, 0x40080
	s_addc_u32 s61, s15, 0
	s_add_u32 s16, s16, 0x100
	s_addc_u32 s17, s17, 0
	s_mov_b32 s85, -2
	s_add_u32 s14, s60, 0xfffc0080
	s_addc_u32 s15, s61, -1
	s_add_i32 s18, 0, 0x10000
	s_cmp_eq_u32 s85, 12
	s_cselect_b32 s15, s22, s15
	s_cselect_b32 s14, s45, s14
	v_add_u32_e32 v137, s18, v141
	s_cselect_b32 vcc_hi, s43, s17
	s_cselect_b32 vcc_lo, s84, s16
	s_add_i32 s21, 0, 0x14000
	ds_read_b128 v[146:149], v137
	ds_read_b128 v[150:153], v137 offset:1024
	ds_read_b128 v[154:157], v137 offset:2048
	ds_read_b128 v[158:161], v137 offset:3072
	v_add_u32_e32 v137, s21, v141
	ds_read_b128 v[162:165], v137
	ds_read_b128 v[166:169], v137 offset:1024
	ds_read_b128 v[170:173], v137 offset:2048
	ds_read_b128 v[174:177], v137 offset:3072
	v_lshl_add_u64 v[138:139], s[60:61], 0, v[184:185]
	s_add_i32 m0, s25, 0xc000
	ds_read_b128 v[178:181], v145
	ds_read_b128 v[194:197], v145 offset:1024
	ds_read_b128 v[198:201], v145 offset:2048
	ds_read_b128 v[202:205], v145 offset:3072
	ds_read_b128 v[206:209], v145 offset:4096
	ds_read_b128 v[210:213], v145 offset:5120
	ds_read_b128 v[214:217], v145 offset:6144
	ds_read_b128 v[218:221], v145 offset:7168
	global_load_lds_dwordx4 v[138:139], off
	v_lshl_add_u64 v[138:139], v[138:139], 0, s[34:35]
	s_add_i32 m0, s25, 0xe000
	s_nop 0
	global_load_lds_dwordx4 v[138:139], off
	s_waitcnt vmcnt(8)
	s_waitcnt lgkmcnt(0)
	s_barrier
	s_setprio 1
	v_mfma_f32_16x16x32_bf16 v[124:127], v[146:149], v[178:181], 0
	v_mfma_f32_16x16x32_bf16 v[120:123], v[154:157], v[178:181], 0
	v_mfma_f32_16x16x32_bf16 v[112:115], v[146:149], v[198:201], 0
	v_mfma_f32_16x16x32_bf16 v[104:107], v[154:157], v[198:201], 0
	v_mfma_f32_16x16x32_bf16 v[96:99], v[146:149], v[206:209], 0
	v_mfma_f32_16x16x32_bf16 v[88:91], v[154:157], v[206:209], 0
	v_mfma_f32_16x16x32_bf16 v[80:83], v[146:149], v[214:217], 0
	v_mfma_f32_16x16x32_bf16 v[72:75], v[154:157], v[214:217], 0
	v_mfma_f32_16x16x32_bf16 v[124:127], v[150:153], v[194:197], v[124:127]
	v_mfma_f32_16x16x32_bf16 v[120:123], v[158:161], v[194:197], v[120:123]
	v_mfma_f32_16x16x32_bf16 v[112:115], v[150:153], v[202:205], v[112:115]
	v_mfma_f32_16x16x32_bf16 v[104:107], v[158:161], v[202:205], v[104:107]
	v_mfma_f32_16x16x32_bf16 v[96:99], v[150:153], v[210:213], v[96:99]
	v_mfma_f32_16x16x32_bf16 v[88:91], v[158:161], v[210:213], v[88:91]
	v_mfma_f32_16x16x32_bf16 v[80:83], v[150:153], v[218:221], v[80:83]
	v_mfma_f32_16x16x32_bf16 v[72:75], v[158:161], v[218:221], v[72:75]
	v_mfma_f32_16x16x32_bf16 v[116:119], v[162:165], v[178:181], 0
	v_mfma_f32_16x16x32_bf16 v[108:111], v[170:173], v[178:181], 0
	v_mfma_f32_16x16x32_bf16 v[100:103], v[162:165], v[198:201], 0
	v_mfma_f32_16x16x32_bf16 v[92:95], v[170:173], v[198:201], 0
	v_mfma_f32_16x16x32_bf16 v[84:87], v[162:165], v[206:209], 0
	v_mfma_f32_16x16x32_bf16 v[76:79], v[170:173], v[206:209], 0
	v_mfma_f32_16x16x32_bf16 v[68:71], v[162:165], v[214:217], 0
	v_mfma_f32_16x16x32_bf16 v[64:67], v[170:173], v[214:217], 0
	v_mfma_f32_16x16x32_bf16 v[116:119], v[166:169], v[194:197], v[116:119]
	v_mfma_f32_16x16x32_bf16 v[108:111], v[174:177], v[194:197], v[108:111]
	v_mfma_f32_16x16x32_bf16 v[100:103], v[166:169], v[202:205], v[100:103]
	v_mfma_f32_16x16x32_bf16 v[92:95], v[174:177], v[202:205], v[92:95]
	v_mfma_f32_16x16x32_bf16 v[84:87], v[166:169], v[210:213], v[84:87]
	v_mfma_f32_16x16x32_bf16 v[76:79], v[174:177], v[210:213], v[76:79]
	v_mfma_f32_16x16x32_bf16 v[68:71], v[166:169], v[218:221], v[68:71]
	v_mfma_f32_16x16x32_bf16 v[64:67], v[174:177], v[218:221], v[64:67]
	s_setprio 0
	s_barrier
	s_add_i32 s18, s18, s23
	v_lshl_add_u64 v[138:139], vcc, 0, v[128:129]
	s_mov_b32 m0, s18
	ds_read_b128 v[178:181], v145 offset:16384
	ds_read_b128 v[194:197], v145 offset:17408
	ds_read_b128 v[198:201], v145 offset:18432
	ds_read_b128 v[202:205], v145 offset:19456
	ds_read_b128 v[206:209], v145 offset:20480
	ds_read_b128 v[210:213], v145 offset:21504
	ds_read_b128 v[214:217], v145 offset:22528
	ds_read_b128 v[218:221], v145 offset:23552
	global_load_lds_dwordx4 v[138:139], off
	v_lshl_add_u64 v[182:183], v[138:139], 0, s[34:35]
	s_add_i32 m0, s18, 0x2000
	s_add_i32 s18, s21, s23
	global_load_lds_dwordx4 v[182:183], off
	v_lshl_add_u64 v[182:183], v[138:139], 0, s[92:93]
	s_mov_b32 m0, s18
	s_nop 0
	global_load_lds_dwordx4 v[182:183], off
	v_lshl_add_u64 v[182:183], v[138:139], 0, s[52:53]
	s_add_i32 m0, s18, 0x2000
	s_nop 0
	global_load_lds_dwordx4 v[182:183], off
	v_lshl_add_u64 v[182:183], s[14:15], 0, v[130:131]
	s_mov_b32 m0, s25
	v_lshl_add_u64 v[186:187], v[182:183], 0, s[34:35]
	global_load_lds_dwordx4 v[182:183], off
	s_mov_b32 m0, s26
	s_nop 0
	global_load_lds_dwordx4 v[186:187], off
	s_waitcnt vmcnt(8)
	s_waitcnt lgkmcnt(0)
	s_barrier
	s_setprio 1
	v_mfma_f32_16x16x32_bf16 v[60:63], v[146:149], v[178:181], 0
	v_mfma_f32_16x16x32_bf16 v[56:59], v[154:157], v[178:181], 0
	v_mfma_f32_16x16x32_bf16 v[48:51], v[146:149], v[198:201], 0
	v_mfma_f32_16x16x32_bf16 v[40:43], v[154:157], v[198:201], 0
	v_mfma_f32_16x16x32_bf16 v[32:35], v[146:149], v[206:209], 0
	v_mfma_f32_16x16x32_bf16 v[24:27], v[154:157], v[206:209], 0
	v_mfma_f32_16x16x32_bf16 v[16:19], v[146:149], v[214:217], 0
	v_mfma_f32_16x16x32_bf16 v[8:11], v[154:157], v[214:217], 0
	v_mfma_f32_16x16x32_bf16 v[60:63], v[150:153], v[194:197], v[60:63]
	v_mfma_f32_16x16x32_bf16 v[56:59], v[158:161], v[194:197], v[56:59]
	v_mfma_f32_16x16x32_bf16 v[48:51], v[150:153], v[202:205], v[48:51]
	v_mfma_f32_16x16x32_bf16 v[40:43], v[158:161], v[202:205], v[40:43]
	v_mfma_f32_16x16x32_bf16 v[32:35], v[150:153], v[210:213], v[32:35]
	v_mfma_f32_16x16x32_bf16 v[24:27], v[158:161], v[210:213], v[24:27]
	v_mfma_f32_16x16x32_bf16 v[16:19], v[150:153], v[218:221], v[16:19]
	v_mfma_f32_16x16x32_bf16 v[8:11], v[158:161], v[218:221], v[8:11]
	v_mfma_f32_16x16x32_bf16 v[52:55], v[162:165], v[178:181], 0
	v_mfma_f32_16x16x32_bf16 v[44:47], v[170:173], v[178:181], 0
	v_mfma_f32_16x16x32_bf16 v[36:39], v[162:165], v[198:201], 0
	v_mfma_f32_16x16x32_bf16 v[28:31], v[170:173], v[198:201], 0
	v_mfma_f32_16x16x32_bf16 v[20:23], v[162:165], v[206:209], 0
	v_mfma_f32_16x16x32_bf16 v[12:15], v[170:173], v[206:209], 0
	v_mfma_f32_16x16x32_bf16 v[4:7], v[162:165], v[214:217], 0
	v_mfma_f32_16x16x32_bf16 v[0:3], v[170:173], v[214:217], 0
	v_mfma_f32_16x16x32_bf16 v[52:55], v[166:169], v[194:197], v[52:55]
	v_mfma_f32_16x16x32_bf16 v[44:47], v[174:177], v[194:197], v[44:47]
	v_mfma_f32_16x16x32_bf16 v[36:39], v[166:169], v[202:205], v[36:39]
	v_mfma_f32_16x16x32_bf16 v[28:31], v[174:177], v[202:205], v[28:31]
	v_mfma_f32_16x16x32_bf16 v[20:23], v[166:169], v[210:213], v[20:23]
	v_mfma_f32_16x16x32_bf16 v[12:15], v[174:177], v[210:213], v[12:15]
	v_mfma_f32_16x16x32_bf16 v[4:7], v[166:169], v[218:221], v[4:7]
	v_mfma_f32_16x16x32_bf16 v[0:3], v[174:177], v[218:221], v[0:3]
	s_setprio 0
	s_barrier
	s_add_i32 s14, 0, 0x18000
	v_add_u32_e32 v137, s14, v141
	s_add_i32 s15, 0, 0x1c000
	ds_read_b128 v[146:149], v137
	ds_read_b128 v[150:153], v137 offset:1024
	ds_read_b128 v[154:157], v137 offset:2048
	ds_read_b128 v[158:161], v137 offset:3072
	v_add_u32_e32 v137, s15, v141
	ds_read_b128 v[162:165], v137
	ds_read_b128 v[166:169], v137 offset:1024
	ds_read_b128 v[170:173], v137 offset:2048
	ds_read_b128 v[174:177], v137 offset:3072
	s_mov_b32 m0, s27
	v_lshl_add_u64 v[186:187], v[182:183], 0, s[92:93]
	ds_read_b128 v[178:181], v145 offset:32768
	ds_read_b128 v[194:197], v145 offset:33792
	ds_read_b128 v[198:201], v145 offset:34816
	ds_read_b128 v[202:205], v145 offset:35840
	ds_read_b128 v[206:209], v145 offset:36864
	ds_read_b128 v[210:213], v145 offset:37888
	ds_read_b128 v[214:217], v145 offset:38912
	ds_read_b128 v[218:221], v145 offset:39936
	global_load_lds_dwordx4 v[186:187], off
	v_lshl_add_u64 v[186:187], v[182:183], 0, s[52:53]
	s_mov_b32 m0, s28
	s_nop 0
	global_load_lds_dwordx4 v[186:187], off
	s_waitcnt vmcnt(8)
	s_waitcnt lgkmcnt(0)
	s_barrier
	s_setprio 1
	v_mfma_f32_16x16x32_bf16 v[124:127], v[146:149], v[178:181], v[124:127]
	v_mfma_f32_16x16x32_bf16 v[120:123], v[154:157], v[178:181], v[120:123]
	v_mfma_f32_16x16x32_bf16 v[112:115], v[146:149], v[198:201], v[112:115]
	v_mfma_f32_16x16x32_bf16 v[104:107], v[154:157], v[198:201], v[104:107]
	v_mfma_f32_16x16x32_bf16 v[96:99], v[146:149], v[206:209], v[96:99]
	v_mfma_f32_16x16x32_bf16 v[88:91], v[154:157], v[206:209], v[88:91]
	v_mfma_f32_16x16x32_bf16 v[80:83], v[146:149], v[214:217], v[80:83]
	v_mfma_f32_16x16x32_bf16 v[72:75], v[154:157], v[214:217], v[72:75]
	v_mfma_f32_16x16x32_bf16 v[124:127], v[150:153], v[194:197], v[124:127]
	v_mfma_f32_16x16x32_bf16 v[120:123], v[158:161], v[194:197], v[120:123]
	v_mfma_f32_16x16x32_bf16 v[112:115], v[150:153], v[202:205], v[112:115]
	v_mfma_f32_16x16x32_bf16 v[104:107], v[158:161], v[202:205], v[104:107]
	v_mfma_f32_16x16x32_bf16 v[96:99], v[150:153], v[210:213], v[96:99]
	v_mfma_f32_16x16x32_bf16 v[88:91], v[158:161], v[210:213], v[88:91]
	v_mfma_f32_16x16x32_bf16 v[80:83], v[150:153], v[218:221], v[80:83]
	v_mfma_f32_16x16x32_bf16 v[72:75], v[158:161], v[218:221], v[72:75]
	v_mfma_f32_16x16x32_bf16 v[116:119], v[162:165], v[178:181], v[116:119]
	v_mfma_f32_16x16x32_bf16 v[108:111], v[170:173], v[178:181], v[108:111]
	v_mfma_f32_16x16x32_bf16 v[100:103], v[162:165], v[198:201], v[100:103]
	v_mfma_f32_16x16x32_bf16 v[92:95], v[170:173], v[198:201], v[92:95]
	v_mfma_f32_16x16x32_bf16 v[84:87], v[162:165], v[206:209], v[84:87]
	v_mfma_f32_16x16x32_bf16 v[76:79], v[170:173], v[206:209], v[76:79]
	v_mfma_f32_16x16x32_bf16 v[68:71], v[162:165], v[214:217], v[68:71]
	v_mfma_f32_16x16x32_bf16 v[64:67], v[170:173], v[214:217], v[64:67]
	v_mfma_f32_16x16x32_bf16 v[116:119], v[166:169], v[194:197], v[116:119]
	v_mfma_f32_16x16x32_bf16 v[108:111], v[174:177], v[194:197], v[108:111]
	v_mfma_f32_16x16x32_bf16 v[100:103], v[166:169], v[202:205], v[100:103]
	v_mfma_f32_16x16x32_bf16 v[92:95], v[174:177], v[202:205], v[92:95]
	v_mfma_f32_16x16x32_bf16 v[84:87], v[166:169], v[210:213], v[84:87]
	v_mfma_f32_16x16x32_bf16 v[76:79], v[174:177], v[210:213], v[76:79]
	v_mfma_f32_16x16x32_bf16 v[68:71], v[166:169], v[218:221], v[68:71]
	v_mfma_f32_16x16x32_bf16 v[64:67], v[174:177], v[218:221], v[64:67]
	s_setprio 0
	s_barrier
	s_add_i32 s14, s14, s23
	v_lshl_add_u64 v[186:187], v[138:139], 0, s[56:57]
	s_mov_b32 m0, s14
	ds_read_b128 v[178:181], v145 offset:49152
	ds_read_b128 v[194:197], v145 offset:50176
	ds_read_b128 v[198:201], v145 offset:51200
	ds_read_b128 v[202:205], v145 offset:52224
	ds_read_b128 v[206:209], v145 offset:53248
	ds_read_b128 v[210:213], v145 offset:54272
	ds_read_b128 v[214:217], v145 offset:55296
	ds_read_b128 v[218:221], v145 offset:56320
	global_load_lds_dwordx4 v[186:187], off
	v_lshl_add_u64 v[186:187], v[138:139], 0, s[96:97]
	s_add_i32 m0, s14, 0x2000
	s_add_i32 s14, s15, s23
	global_load_lds_dwordx4 v[186:187], off
	v_lshl_add_u64 v[186:187], v[138:139], 0, s[88:89]
	s_mov_b32 m0, s14
	v_lshl_add_u64 v[138:139], v[138:139], 0, s[68:69]
	global_load_lds_dwordx4 v[186:187], off
	s_add_i32 m0, s14, 0x2000
	s_nop 0
	global_load_lds_dwordx4 v[138:139], off
	v_lshl_add_u64 v[138:139], v[182:183], 0, s[56:57]
	s_mov_b32 m0, s29
	s_nop 0
	global_load_lds_dwordx4 v[138:139], off
	v_lshl_add_u64 v[138:139], v[182:183], 0, s[96:97]
	s_mov_b32 m0, s30
	s_nop 0
	global_load_lds_dwordx4 v[138:139], off
	s_waitcnt vmcnt(8)
	s_waitcnt lgkmcnt(0)
	s_barrier
	s_setprio 1
	v_mfma_f32_16x16x32_bf16 v[60:63], v[146:149], v[178:181], v[60:63]
	v_mfma_f32_16x16x32_bf16 v[56:59], v[154:157], v[178:181], v[56:59]
	v_mfma_f32_16x16x32_bf16 v[48:51], v[146:149], v[198:201], v[48:51]
	v_mfma_f32_16x16x32_bf16 v[40:43], v[154:157], v[198:201], v[40:43]
	v_mfma_f32_16x16x32_bf16 v[32:35], v[146:149], v[206:209], v[32:35]
	v_mfma_f32_16x16x32_bf16 v[24:27], v[154:157], v[206:209], v[24:27]
	v_mfma_f32_16x16x32_bf16 v[16:19], v[146:149], v[214:217], v[16:19]
	v_mfma_f32_16x16x32_bf16 v[8:11], v[154:157], v[214:217], v[8:11]
	v_mfma_f32_16x16x32_bf16 v[60:63], v[150:153], v[194:197], v[60:63]
	v_mfma_f32_16x16x32_bf16 v[56:59], v[158:161], v[194:197], v[56:59]
	v_mfma_f32_16x16x32_bf16 v[48:51], v[150:153], v[202:205], v[48:51]
	v_mfma_f32_16x16x32_bf16 v[40:43], v[158:161], v[202:205], v[40:43]
	v_mfma_f32_16x16x32_bf16 v[32:35], v[150:153], v[210:213], v[32:35]
	v_mfma_f32_16x16x32_bf16 v[24:27], v[158:161], v[210:213], v[24:27]
	v_mfma_f32_16x16x32_bf16 v[16:19], v[150:153], v[218:221], v[16:19]
	v_mfma_f32_16x16x32_bf16 v[8:11], v[158:161], v[218:221], v[8:11]
	v_mfma_f32_16x16x32_bf16 v[52:55], v[162:165], v[178:181], v[52:55]
	v_mfma_f32_16x16x32_bf16 v[44:47], v[170:173], v[178:181], v[44:47]
	v_mfma_f32_16x16x32_bf16 v[36:39], v[162:165], v[198:201], v[36:39]
	v_mfma_f32_16x16x32_bf16 v[28:31], v[170:173], v[198:201], v[28:31]
	v_mfma_f32_16x16x32_bf16 v[20:23], v[162:165], v[206:209], v[20:23]
	v_mfma_f32_16x16x32_bf16 v[12:15], v[170:173], v[206:209], v[12:15]
	v_mfma_f32_16x16x32_bf16 v[4:7], v[162:165], v[214:217], v[4:7]
	v_mfma_f32_16x16x32_bf16 v[0:3], v[170:173], v[214:217], v[0:3]
	v_mfma_f32_16x16x32_bf16 v[52:55], v[166:169], v[194:197], v[52:55]
	v_mfma_f32_16x16x32_bf16 v[44:47], v[174:177], v[194:197], v[44:47]
	v_mfma_f32_16x16x32_bf16 v[36:39], v[166:169], v[202:205], v[36:39]
	v_mfma_f32_16x16x32_bf16 v[28:31], v[174:177], v[202:205], v[28:31]
	v_mfma_f32_16x16x32_bf16 v[20:23], v[166:169], v[210:213], v[20:23]
	v_mfma_f32_16x16x32_bf16 v[12:15], v[174:177], v[210:213], v[12:15]
	v_mfma_f32_16x16x32_bf16 v[4:7], v[166:169], v[218:221], v[4:7]
	v_mfma_f32_16x16x32_bf16 v[0:3], v[174:177], v[218:221], v[0:3]
	s_setprio 0
	s_barrier
	s_add_i32 s85, s85, 2
	s_add_u32 s60, s60, 0x100
	s_addc_u32 s61, s61, 0
	s_add_u32 s16, s16, 0x100
	s_addc_u32 s17, s17, 0
	s_cmp_gt_u32 s85, 13
.LBB0_229:
	s_add_u32 s14, s60, 0xfffc0080
	s_addc_u32 s15, s61, -1
	s_add_i32 s18, 0, 0x10000
	s_cmp_eq_u32 s85, 12
	s_cselect_b32 s15, s22, s15
	s_cselect_b32 s14, s45, s14
	v_add_u32_e32 v137, s18, v141
	s_cselect_b32 vcc_hi, s43, s17
	s_cselect_b32 vcc_lo, s84, s16
	s_add_i32 s21, 0, 0x14000
	ds_read_b128 v[146:149], v137
	ds_read_b128 v[150:153], v137 offset:1024
	ds_read_b128 v[154:157], v137 offset:2048
	ds_read_b128 v[158:161], v137 offset:3072
	v_add_u32_e32 v137, s21, v141
	ds_read_b128 v[162:165], v137
	ds_read_b128 v[166:169], v137 offset:1024
	ds_read_b128 v[170:173], v137 offset:2048
	ds_read_b128 v[174:177], v137 offset:3072
	v_lshl_add_u64 v[138:139], s[60:61], 0, v[184:185]
	s_add_i32 m0, s25, 0xc000
	ds_read_b128 v[178:181], v145
	ds_read_b128 v[194:197], v145 offset:1024
	ds_read_b128 v[198:201], v145 offset:2048
	ds_read_b128 v[202:205], v145 offset:3072
	ds_read_b128 v[206:209], v145 offset:4096
	ds_read_b128 v[210:213], v145 offset:5120
	ds_read_b128 v[214:217], v145 offset:6144
	ds_read_b128 v[218:221], v145 offset:7168
	global_load_lds_dwordx4 v[138:139], off
	v_lshl_add_u64 v[138:139], v[138:139], 0, s[34:35]
	s_add_i32 m0, s25, 0xe000
	s_nop 0
	global_load_lds_dwordx4 v[138:139], off
	s_waitcnt vmcnt(8)
	s_waitcnt lgkmcnt(0)
	s_barrier
	s_setprio 1
	v_mfma_f32_16x16x32_bf16 v[124:127], v[146:149], v[178:181], v[124:127]
	v_mfma_f32_16x16x32_bf16 v[120:123], v[154:157], v[178:181], v[120:123]
	v_mfma_f32_16x16x32_bf16 v[112:115], v[146:149], v[198:201], v[112:115]
	v_mfma_f32_16x16x32_bf16 v[104:107], v[154:157], v[198:201], v[104:107]
	v_mfma_f32_16x16x32_bf16 v[96:99], v[146:149], v[206:209], v[96:99]
	v_mfma_f32_16x16x32_bf16 v[88:91], v[154:157], v[206:209], v[88:91]
	v_mfma_f32_16x16x32_bf16 v[80:83], v[146:149], v[214:217], v[80:83]
	v_mfma_f32_16x16x32_bf16 v[72:75], v[154:157], v[214:217], v[72:75]
	v_mfma_f32_16x16x32_bf16 v[124:127], v[150:153], v[194:197], v[124:127]
	v_mfma_f32_16x16x32_bf16 v[120:123], v[158:161], v[194:197], v[120:123]
	v_mfma_f32_16x16x32_bf16 v[112:115], v[150:153], v[202:205], v[112:115]
	v_mfma_f32_16x16x32_bf16 v[104:107], v[158:161], v[202:205], v[104:107]
	v_mfma_f32_16x16x32_bf16 v[96:99], v[150:153], v[210:213], v[96:99]
	v_mfma_f32_16x16x32_bf16 v[88:91], v[158:161], v[210:213], v[88:91]
	v_mfma_f32_16x16x32_bf16 v[80:83], v[150:153], v[218:221], v[80:83]
	v_mfma_f32_16x16x32_bf16 v[72:75], v[158:161], v[218:221], v[72:75]
	v_mfma_f32_16x16x32_bf16 v[116:119], v[162:165], v[178:181], v[116:119]
	v_mfma_f32_16x16x32_bf16 v[108:111], v[170:173], v[178:181], v[108:111]
	v_mfma_f32_16x16x32_bf16 v[100:103], v[162:165], v[198:201], v[100:103]
	v_mfma_f32_16x16x32_bf16 v[92:95], v[170:173], v[198:201], v[92:95]
	v_mfma_f32_16x16x32_bf16 v[84:87], v[162:165], v[206:209], v[84:87]
	v_mfma_f32_16x16x32_bf16 v[76:79], v[170:173], v[206:209], v[76:79]
	v_mfma_f32_16x16x32_bf16 v[68:71], v[162:165], v[214:217], v[68:71]
	v_mfma_f32_16x16x32_bf16 v[64:67], v[170:173], v[214:217], v[64:67]
	v_mfma_f32_16x16x32_bf16 v[116:119], v[166:169], v[194:197], v[116:119]
	v_mfma_f32_16x16x32_bf16 v[108:111], v[174:177], v[194:197], v[108:111]
	v_mfma_f32_16x16x32_bf16 v[100:103], v[166:169], v[202:205], v[100:103]
	v_mfma_f32_16x16x32_bf16 v[92:95], v[174:177], v[202:205], v[92:95]
	v_mfma_f32_16x16x32_bf16 v[84:87], v[166:169], v[210:213], v[84:87]
	v_mfma_f32_16x16x32_bf16 v[76:79], v[174:177], v[210:213], v[76:79]
	v_mfma_f32_16x16x32_bf16 v[68:71], v[166:169], v[218:221], v[68:71]
	v_mfma_f32_16x16x32_bf16 v[64:67], v[174:177], v[218:221], v[64:67]
	s_setprio 0
	s_barrier
	s_add_i32 s18, s18, s23
	v_lshl_add_u64 v[138:139], vcc, 0, v[128:129]
	s_mov_b32 m0, s18
	ds_read_b128 v[178:181], v145 offset:16384
	ds_read_b128 v[194:197], v145 offset:17408
	ds_read_b128 v[198:201], v145 offset:18432
	ds_read_b128 v[202:205], v145 offset:19456
	ds_read_b128 v[206:209], v145 offset:20480
	ds_read_b128 v[210:213], v145 offset:21504
	ds_read_b128 v[214:217], v145 offset:22528
	ds_read_b128 v[218:221], v145 offset:23552
	global_load_lds_dwordx4 v[138:139], off
	v_lshl_add_u64 v[182:183], v[138:139], 0, s[34:35]
	s_add_i32 m0, s18, 0x2000
	s_add_i32 s18, s21, s23
	global_load_lds_dwordx4 v[182:183], off
	v_lshl_add_u64 v[182:183], v[138:139], 0, s[92:93]
	s_mov_b32 m0, s18
	s_nop 0
	global_load_lds_dwordx4 v[182:183], off
	v_lshl_add_u64 v[182:183], v[138:139], 0, s[52:53]
	s_add_i32 m0, s18, 0x2000
	s_nop 0
	global_load_lds_dwordx4 v[182:183], off
	v_lshl_add_u64 v[182:183], s[14:15], 0, v[130:131]
	s_mov_b32 m0, s25
	v_lshl_add_u64 v[186:187], v[182:183], 0, s[34:35]
	global_load_lds_dwordx4 v[182:183], off
	s_mov_b32 m0, s26
	s_nop 0
	global_load_lds_dwordx4 v[186:187], off
	s_waitcnt vmcnt(8)
	s_waitcnt lgkmcnt(0)
	s_barrier
	s_setprio 1
	v_mfma_f32_16x16x32_bf16 v[60:63], v[146:149], v[178:181], v[60:63]
	v_mfma_f32_16x16x32_bf16 v[56:59], v[154:157], v[178:181], v[56:59]
	v_mfma_f32_16x16x32_bf16 v[48:51], v[146:149], v[198:201], v[48:51]
	v_mfma_f32_16x16x32_bf16 v[40:43], v[154:157], v[198:201], v[40:43]
	v_mfma_f32_16x16x32_bf16 v[32:35], v[146:149], v[206:209], v[32:35]
	v_mfma_f32_16x16x32_bf16 v[24:27], v[154:157], v[206:209], v[24:27]
	v_mfma_f32_16x16x32_bf16 v[16:19], v[146:149], v[214:217], v[16:19]
	v_mfma_f32_16x16x32_bf16 v[8:11], v[154:157], v[214:217], v[8:11]
	v_mfma_f32_16x16x32_bf16 v[60:63], v[150:153], v[194:197], v[60:63]
	v_mfma_f32_16x16x32_bf16 v[56:59], v[158:161], v[194:197], v[56:59]
	v_mfma_f32_16x16x32_bf16 v[48:51], v[150:153], v[202:205], v[48:51]
	v_mfma_f32_16x16x32_bf16 v[40:43], v[158:161], v[202:205], v[40:43]
	v_mfma_f32_16x16x32_bf16 v[32:35], v[150:153], v[210:213], v[32:35]
	v_mfma_f32_16x16x32_bf16 v[24:27], v[158:161], v[210:213], v[24:27]
	v_mfma_f32_16x16x32_bf16 v[16:19], v[150:153], v[218:221], v[16:19]
	v_mfma_f32_16x16x32_bf16 v[8:11], v[158:161], v[218:221], v[8:11]
	v_mfma_f32_16x16x32_bf16 v[52:55], v[162:165], v[178:181], v[52:55]
	v_mfma_f32_16x16x32_bf16 v[44:47], v[170:173], v[178:181], v[44:47]
	v_mfma_f32_16x16x32_bf16 v[36:39], v[162:165], v[198:201], v[36:39]
	v_mfma_f32_16x16x32_bf16 v[28:31], v[170:173], v[198:201], v[28:31]
	v_mfma_f32_16x16x32_bf16 v[20:23], v[162:165], v[206:209], v[20:23]
	v_mfma_f32_16x16x32_bf16 v[12:15], v[170:173], v[206:209], v[12:15]
	v_mfma_f32_16x16x32_bf16 v[4:7], v[162:165], v[214:217], v[4:7]
	v_mfma_f32_16x16x32_bf16 v[0:3], v[170:173], v[214:217], v[0:3]
	v_mfma_f32_16x16x32_bf16 v[52:55], v[166:169], v[194:197], v[52:55]
	v_mfma_f32_16x16x32_bf16 v[44:47], v[174:177], v[194:197], v[44:47]
	v_mfma_f32_16x16x32_bf16 v[36:39], v[166:169], v[202:205], v[36:39]
	v_mfma_f32_16x16x32_bf16 v[28:31], v[174:177], v[202:205], v[28:31]
	v_mfma_f32_16x16x32_bf16 v[20:23], v[166:169], v[210:213], v[20:23]
	v_mfma_f32_16x16x32_bf16 v[12:15], v[174:177], v[210:213], v[12:15]
	v_mfma_f32_16x16x32_bf16 v[4:7], v[166:169], v[218:221], v[4:7]
	v_mfma_f32_16x16x32_bf16 v[0:3], v[174:177], v[218:221], v[0:3]
	s_setprio 0
	s_barrier
	s_add_i32 s14, 0, 0x18000
	v_add_u32_e32 v137, s14, v141
	s_add_i32 s15, 0, 0x1c000
	ds_read_b128 v[146:149], v137
	ds_read_b128 v[150:153], v137 offset:1024
	ds_read_b128 v[154:157], v137 offset:2048
	ds_read_b128 v[158:161], v137 offset:3072
	v_add_u32_e32 v137, s15, v141
	ds_read_b128 v[162:165], v137
	ds_read_b128 v[166:169], v137 offset:1024
	ds_read_b128 v[170:173], v137 offset:2048
	ds_read_b128 v[174:177], v137 offset:3072
	s_mov_b32 m0, s27
	v_lshl_add_u64 v[186:187], v[182:183], 0, s[92:93]
	ds_read_b128 v[178:181], v145 offset:32768
	ds_read_b128 v[194:197], v145 offset:33792
	ds_read_b128 v[198:201], v145 offset:34816
	ds_read_b128 v[202:205], v145 offset:35840
	ds_read_b128 v[206:209], v145 offset:36864
	ds_read_b128 v[210:213], v145 offset:37888
	ds_read_b128 v[214:217], v145 offset:38912
	ds_read_b128 v[218:221], v145 offset:39936
	global_load_lds_dwordx4 v[186:187], off
	v_lshl_add_u64 v[186:187], v[182:183], 0, s[52:53]
	s_mov_b32 m0, s28
	s_nop 0
	global_load_lds_dwordx4 v[186:187], off
	s_waitcnt vmcnt(8)
	s_waitcnt lgkmcnt(0)
	s_barrier
	s_setprio 1
	v_mfma_f32_16x16x32_bf16 v[124:127], v[146:149], v[178:181], v[124:127]
	v_mfma_f32_16x16x32_bf16 v[120:123], v[154:157], v[178:181], v[120:123]
	v_mfma_f32_16x16x32_bf16 v[112:115], v[146:149], v[198:201], v[112:115]
	v_mfma_f32_16x16x32_bf16 v[104:107], v[154:157], v[198:201], v[104:107]
	v_mfma_f32_16x16x32_bf16 v[96:99], v[146:149], v[206:209], v[96:99]
	v_mfma_f32_16x16x32_bf16 v[88:91], v[154:157], v[206:209], v[88:91]
	v_mfma_f32_16x16x32_bf16 v[80:83], v[146:149], v[214:217], v[80:83]
	v_mfma_f32_16x16x32_bf16 v[72:75], v[154:157], v[214:217], v[72:75]
	v_mfma_f32_16x16x32_bf16 v[124:127], v[150:153], v[194:197], v[124:127]
	v_mfma_f32_16x16x32_bf16 v[120:123], v[158:161], v[194:197], v[120:123]
	v_mfma_f32_16x16x32_bf16 v[112:115], v[150:153], v[202:205], v[112:115]
	v_mfma_f32_16x16x32_bf16 v[104:107], v[158:161], v[202:205], v[104:107]
	v_mfma_f32_16x16x32_bf16 v[96:99], v[150:153], v[210:213], v[96:99]
	v_mfma_f32_16x16x32_bf16 v[88:91], v[158:161], v[210:213], v[88:91]
	v_mfma_f32_16x16x32_bf16 v[80:83], v[150:153], v[218:221], v[80:83]
	v_mfma_f32_16x16x32_bf16 v[72:75], v[158:161], v[218:221], v[72:75]
	v_mfma_f32_16x16x32_bf16 v[116:119], v[162:165], v[178:181], v[116:119]
	v_mfma_f32_16x16x32_bf16 v[108:111], v[170:173], v[178:181], v[108:111]
	v_mfma_f32_16x16x32_bf16 v[100:103], v[162:165], v[198:201], v[100:103]
	v_mfma_f32_16x16x32_bf16 v[92:95], v[170:173], v[198:201], v[92:95]
	v_mfma_f32_16x16x32_bf16 v[84:87], v[162:165], v[206:209], v[84:87]
	v_mfma_f32_16x16x32_bf16 v[76:79], v[170:173], v[206:209], v[76:79]
	v_mfma_f32_16x16x32_bf16 v[68:71], v[162:165], v[214:217], v[68:71]
	v_mfma_f32_16x16x32_bf16 v[64:67], v[170:173], v[214:217], v[64:67]
	v_mfma_f32_16x16x32_bf16 v[116:119], v[166:169], v[194:197], v[116:119]
	v_mfma_f32_16x16x32_bf16 v[108:111], v[174:177], v[194:197], v[108:111]
	v_mfma_f32_16x16x32_bf16 v[100:103], v[166:169], v[202:205], v[100:103]
	v_mfma_f32_16x16x32_bf16 v[92:95], v[174:177], v[202:205], v[92:95]
	v_mfma_f32_16x16x32_bf16 v[84:87], v[166:169], v[210:213], v[84:87]
	v_mfma_f32_16x16x32_bf16 v[76:79], v[174:177], v[210:213], v[76:79]
	v_mfma_f32_16x16x32_bf16 v[68:71], v[166:169], v[218:221], v[68:71]
	v_mfma_f32_16x16x32_bf16 v[64:67], v[174:177], v[218:221], v[64:67]
	s_setprio 0
	s_barrier
	s_add_i32 s14, s14, s23
	v_lshl_add_u64 v[186:187], v[138:139], 0, s[56:57]
	s_mov_b32 m0, s14
	ds_read_b128 v[178:181], v145 offset:49152
	ds_read_b128 v[194:197], v145 offset:50176
	ds_read_b128 v[198:201], v145 offset:51200
	ds_read_b128 v[202:205], v145 offset:52224
	ds_read_b128 v[206:209], v145 offset:53248
	ds_read_b128 v[210:213], v145 offset:54272
	ds_read_b128 v[214:217], v145 offset:55296
	ds_read_b128 v[218:221], v145 offset:56320
	global_load_lds_dwordx4 v[186:187], off
	v_lshl_add_u64 v[186:187], v[138:139], 0, s[96:97]
	s_add_i32 m0, s14, 0x2000
	s_add_i32 s14, s15, s23
	global_load_lds_dwordx4 v[186:187], off
	v_lshl_add_u64 v[186:187], v[138:139], 0, s[88:89]
	s_mov_b32 m0, s14
	v_lshl_add_u64 v[138:139], v[138:139], 0, s[68:69]
	global_load_lds_dwordx4 v[186:187], off
	s_add_i32 m0, s14, 0x2000
	s_nop 0
	global_load_lds_dwordx4 v[138:139], off
	v_lshl_add_u64 v[138:139], v[182:183], 0, s[56:57]
	s_mov_b32 m0, s29
	s_nop 0
	global_load_lds_dwordx4 v[138:139], off
	v_lshl_add_u64 v[138:139], v[182:183], 0, s[96:97]
	s_mov_b32 m0, s30
	s_nop 0
	global_load_lds_dwordx4 v[138:139], off
	s_waitcnt vmcnt(8)
	s_waitcnt lgkmcnt(0)
	s_barrier
	s_setprio 1
	v_mfma_f32_16x16x32_bf16 v[60:63], v[146:149], v[178:181], v[60:63]
	v_mfma_f32_16x16x32_bf16 v[56:59], v[154:157], v[178:181], v[56:59]
	v_mfma_f32_16x16x32_bf16 v[48:51], v[146:149], v[198:201], v[48:51]
	v_mfma_f32_16x16x32_bf16 v[40:43], v[154:157], v[198:201], v[40:43]
	v_mfma_f32_16x16x32_bf16 v[32:35], v[146:149], v[206:209], v[32:35]
	v_mfma_f32_16x16x32_bf16 v[24:27], v[154:157], v[206:209], v[24:27]
	v_mfma_f32_16x16x32_bf16 v[16:19], v[146:149], v[214:217], v[16:19]
	v_mfma_f32_16x16x32_bf16 v[8:11], v[154:157], v[214:217], v[8:11]
	v_mfma_f32_16x16x32_bf16 v[60:63], v[150:153], v[194:197], v[60:63]
	v_mfma_f32_16x16x32_bf16 v[56:59], v[158:161], v[194:197], v[56:59]
	v_mfma_f32_16x16x32_bf16 v[48:51], v[150:153], v[202:205], v[48:51]
	v_mfma_f32_16x16x32_bf16 v[40:43], v[158:161], v[202:205], v[40:43]
	v_mfma_f32_16x16x32_bf16 v[32:35], v[150:153], v[210:213], v[32:35]
	v_mfma_f32_16x16x32_bf16 v[24:27], v[158:161], v[210:213], v[24:27]
	v_mfma_f32_16x16x32_bf16 v[16:19], v[150:153], v[218:221], v[16:19]
	v_mfma_f32_16x16x32_bf16 v[8:11], v[158:161], v[218:221], v[8:11]
	v_mfma_f32_16x16x32_bf16 v[52:55], v[162:165], v[178:181], v[52:55]
	v_mfma_f32_16x16x32_bf16 v[44:47], v[170:173], v[178:181], v[44:47]
	v_mfma_f32_16x16x32_bf16 v[36:39], v[162:165], v[198:201], v[36:39]
	v_mfma_f32_16x16x32_bf16 v[28:31], v[170:173], v[198:201], v[28:31]
	v_mfma_f32_16x16x32_bf16 v[20:23], v[162:165], v[206:209], v[20:23]
	v_mfma_f32_16x16x32_bf16 v[12:15], v[170:173], v[206:209], v[12:15]
	v_mfma_f32_16x16x32_bf16 v[4:7], v[162:165], v[214:217], v[4:7]
	v_mfma_f32_16x16x32_bf16 v[0:3], v[170:173], v[214:217], v[0:3]
	v_mfma_f32_16x16x32_bf16 v[52:55], v[166:169], v[194:197], v[52:55]
	v_mfma_f32_16x16x32_bf16 v[44:47], v[174:177], v[194:197], v[44:47]
	v_mfma_f32_16x16x32_bf16 v[36:39], v[166:169], v[202:205], v[36:39]
	v_mfma_f32_16x16x32_bf16 v[28:31], v[174:177], v[202:205], v[28:31]
	v_mfma_f32_16x16x32_bf16 v[20:23], v[166:169], v[210:213], v[20:23]
	v_mfma_f32_16x16x32_bf16 v[12:15], v[174:177], v[210:213], v[12:15]
	v_mfma_f32_16x16x32_bf16 v[4:7], v[166:169], v[218:221], v[4:7]
	v_mfma_f32_16x16x32_bf16 v[0:3], v[174:177], v[218:221], v[0:3]
	s_setprio 0
	s_barrier
	s_add_i32 s85, s85, 2
	s_add_u32 s60, s60, 0x100
	s_addc_u32 s61, s61, 0
	s_add_u32 s16, s16, 0x100
	s_addc_u32 s17, s17, 0
	s_cmp_gt_u32 s85, 13
	s_cbranch_scc0 .LBB0_229
	s_and_b64 vcc, exec, s[40:41]
	s_cbranch_vccz .LBB0_232
	s_barrier

.LBB0_248:
	s_ashr_i32 s45, s44, 31
	s_lshl_b64 s[46:47], s[44:45], 19
	s_add_u32 s46, s64, s46
	s_addc_u32 s47, s65, s47
	s_and_b64 s[48:49], s[38:39], exec
	s_cselect_b32 s22, s47, s15
	s_cselect_b32 s45, s46, s14
	s_ashr_i32 s43, s42, 31
	s_lshl_b64 s[48:49], s[42:43], 19
	s_add_u32 s48, s6, s48
	s_addc_u32 s49, s19, s49
	s_and_b64 s[60:61], s[38:39], exec
	s_cselect_b32 s43, s49, s17
	s_cselect_b32 s84, s48, s16
	s_add_u32 s60, s14, 0x40080
	s_addc_u32 s61, s15, 0
	s_add_u32 s16, s16, 0x100
	s_addc_u32 s17, s17, 0
	s_mov_b32 s85, -2
	s_add_u32 s14, s60, 0xfffc0080
	s_addc_u32 s15, s61, -1
	s_add_i32 s18, 0, 0x10000
	s_cmp_eq_u32 s85, 12
	s_cselect_b32 s15, s22, s15
	s_cselect_b32 s14, s45, s14
	s_waitcnt lgkmcnt(0)
	v_add_u32_e32 v137, s18, v149
	s_cselect_b32 vcc_hi, s43, s17
	s_cselect_b32 vcc_lo, s84, s16
	s_add_i32 s21, 0, 0x14000
	ds_read_b128 v[138:141], v137
	ds_read_b128 v[142:145], v137 offset:1024
	ds_read_b128 v[154:157], v137 offset:2048
	ds_read_b128 v[158:161], v137 offset:3072
	v_add_u32_e32 v137, s21, v149
	ds_read_b128 v[162:165], v137
	ds_read_b128 v[166:169], v137 offset:1024
	ds_read_b128 v[170:173], v137 offset:2048
	ds_read_b128 v[174:177], v137 offset:3072
	v_lshl_add_u64 v[146:147], s[60:61], 0, v[134:135]
	s_add_i32 m0, s25, 0xc000
	ds_read_b128 v[178:181], v153
	ds_read_b128 v[194:197], v153 offset:1024
	ds_read_b128 v[198:201], v153 offset:2048
	ds_read_b128 v[202:205], v153 offset:3072
	ds_read_b128 v[206:209], v153 offset:4096
	ds_read_b128 v[210:213], v153 offset:5120
	ds_read_b128 v[214:217], v153 offset:6144
	ds_read_b128 v[218:221], v153 offset:7168
	global_load_lds_dwordx4 v[146:147], off
	v_lshl_add_u64 v[146:147], v[146:147], 0, s[34:35]
	s_add_i32 m0, s25, 0xe000
	s_nop 0
	global_load_lds_dwordx4 v[146:147], off
	s_waitcnt vmcnt(8)
	s_waitcnt lgkmcnt(0)
	s_barrier
	s_setprio 1
	v_mfma_f32_16x16x32_bf16 v[124:127], v[138:141], v[178:181], 0
	v_mfma_f32_16x16x32_bf16 v[120:123], v[154:157], v[178:181], 0
	v_mfma_f32_16x16x32_bf16 v[108:111], v[138:141], v[198:201], 0
	v_mfma_f32_16x16x32_bf16 v[104:107], v[154:157], v[198:201], 0
	v_mfma_f32_16x16x32_bf16 v[96:99], v[138:141], v[206:209], 0
	v_mfma_f32_16x16x32_bf16 v[88:91], v[154:157], v[206:209], 0
	v_mfma_f32_16x16x32_bf16 v[80:83], v[138:141], v[214:217], 0
	v_mfma_f32_16x16x32_bf16 v[72:75], v[154:157], v[214:217], 0
	v_mfma_f32_16x16x32_bf16 v[124:127], v[142:145], v[194:197], v[124:127]
	v_mfma_f32_16x16x32_bf16 v[120:123], v[158:161], v[194:197], v[120:123]
	v_mfma_f32_16x16x32_bf16 v[108:111], v[142:145], v[202:205], v[108:111]
	v_mfma_f32_16x16x32_bf16 v[104:107], v[158:161], v[202:205], v[104:107]
	v_mfma_f32_16x16x32_bf16 v[96:99], v[142:145], v[210:213], v[96:99]
	v_mfma_f32_16x16x32_bf16 v[88:91], v[158:161], v[210:213], v[88:91]
	v_mfma_f32_16x16x32_bf16 v[80:83], v[142:145], v[218:221], v[80:83]
	v_mfma_f32_16x16x32_bf16 v[72:75], v[158:161], v[218:221], v[72:75]
	v_mfma_f32_16x16x32_bf16 v[116:119], v[162:165], v[178:181], 0
	v_mfma_f32_16x16x32_bf16 v[112:115], v[170:173], v[178:181], 0
	v_mfma_f32_16x16x32_bf16 v[100:103], v[162:165], v[198:201], 0
	v_mfma_f32_16x16x32_bf16 v[92:95], v[170:173], v[198:201], 0
	v_mfma_f32_16x16x32_bf16 v[84:87], v[162:165], v[206:209], 0
	v_mfma_f32_16x16x32_bf16 v[76:79], v[170:173], v[206:209], 0
	v_mfma_f32_16x16x32_bf16 v[68:71], v[162:165], v[214:217], 0
	v_mfma_f32_16x16x32_bf16 v[64:67], v[170:173], v[214:217], 0
	v_mfma_f32_16x16x32_bf16 v[116:119], v[166:169], v[194:197], v[116:119]
	v_mfma_f32_16x16x32_bf16 v[112:115], v[174:177], v[194:197], v[112:115]
	v_mfma_f32_16x16x32_bf16 v[100:103], v[166:169], v[202:205], v[100:103]
	v_mfma_f32_16x16x32_bf16 v[92:95], v[174:177], v[202:205], v[92:95]
	v_mfma_f32_16x16x32_bf16 v[84:87], v[166:169], v[210:213], v[84:87]
	v_mfma_f32_16x16x32_bf16 v[76:79], v[174:177], v[210:213], v[76:79]
	v_mfma_f32_16x16x32_bf16 v[68:71], v[166:169], v[218:221], v[68:71]
	v_mfma_f32_16x16x32_bf16 v[64:67], v[174:177], v[218:221], v[64:67]
	s_setprio 0
	s_barrier
	s_add_i32 s18, s18, s23
	v_lshl_add_u64 v[146:147], vcc, 0, v[128:129]
	s_mov_b32 m0, s18
	ds_read_b128 v[178:181], v153 offset:16384
	ds_read_b128 v[194:197], v153 offset:17408
	ds_read_b128 v[198:201], v153 offset:18432
	ds_read_b128 v[202:205], v153 offset:19456
	ds_read_b128 v[206:209], v153 offset:20480
	ds_read_b128 v[210:213], v153 offset:21504
	ds_read_b128 v[214:217], v153 offset:22528
	ds_read_b128 v[218:221], v153 offset:23552
	global_load_lds_dwordx4 v[146:147], off
	v_lshl_add_u64 v[182:183], v[146:147], 0, s[34:35]
	s_add_i32 m0, s18, 0x2000
	s_add_i32 s18, s21, s23
	global_load_lds_dwordx4 v[182:183], off
	v_lshl_add_u64 v[182:183], v[146:147], 0, s[92:93]
	s_mov_b32 m0, s18
	s_nop 0
	global_load_lds_dwordx4 v[182:183], off
	v_lshl_add_u64 v[182:183], v[146:147], 0, s[52:53]
	s_add_i32 m0, s18, 0x2000
	s_nop 0
	global_load_lds_dwordx4 v[182:183], off
	v_lshl_add_u64 v[182:183], s[14:15], 0, v[130:131]
	s_mov_b32 m0, s25
	v_lshl_add_u64 v[186:187], v[182:183], 0, s[34:35]
	global_load_lds_dwordx4 v[182:183], off
	s_mov_b32 m0, s26
	s_nop 0
	global_load_lds_dwordx4 v[186:187], off
	s_waitcnt vmcnt(8)
	s_waitcnt lgkmcnt(0)
	s_barrier
	s_setprio 1
	v_mfma_f32_16x16x32_bf16 v[60:63], v[138:141], v[178:181], 0
	v_mfma_f32_16x16x32_bf16 v[56:59], v[154:157], v[178:181], 0
	v_mfma_f32_16x16x32_bf16 v[48:51], v[138:141], v[198:201], 0
	v_mfma_f32_16x16x32_bf16 v[40:43], v[154:157], v[198:201], 0
	v_mfma_f32_16x16x32_bf16 v[32:35], v[138:141], v[206:209], 0
	v_mfma_f32_16x16x32_bf16 v[24:27], v[154:157], v[206:209], 0
	v_mfma_f32_16x16x32_bf16 v[16:19], v[138:141], v[214:217], 0
	v_mfma_f32_16x16x32_bf16 v[8:11], v[154:157], v[214:217], 0
	v_mfma_f32_16x16x32_bf16 v[60:63], v[142:145], v[194:197], v[60:63]
	v_mfma_f32_16x16x32_bf16 v[56:59], v[158:161], v[194:197], v[56:59]
	v_mfma_f32_16x16x32_bf16 v[48:51], v[142:145], v[202:205], v[48:51]
	v_mfma_f32_16x16x32_bf16 v[40:43], v[158:161], v[202:205], v[40:43]
	v_mfma_f32_16x16x32_bf16 v[32:35], v[142:145], v[210:213], v[32:35]
	v_mfma_f32_16x16x32_bf16 v[24:27], v[158:161], v[210:213], v[24:27]
	v_mfma_f32_16x16x32_bf16 v[16:19], v[142:145], v[218:221], v[16:19]
	v_mfma_f32_16x16x32_bf16 v[8:11], v[158:161], v[218:221], v[8:11]
	v_mfma_f32_16x16x32_bf16 v[52:55], v[162:165], v[178:181], 0
	v_mfma_f32_16x16x32_bf16 v[44:47], v[170:173], v[178:181], 0
	v_mfma_f32_16x16x32_bf16 v[36:39], v[162:165], v[198:201], 0
	v_mfma_f32_16x16x32_bf16 v[28:31], v[170:173], v[198:201], 0
	v_mfma_f32_16x16x32_bf16 v[20:23], v[162:165], v[206:209], 0
	v_mfma_f32_16x16x32_bf16 v[12:15], v[170:173], v[206:209], 0
	v_mfma_f32_16x16x32_bf16 v[4:7], v[162:165], v[214:217], 0
	v_mfma_f32_16x16x32_bf16 v[0:3], v[170:173], v[214:217], 0
	v_mfma_f32_16x16x32_bf16 v[52:55], v[166:169], v[194:197], v[52:55]
	v_mfma_f32_16x16x32_bf16 v[44:47], v[174:177], v[194:197], v[44:47]
	v_mfma_f32_16x16x32_bf16 v[36:39], v[166:169], v[202:205], v[36:39]
	v_mfma_f32_16x16x32_bf16 v[28:31], v[174:177], v[202:205], v[28:31]
	v_mfma_f32_16x16x32_bf16 v[20:23], v[166:169], v[210:213], v[20:23]
	v_mfma_f32_16x16x32_bf16 v[12:15], v[174:177], v[210:213], v[12:15]
	v_mfma_f32_16x16x32_bf16 v[4:7], v[166:169], v[218:221], v[4:7]
	v_mfma_f32_16x16x32_bf16 v[0:3], v[174:177], v[218:221], v[0:3]
	s_setprio 0
	s_barrier
	s_add_i32 s14, 0, 0x18000
	v_add_u32_e32 v137, s14, v149
	s_add_i32 s15, 0, 0x1c000
	ds_read_b128 v[138:141], v137
	ds_read_b128 v[142:145], v137 offset:1024
	ds_read_b128 v[154:157], v137 offset:2048
	ds_read_b128 v[158:161], v137 offset:3072
	v_add_u32_e32 v137, s15, v149
	ds_read_b128 v[162:165], v137
	ds_read_b128 v[166:169], v137 offset:1024
	ds_read_b128 v[170:173], v137 offset:2048
	ds_read_b128 v[174:177], v137 offset:3072
	s_mov_b32 m0, s27
	v_lshl_add_u64 v[186:187], v[182:183], 0, s[92:93]
	ds_read_b128 v[178:181], v153 offset:32768
	ds_read_b128 v[194:197], v153 offset:33792
	ds_read_b128 v[198:201], v153 offset:34816
	ds_read_b128 v[202:205], v153 offset:35840
	ds_read_b128 v[206:209], v153 offset:36864
	ds_read_b128 v[210:213], v153 offset:37888
	ds_read_b128 v[214:217], v153 offset:38912
	ds_read_b128 v[218:221], v153 offset:39936
	global_load_lds_dwordx4 v[186:187], off
	v_lshl_add_u64 v[186:187], v[182:183], 0, s[52:53]
	s_mov_b32 m0, s28
	s_nop 0
	global_load_lds_dwordx4 v[186:187], off
	s_waitcnt vmcnt(8)
	s_waitcnt lgkmcnt(0)
	s_barrier
	s_setprio 1
	v_mfma_f32_16x16x32_bf16 v[124:127], v[138:141], v[178:181], v[124:127]
	v_mfma_f32_16x16x32_bf16 v[120:123], v[154:157], v[178:181], v[120:123]
	v_mfma_f32_16x16x32_bf16 v[108:111], v[138:141], v[198:201], v[108:111]
	v_mfma_f32_16x16x32_bf16 v[104:107], v[154:157], v[198:201], v[104:107]
	v_mfma_f32_16x16x32_bf16 v[96:99], v[138:141], v[206:209], v[96:99]
	v_mfma_f32_16x16x32_bf16 v[88:91], v[154:157], v[206:209], v[88:91]
	v_mfma_f32_16x16x32_bf16 v[80:83], v[138:141], v[214:217], v[80:83]
	v_mfma_f32_16x16x32_bf16 v[72:75], v[154:157], v[214:217], v[72:75]
	v_mfma_f32_16x16x32_bf16 v[124:127], v[142:145], v[194:197], v[124:127]
	v_mfma_f32_16x16x32_bf16 v[120:123], v[158:161], v[194:197], v[120:123]
	v_mfma_f32_16x16x32_bf16 v[108:111], v[142:145], v[202:205], v[108:111]
	v_mfma_f32_16x16x32_bf16 v[104:107], v[158:161], v[202:205], v[104:107]
	v_mfma_f32_16x16x32_bf16 v[96:99], v[142:145], v[210:213], v[96:99]
	v_mfma_f32_16x16x32_bf16 v[88:91], v[158:161], v[210:213], v[88:91]
	v_mfma_f32_16x16x32_bf16 v[80:83], v[142:145], v[218:221], v[80:83]
	v_mfma_f32_16x16x32_bf16 v[72:75], v[158:161], v[218:221], v[72:75]
	v_mfma_f32_16x16x32_bf16 v[116:119], v[162:165], v[178:181], v[116:119]
	v_mfma_f32_16x16x32_bf16 v[112:115], v[170:173], v[178:181], v[112:115]
	v_mfma_f32_16x16x32_bf16 v[100:103], v[162:165], v[198:201], v[100:103]
	v_mfma_f32_16x16x32_bf16 v[92:95], v[170:173], v[198:201], v[92:95]
	v_mfma_f32_16x16x32_bf16 v[84:87], v[162:165], v[206:209], v[84:87]
	v_mfma_f32_16x16x32_bf16 v[76:79], v[170:173], v[206:209], v[76:79]
	v_mfma_f32_16x16x32_bf16 v[68:71], v[162:165], v[214:217], v[68:71]
	v_mfma_f32_16x16x32_bf16 v[64:67], v[170:173], v[214:217], v[64:67]
	v_mfma_f32_16x16x32_bf16 v[116:119], v[166:169], v[194:197], v[116:119]
	v_mfma_f32_16x16x32_bf16 v[112:115], v[174:177], v[194:197], v[112:115]
	v_mfma_f32_16x16x32_bf16 v[100:103], v[166:169], v[202:205], v[100:103]
	v_mfma_f32_16x16x32_bf16 v[92:95], v[174:177], v[202:205], v[92:95]
	v_mfma_f32_16x16x32_bf16 v[84:87], v[166:169], v[210:213], v[84:87]
	v_mfma_f32_16x16x32_bf16 v[76:79], v[174:177], v[210:213], v[76:79]
	v_mfma_f32_16x16x32_bf16 v[68:71], v[166:169], v[218:221], v[68:71]
	v_mfma_f32_16x16x32_bf16 v[64:67], v[174:177], v[218:221], v[64:67]
	s_setprio 0
	s_barrier
	s_add_i32 s14, s14, s23
	v_lshl_add_u64 v[186:187], v[146:147], 0, s[56:57]
	s_mov_b32 m0, s14
	ds_read_b128 v[178:181], v153 offset:49152
	ds_read_b128 v[194:197], v153 offset:50176
	ds_read_b128 v[198:201], v153 offset:51200
	ds_read_b128 v[202:205], v153 offset:52224
	ds_read_b128 v[206:209], v153 offset:53248
	ds_read_b128 v[210:213], v153 offset:54272
	ds_read_b128 v[214:217], v153 offset:55296
	ds_read_b128 v[218:221], v153 offset:56320
	global_load_lds_dwordx4 v[186:187], off
	v_lshl_add_u64 v[186:187], v[146:147], 0, s[96:97]
	s_add_i32 m0, s14, 0x2000
	s_add_i32 s14, s15, s23
	global_load_lds_dwordx4 v[186:187], off
	v_lshl_add_u64 v[186:187], v[146:147], 0, s[88:89]
	s_mov_b32 m0, s14
	v_lshl_add_u64 v[146:147], v[146:147], 0, s[68:69]
	global_load_lds_dwordx4 v[186:187], off
	s_add_i32 m0, s14, 0x2000
	s_nop 0
	global_load_lds_dwordx4 v[146:147], off
	v_lshl_add_u64 v[146:147], v[182:183], 0, s[56:57]
	s_mov_b32 m0, s29
	s_nop 0
	global_load_lds_dwordx4 v[146:147], off
	v_lshl_add_u64 v[146:147], v[182:183], 0, s[96:97]
	s_mov_b32 m0, s30
	s_nop 0
	global_load_lds_dwordx4 v[146:147], off
	s_waitcnt vmcnt(8)
	s_waitcnt lgkmcnt(0)
	s_barrier
	s_setprio 1
	v_mfma_f32_16x16x32_bf16 v[60:63], v[138:141], v[178:181], v[60:63]
	v_mfma_f32_16x16x32_bf16 v[56:59], v[154:157], v[178:181], v[56:59]
	v_mfma_f32_16x16x32_bf16 v[48:51], v[138:141], v[198:201], v[48:51]
	v_mfma_f32_16x16x32_bf16 v[40:43], v[154:157], v[198:201], v[40:43]
	v_mfma_f32_16x16x32_bf16 v[32:35], v[138:141], v[206:209], v[32:35]
	v_mfma_f32_16x16x32_bf16 v[24:27], v[154:157], v[206:209], v[24:27]
	v_mfma_f32_16x16x32_bf16 v[16:19], v[138:141], v[214:217], v[16:19]
	v_mfma_f32_16x16x32_bf16 v[8:11], v[154:157], v[214:217], v[8:11]
	v_mfma_f32_16x16x32_bf16 v[60:63], v[142:145], v[194:197], v[60:63]
	v_mfma_f32_16x16x32_bf16 v[56:59], v[158:161], v[194:197], v[56:59]
	v_mfma_f32_16x16x32_bf16 v[48:51], v[142:145], v[202:205], v[48:51]
	v_mfma_f32_16x16x32_bf16 v[40:43], v[158:161], v[202:205], v[40:43]
	v_mfma_f32_16x16x32_bf16 v[32:35], v[142:145], v[210:213], v[32:35]
	v_mfma_f32_16x16x32_bf16 v[24:27], v[158:161], v[210:213], v[24:27]
	v_mfma_f32_16x16x32_bf16 v[16:19], v[142:145], v[218:221], v[16:19]
	v_mfma_f32_16x16x32_bf16 v[8:11], v[158:161], v[218:221], v[8:11]
	v_mfma_f32_16x16x32_bf16 v[52:55], v[162:165], v[178:181], v[52:55]
	v_mfma_f32_16x16x32_bf16 v[44:47], v[170:173], v[178:181], v[44:47]
	v_mfma_f32_16x16x32_bf16 v[36:39], v[162:165], v[198:201], v[36:39]
	v_mfma_f32_16x16x32_bf16 v[28:31], v[170:173], v[198:201], v[28:31]
	v_mfma_f32_16x16x32_bf16 v[20:23], v[162:165], v[206:209], v[20:23]
	v_mfma_f32_16x16x32_bf16 v[12:15], v[170:173], v[206:209], v[12:15]
	v_mfma_f32_16x16x32_bf16 v[4:7], v[162:165], v[214:217], v[4:7]
	v_mfma_f32_16x16x32_bf16 v[0:3], v[170:173], v[214:217], v[0:3]
	v_mfma_f32_16x16x32_bf16 v[52:55], v[166:169], v[194:197], v[52:55]
	v_mfma_f32_16x16x32_bf16 v[44:47], v[174:177], v[194:197], v[44:47]
	v_mfma_f32_16x16x32_bf16 v[36:39], v[166:169], v[202:205], v[36:39]
	v_mfma_f32_16x16x32_bf16 v[28:31], v[174:177], v[202:205], v[28:31]
	v_mfma_f32_16x16x32_bf16 v[20:23], v[166:169], v[210:213], v[20:23]
	v_mfma_f32_16x16x32_bf16 v[12:15], v[174:177], v[210:213], v[12:15]
	v_mfma_f32_16x16x32_bf16 v[4:7], v[166:169], v[218:221], v[4:7]
	v_mfma_f32_16x16x32_bf16 v[0:3], v[174:177], v[218:221], v[0:3]
	s_setprio 0
	s_barrier
	s_add_i32 s85, s85, 2
	s_add_u32 s60, s60, 0x100
	s_addc_u32 s61, s61, 0
	s_add_u32 s16, s16, 0x100
	s_addc_u32 s17, s17, 0
	s_cmp_gt_u32 s85, 13
.LBB0_249:
	s_add_u32 s14, s60, 0xfffc0080
	s_addc_u32 s15, s61, -1
	s_add_i32 s18, 0, 0x10000
	s_cmp_eq_u32 s85, 12
	s_cselect_b32 s15, s22, s15
	s_cselect_b32 s14, s45, s14
	s_waitcnt lgkmcnt(0)
	v_add_u32_e32 v137, s18, v149
	s_cselect_b32 vcc_hi, s43, s17
	s_cselect_b32 vcc_lo, s84, s16
	s_add_i32 s21, 0, 0x14000
	ds_read_b128 v[138:141], v137
	ds_read_b128 v[142:145], v137 offset:1024
	ds_read_b128 v[154:157], v137 offset:2048
	ds_read_b128 v[158:161], v137 offset:3072
	v_add_u32_e32 v137, s21, v149
	ds_read_b128 v[162:165], v137
	ds_read_b128 v[166:169], v137 offset:1024
	ds_read_b128 v[170:173], v137 offset:2048
	ds_read_b128 v[174:177], v137 offset:3072
	v_lshl_add_u64 v[146:147], s[60:61], 0, v[134:135]
	s_add_i32 m0, s25, 0xc000
	ds_read_b128 v[178:181], v153
	ds_read_b128 v[194:197], v153 offset:1024
	ds_read_b128 v[198:201], v153 offset:2048
	ds_read_b128 v[202:205], v153 offset:3072
	ds_read_b128 v[206:209], v153 offset:4096
	ds_read_b128 v[210:213], v153 offset:5120
	ds_read_b128 v[214:217], v153 offset:6144
	ds_read_b128 v[218:221], v153 offset:7168
	global_load_lds_dwordx4 v[146:147], off
	v_lshl_add_u64 v[146:147], v[146:147], 0, s[34:35]
	s_add_i32 m0, s25, 0xe000
	s_nop 0
	global_load_lds_dwordx4 v[146:147], off
	s_waitcnt vmcnt(8)
	s_waitcnt lgkmcnt(0)
	s_barrier
	s_setprio 1
	v_mfma_f32_16x16x32_bf16 v[124:127], v[138:141], v[178:181], v[124:127]
	v_mfma_f32_16x16x32_bf16 v[120:123], v[154:157], v[178:181], v[120:123]
	v_mfma_f32_16x16x32_bf16 v[108:111], v[138:141], v[198:201], v[108:111]
	v_mfma_f32_16x16x32_bf16 v[104:107], v[154:157], v[198:201], v[104:107]
	v_mfma_f32_16x16x32_bf16 v[96:99], v[138:141], v[206:209], v[96:99]
	v_mfma_f32_16x16x32_bf16 v[88:91], v[154:157], v[206:209], v[88:91]
	v_mfma_f32_16x16x32_bf16 v[80:83], v[138:141], v[214:217], v[80:83]
	v_mfma_f32_16x16x32_bf16 v[72:75], v[154:157], v[214:217], v[72:75]
	v_mfma_f32_16x16x32_bf16 v[124:127], v[142:145], v[194:197], v[124:127]
	v_mfma_f32_16x16x32_bf16 v[120:123], v[158:161], v[194:197], v[120:123]
	v_mfma_f32_16x16x32_bf16 v[108:111], v[142:145], v[202:205], v[108:111]
	v_mfma_f32_16x16x32_bf16 v[104:107], v[158:161], v[202:205], v[104:107]
	v_mfma_f32_16x16x32_bf16 v[96:99], v[142:145], v[210:213], v[96:99]
	v_mfma_f32_16x16x32_bf16 v[88:91], v[158:161], v[210:213], v[88:91]
	v_mfma_f32_16x16x32_bf16 v[80:83], v[142:145], v[218:221], v[80:83]
	v_mfma_f32_16x16x32_bf16 v[72:75], v[158:161], v[218:221], v[72:75]
	v_mfma_f32_16x16x32_bf16 v[116:119], v[162:165], v[178:181], v[116:119]
	v_mfma_f32_16x16x32_bf16 v[112:115], v[170:173], v[178:181], v[112:115]
	v_mfma_f32_16x16x32_bf16 v[100:103], v[162:165], v[198:201], v[100:103]
	v_mfma_f32_16x16x32_bf16 v[92:95], v[170:173], v[198:201], v[92:95]
	v_mfma_f32_16x16x32_bf16 v[84:87], v[162:165], v[206:209], v[84:87]
	v_mfma_f32_16x16x32_bf16 v[76:79], v[170:173], v[206:209], v[76:79]
	v_mfma_f32_16x16x32_bf16 v[68:71], v[162:165], v[214:217], v[68:71]
	v_mfma_f32_16x16x32_bf16 v[64:67], v[170:173], v[214:217], v[64:67]
	v_mfma_f32_16x16x32_bf16 v[116:119], v[166:169], v[194:197], v[116:119]
	v_mfma_f32_16x16x32_bf16 v[112:115], v[174:177], v[194:197], v[112:115]
	v_mfma_f32_16x16x32_bf16 v[100:103], v[166:169], v[202:205], v[100:103]
	v_mfma_f32_16x16x32_bf16 v[92:95], v[174:177], v[202:205], v[92:95]
	v_mfma_f32_16x16x32_bf16 v[84:87], v[166:169], v[210:213], v[84:87]
	v_mfma_f32_16x16x32_bf16 v[76:79], v[174:177], v[210:213], v[76:79]
	v_mfma_f32_16x16x32_bf16 v[68:71], v[166:169], v[218:221], v[68:71]
	v_mfma_f32_16x16x32_bf16 v[64:67], v[174:177], v[218:221], v[64:67]
	s_setprio 0
	s_barrier
	s_add_i32 s18, s18, s23
	v_lshl_add_u64 v[146:147], vcc, 0, v[128:129]
	s_mov_b32 m0, s18
	ds_read_b128 v[178:181], v153 offset:16384
	ds_read_b128 v[194:197], v153 offset:17408
	ds_read_b128 v[198:201], v153 offset:18432
	ds_read_b128 v[202:205], v153 offset:19456
	ds_read_b128 v[206:209], v153 offset:20480
	ds_read_b128 v[210:213], v153 offset:21504
	ds_read_b128 v[214:217], v153 offset:22528
	ds_read_b128 v[218:221], v153 offset:23552
	global_load_lds_dwordx4 v[146:147], off
	v_lshl_add_u64 v[182:183], v[146:147], 0, s[34:35]
	s_add_i32 m0, s18, 0x2000
	s_add_i32 s18, s21, s23
	global_load_lds_dwordx4 v[182:183], off
	v_lshl_add_u64 v[182:183], v[146:147], 0, s[92:93]
	s_mov_b32 m0, s18
	s_nop 0
	global_load_lds_dwordx4 v[182:183], off
	v_lshl_add_u64 v[182:183], v[146:147], 0, s[52:53]
	s_add_i32 m0, s18, 0x2000
	s_nop 0
	global_load_lds_dwordx4 v[182:183], off
	v_lshl_add_u64 v[182:183], s[14:15], 0, v[130:131]
	s_mov_b32 m0, s25
	v_lshl_add_u64 v[186:187], v[182:183], 0, s[34:35]
	global_load_lds_dwordx4 v[182:183], off
	s_mov_b32 m0, s26
	s_nop 0
	global_load_lds_dwordx4 v[186:187], off
	s_waitcnt vmcnt(8)
	s_waitcnt lgkmcnt(0)
	s_barrier
	s_setprio 1
	v_mfma_f32_16x16x32_bf16 v[60:63], v[138:141], v[178:181], v[60:63]
	v_mfma_f32_16x16x32_bf16 v[56:59], v[154:157], v[178:181], v[56:59]
	v_mfma_f32_16x16x32_bf16 v[48:51], v[138:141], v[198:201], v[48:51]
	v_mfma_f32_16x16x32_bf16 v[40:43], v[154:157], v[198:201], v[40:43]
	v_mfma_f32_16x16x32_bf16 v[32:35], v[138:141], v[206:209], v[32:35]
	v_mfma_f32_16x16x32_bf16 v[24:27], v[154:157], v[206:209], v[24:27]
	v_mfma_f32_16x16x32_bf16 v[16:19], v[138:141], v[214:217], v[16:19]
	v_mfma_f32_16x16x32_bf16 v[8:11], v[154:157], v[214:217], v[8:11]
	v_mfma_f32_16x16x32_bf16 v[60:63], v[142:145], v[194:197], v[60:63]
	v_mfma_f32_16x16x32_bf16 v[56:59], v[158:161], v[194:197], v[56:59]
	v_mfma_f32_16x16x32_bf16 v[48:51], v[142:145], v[202:205], v[48:51]
	v_mfma_f32_16x16x32_bf16 v[40:43], v[158:161], v[202:205], v[40:43]
	v_mfma_f32_16x16x32_bf16 v[32:35], v[142:145], v[210:213], v[32:35]
	v_mfma_f32_16x16x32_bf16 v[24:27], v[158:161], v[210:213], v[24:27]
	v_mfma_f32_16x16x32_bf16 v[16:19], v[142:145], v[218:221], v[16:19]
	v_mfma_f32_16x16x32_bf16 v[8:11], v[158:161], v[218:221], v[8:11]
	v_mfma_f32_16x16x32_bf16 v[52:55], v[162:165], v[178:181], v[52:55]
	v_mfma_f32_16x16x32_bf16 v[44:47], v[170:173], v[178:181], v[44:47]
	v_mfma_f32_16x16x32_bf16 v[36:39], v[162:165], v[198:201], v[36:39]
	v_mfma_f32_16x16x32_bf16 v[28:31], v[170:173], v[198:201], v[28:31]
	v_mfma_f32_16x16x32_bf16 v[20:23], v[162:165], v[206:209], v[20:23]
	v_mfma_f32_16x16x32_bf16 v[12:15], v[170:173], v[206:209], v[12:15]
	v_mfma_f32_16x16x32_bf16 v[4:7], v[162:165], v[214:217], v[4:7]
	v_mfma_f32_16x16x32_bf16 v[0:3], v[170:173], v[214:217], v[0:3]
	v_mfma_f32_16x16x32_bf16 v[52:55], v[166:169], v[194:197], v[52:55]
	v_mfma_f32_16x16x32_bf16 v[44:47], v[174:177], v[194:197], v[44:47]
	v_mfma_f32_16x16x32_bf16 v[36:39], v[166:169], v[202:205], v[36:39]
	v_mfma_f32_16x16x32_bf16 v[28:31], v[174:177], v[202:205], v[28:31]
	v_mfma_f32_16x16x32_bf16 v[20:23], v[166:169], v[210:213], v[20:23]
	v_mfma_f32_16x16x32_bf16 v[12:15], v[174:177], v[210:213], v[12:15]
	v_mfma_f32_16x16x32_bf16 v[4:7], v[166:169], v[218:221], v[4:7]
	v_mfma_f32_16x16x32_bf16 v[0:3], v[174:177], v[218:221], v[0:3]
	s_setprio 0
	s_barrier
	s_add_i32 s14, 0, 0x18000
	v_add_u32_e32 v137, s14, v149
	s_add_i32 s15, 0, 0x1c000
	ds_read_b128 v[138:141], v137
	ds_read_b128 v[142:145], v137 offset:1024
	ds_read_b128 v[154:157], v137 offset:2048
	ds_read_b128 v[158:161], v137 offset:3072
	v_add_u32_e32 v137, s15, v149
	ds_read_b128 v[162:165], v137
	ds_read_b128 v[166:169], v137 offset:1024
	ds_read_b128 v[170:173], v137 offset:2048
	ds_read_b128 v[174:177], v137 offset:3072
	s_mov_b32 m0, s27
	v_lshl_add_u64 v[186:187], v[182:183], 0, s[92:93]
	ds_read_b128 v[178:181], v153 offset:32768
	ds_read_b128 v[194:197], v153 offset:33792
	ds_read_b128 v[198:201], v153 offset:34816
	ds_read_b128 v[202:205], v153 offset:35840
	ds_read_b128 v[206:209], v153 offset:36864
	ds_read_b128 v[210:213], v153 offset:37888
	ds_read_b128 v[214:217], v153 offset:38912
	ds_read_b128 v[218:221], v153 offset:39936
	global_load_lds_dwordx4 v[186:187], off
	v_lshl_add_u64 v[186:187], v[182:183], 0, s[52:53]
	s_mov_b32 m0, s28
	s_nop 0
	global_load_lds_dwordx4 v[186:187], off
	s_waitcnt vmcnt(8)
	s_waitcnt lgkmcnt(0)
	s_barrier
	s_setprio 1
	v_mfma_f32_16x16x32_bf16 v[124:127], v[138:141], v[178:181], v[124:127]
	v_mfma_f32_16x16x32_bf16 v[120:123], v[154:157], v[178:181], v[120:123]
	v_mfma_f32_16x16x32_bf16 v[108:111], v[138:141], v[198:201], v[108:111]
	v_mfma_f32_16x16x32_bf16 v[104:107], v[154:157], v[198:201], v[104:107]
	v_mfma_f32_16x16x32_bf16 v[96:99], v[138:141], v[206:209], v[96:99]
	v_mfma_f32_16x16x32_bf16 v[88:91], v[154:157], v[206:209], v[88:91]
	v_mfma_f32_16x16x32_bf16 v[80:83], v[138:141], v[214:217], v[80:83]
	v_mfma_f32_16x16x32_bf16 v[72:75], v[154:157], v[214:217], v[72:75]
	v_mfma_f32_16x16x32_bf16 v[124:127], v[142:145], v[194:197], v[124:127]
	v_mfma_f32_16x16x32_bf16 v[120:123], v[158:161], v[194:197], v[120:123]
	v_mfma_f32_16x16x32_bf16 v[108:111], v[142:145], v[202:205], v[108:111]
	v_mfma_f32_16x16x32_bf16 v[104:107], v[158:161], v[202:205], v[104:107]
	v_mfma_f32_16x16x32_bf16 v[96:99], v[142:145], v[210:213], v[96:99]
	v_mfma_f32_16x16x32_bf16 v[88:91], v[158:161], v[210:213], v[88:91]
	v_mfma_f32_16x16x32_bf16 v[80:83], v[142:145], v[218:221], v[80:83]
	v_mfma_f32_16x16x32_bf16 v[72:75], v[158:161], v[218:221], v[72:75]
	v_mfma_f32_16x16x32_bf16 v[116:119], v[162:165], v[178:181], v[116:119]
	v_mfma_f32_16x16x32_bf16 v[112:115], v[170:173], v[178:181], v[112:115]
	v_mfma_f32_16x16x32_bf16 v[100:103], v[162:165], v[198:201], v[100:103]
	v_mfma_f32_16x16x32_bf16 v[92:95], v[170:173], v[198:201], v[92:95]
	v_mfma_f32_16x16x32_bf16 v[84:87], v[162:165], v[206:209], v[84:87]
	v_mfma_f32_16x16x32_bf16 v[76:79], v[170:173], v[206:209], v[76:79]
	v_mfma_f32_16x16x32_bf16 v[68:71], v[162:165], v[214:217], v[68:71]
	v_mfma_f32_16x16x32_bf16 v[64:67], v[170:173], v[214:217], v[64:67]
	v_mfma_f32_16x16x32_bf16 v[116:119], v[166:169], v[194:197], v[116:119]
	v_mfma_f32_16x16x32_bf16 v[112:115], v[174:177], v[194:197], v[112:115]
	v_mfma_f32_16x16x32_bf16 v[100:103], v[166:169], v[202:205], v[100:103]
	v_mfma_f32_16x16x32_bf16 v[92:95], v[174:177], v[202:205], v[92:95]
	v_mfma_f32_16x16x32_bf16 v[84:87], v[166:169], v[210:213], v[84:87]
	v_mfma_f32_16x16x32_bf16 v[76:79], v[174:177], v[210:213], v[76:79]
	v_mfma_f32_16x16x32_bf16 v[68:71], v[166:169], v[218:221], v[68:71]
	v_mfma_f32_16x16x32_bf16 v[64:67], v[174:177], v[218:221], v[64:67]
	s_setprio 0
	s_barrier
	s_add_i32 s14, s14, s23
	v_lshl_add_u64 v[186:187], v[146:147], 0, s[56:57]
	s_mov_b32 m0, s14
	ds_read_b128 v[178:181], v153 offset:49152
	ds_read_b128 v[194:197], v153 offset:50176
	ds_read_b128 v[198:201], v153 offset:51200
	ds_read_b128 v[202:205], v153 offset:52224
	ds_read_b128 v[206:209], v153 offset:53248
	ds_read_b128 v[210:213], v153 offset:54272
	ds_read_b128 v[214:217], v153 offset:55296
	ds_read_b128 v[218:221], v153 offset:56320
	global_load_lds_dwordx4 v[186:187], off
	v_lshl_add_u64 v[186:187], v[146:147], 0, s[96:97]
	s_add_i32 m0, s14, 0x2000
	s_add_i32 s14, s15, s23
	global_load_lds_dwordx4 v[186:187], off
	v_lshl_add_u64 v[186:187], v[146:147], 0, s[88:89]
	s_mov_b32 m0, s14
	v_lshl_add_u64 v[146:147], v[146:147], 0, s[68:69]
	global_load_lds_dwordx4 v[186:187], off
	s_add_i32 m0, s14, 0x2000
	s_nop 0
	global_load_lds_dwordx4 v[146:147], off
	v_lshl_add_u64 v[146:147], v[182:183], 0, s[56:57]
	s_mov_b32 m0, s29
	s_nop 0
	global_load_lds_dwordx4 v[146:147], off
	v_lshl_add_u64 v[146:147], v[182:183], 0, s[96:97]
	s_mov_b32 m0, s30
	s_nop 0
	global_load_lds_dwordx4 v[146:147], off
	s_waitcnt vmcnt(8)
	s_waitcnt lgkmcnt(0)
	s_barrier
	s_setprio 1
	v_mfma_f32_16x16x32_bf16 v[60:63], v[138:141], v[178:181], v[60:63]
	v_mfma_f32_16x16x32_bf16 v[56:59], v[154:157], v[178:181], v[56:59]
	v_mfma_f32_16x16x32_bf16 v[48:51], v[138:141], v[198:201], v[48:51]
	v_mfma_f32_16x16x32_bf16 v[40:43], v[154:157], v[198:201], v[40:43]
	v_mfma_f32_16x16x32_bf16 v[32:35], v[138:141], v[206:209], v[32:35]
	v_mfma_f32_16x16x32_bf16 v[24:27], v[154:157], v[206:209], v[24:27]
	v_mfma_f32_16x16x32_bf16 v[16:19], v[138:141], v[214:217], v[16:19]
	v_mfma_f32_16x16x32_bf16 v[8:11], v[154:157], v[214:217], v[8:11]
	v_mfma_f32_16x16x32_bf16 v[60:63], v[142:145], v[194:197], v[60:63]
	v_mfma_f32_16x16x32_bf16 v[56:59], v[158:161], v[194:197], v[56:59]
	v_mfma_f32_16x16x32_bf16 v[48:51], v[142:145], v[202:205], v[48:51]
	v_mfma_f32_16x16x32_bf16 v[40:43], v[158:161], v[202:205], v[40:43]
	v_mfma_f32_16x16x32_bf16 v[32:35], v[142:145], v[210:213], v[32:35]
	v_mfma_f32_16x16x32_bf16 v[24:27], v[158:161], v[210:213], v[24:27]
	v_mfma_f32_16x16x32_bf16 v[16:19], v[142:145], v[218:221], v[16:19]
	v_mfma_f32_16x16x32_bf16 v[8:11], v[158:161], v[218:221], v[8:11]
	v_mfma_f32_16x16x32_bf16 v[52:55], v[162:165], v[178:181], v[52:55]
	v_mfma_f32_16x16x32_bf16 v[44:47], v[170:173], v[178:181], v[44:47]
	v_mfma_f32_16x16x32_bf16 v[36:39], v[162:165], v[198:201], v[36:39]
	v_mfma_f32_16x16x32_bf16 v[28:31], v[170:173], v[198:201], v[28:31]
	v_mfma_f32_16x16x32_bf16 v[20:23], v[162:165], v[206:209], v[20:23]
	v_mfma_f32_16x16x32_bf16 v[12:15], v[170:173], v[206:209], v[12:15]
	v_mfma_f32_16x16x32_bf16 v[4:7], v[162:165], v[214:217], v[4:7]
	v_mfma_f32_16x16x32_bf16 v[0:3], v[170:173], v[214:217], v[0:3]
	v_mfma_f32_16x16x32_bf16 v[52:55], v[166:169], v[194:197], v[52:55]
	v_mfma_f32_16x16x32_bf16 v[44:47], v[174:177], v[194:197], v[44:47]
	v_mfma_f32_16x16x32_bf16 v[36:39], v[166:169], v[202:205], v[36:39]
	v_mfma_f32_16x16x32_bf16 v[28:31], v[174:177], v[202:205], v[28:31]
	v_mfma_f32_16x16x32_bf16 v[20:23], v[166:169], v[210:213], v[20:23]
	v_mfma_f32_16x16x32_bf16 v[12:15], v[174:177], v[210:213], v[12:15]
	v_mfma_f32_16x16x32_bf16 v[4:7], v[166:169], v[218:221], v[4:7]
	v_mfma_f32_16x16x32_bf16 v[0:3], v[174:177], v[218:221], v[0:3]
	s_setprio 0
	s_barrier
	s_add_i32 s85, s85, 2
	s_add_u32 s60, s60, 0x100
	s_addc_u32 s61, s61, 0
	s_add_u32 s16, s16, 0x100
	s_addc_u32 s17, s17, 0
	s_cmp_gt_u32 s85, 13
	s_cbranch_scc0 .LBB0_249
	s_and_b64 vcc, exec, s[40:41]
	s_cbranch_vccz .LBB0_252
	s_barrier

.LBB0_361:
	s_add_u32 vcc_lo, s16, 0x80
	s_addc_u32 vcc_hi, s17, 0
	s_add_u32 s16, s14, 0x100
	s_addc_u32 s17, s15, 0
	s_mov_b32 s14, 0
	s_add_i32 s24, s14, 2
	s_add_u32 s46, vcc_lo, 0x80
	s_addc_u32 s15, vcc_hi, 0
	s_add_i32 s18, 0, 0x10000
	s_cmp_eq_u32 s6, s14
	s_cselect_b32 s15, s1, s15
	s_cselect_b32 s14, s0, s46
	s_cselect_b32 s47, s13, s17
	s_cselect_b32 s46, s12, s16
	s_add_i32 s21, 0, 0x14000
	v_add_u32_e32 v140, s18, v223
	v_add_u32_e32 v156, s21, v223
	s_waitcnt lgkmcnt(0)
	ds_read_b128 v[128:131], v140
	ds_read_b128 v[132:135], v140 offset:1024
	ds_read_b128 v[136:139], v140 offset:2048
	ds_read_b128 v[140:143], v140 offset:3072
	ds_read_b128 v[144:147], v156
	ds_read_b128 v[148:151], v156 offset:1024
	ds_read_b128 v[152:155], v156 offset:2048
	ds_read_b128 v[156:159], v156 offset:3072
	v_lshl_add_u64 v[186:187], vcc, 0, v[196:197]
	s_add_i32 m0, s28, 0xc000
	ds_read_b128 v[160:163], v225
	ds_read_b128 v[164:167], v225 offset:1024
	ds_read_b128 v[168:171], v225 offset:2048
	ds_read_b128 v[172:175], v225 offset:3072
	ds_read_b128 v[176:179], v225 offset:4096
	ds_read_b128 v[180:183], v225 offset:5120
	ds_read_b128 v[200:203], v225 offset:6144
	ds_read_b128 v[204:207], v225 offset:7168
	global_load_lds_dwordx4 v[186:187], off
	v_lshl_add_u64 v[186:187], vcc, 0, v[198:199]
	s_add_i32 m0, s28, 0xe000
	s_nop 0
	global_load_lds_dwordx4 v[186:187], off
	s_waitcnt vmcnt(8)
	s_waitcnt lgkmcnt(0)
	s_barrier
	s_setprio 1
	v_mfma_f32_16x16x32_bf16 v[124:127], v[128:131], v[160:163], 0
	v_mfma_f32_16x16x32_bf16 v[120:123], v[136:139], v[160:163], 0
	v_mfma_f32_16x16x32_bf16 v[108:111], v[128:131], v[168:171], 0
	v_mfma_f32_16x16x32_bf16 v[104:107], v[136:139], v[168:171], 0
	v_mfma_f32_16x16x32_bf16 v[92:95], v[128:131], v[176:179], 0
	v_mfma_f32_16x16x32_bf16 v[88:91], v[136:139], v[176:179], 0
	v_mfma_f32_16x16x32_bf16 v[76:79], v[128:131], v[200:203], 0
	v_mfma_f32_16x16x32_bf16 v[72:75], v[136:139], v[200:203], 0
	v_mfma_f32_16x16x32_bf16 v[124:127], v[132:135], v[164:167], v[124:127]
	v_mfma_f32_16x16x32_bf16 v[120:123], v[140:143], v[164:167], v[120:123]
	v_mfma_f32_16x16x32_bf16 v[108:111], v[132:135], v[172:175], v[108:111]
	v_mfma_f32_16x16x32_bf16 v[104:107], v[140:143], v[172:175], v[104:107]
	v_mfma_f32_16x16x32_bf16 v[92:95], v[132:135], v[180:183], v[92:95]
	v_mfma_f32_16x16x32_bf16 v[88:91], v[140:143], v[180:183], v[88:91]
	v_mfma_f32_16x16x32_bf16 v[76:79], v[132:135], v[204:207], v[76:79]
	v_mfma_f32_16x16x32_bf16 v[72:75], v[140:143], v[204:207], v[72:75]
	v_mfma_f32_16x16x32_bf16 v[116:119], v[144:147], v[160:163], 0
	v_mfma_f32_16x16x32_bf16 v[112:115], v[152:155], v[160:163], 0
	v_mfma_f32_16x16x32_bf16 v[100:103], v[144:147], v[168:171], 0
	v_mfma_f32_16x16x32_bf16 v[96:99], v[152:155], v[168:171], 0
	v_mfma_f32_16x16x32_bf16 v[84:87], v[144:147], v[176:179], 0
	v_mfma_f32_16x16x32_bf16 v[80:83], v[152:155], v[176:179], 0
	v_mfma_f32_16x16x32_bf16 v[68:71], v[144:147], v[200:203], 0
	v_mfma_f32_16x16x32_bf16 v[64:67], v[152:155], v[200:203], 0
	v_mfma_f32_16x16x32_bf16 v[116:119], v[148:151], v[164:167], v[116:119]
	v_mfma_f32_16x16x32_bf16 v[112:115], v[156:159], v[164:167], v[112:115]
	v_mfma_f32_16x16x32_bf16 v[100:103], v[148:151], v[172:175], v[100:103]
	v_mfma_f32_16x16x32_bf16 v[96:99], v[156:159], v[172:175], v[96:99]
	v_mfma_f32_16x16x32_bf16 v[84:87], v[148:151], v[180:183], v[84:87]
	v_mfma_f32_16x16x32_bf16 v[80:83], v[156:159], v[180:183], v[80:83]
	v_mfma_f32_16x16x32_bf16 v[68:71], v[148:151], v[204:207], v[68:71]
	v_mfma_f32_16x16x32_bf16 v[64:67], v[156:159], v[204:207], v[64:67]
	s_setprio 0
	s_barrier
	s_add_i32 s18, s18, s27
	v_lshl_add_u64 v[186:187], s[46:47], 0, v[184:185]
	s_mov_b32 m0, s18
	ds_read_b128 v[160:163], v225 offset:16384
	ds_read_b128 v[164:167], v225 offset:17408
	ds_read_b128 v[168:171], v225 offset:18432
	ds_read_b128 v[172:175], v225 offset:19456
	ds_read_b128 v[176:179], v225 offset:20480
	ds_read_b128 v[180:183], v225 offset:21504
	ds_read_b128 v[200:203], v225 offset:22528
	ds_read_b128 v[204:207], v225 offset:23552
	global_load_lds_dwordx4 v[186:187], off
	s_add_i32 m0, s18, 0x2000
	s_add_u32 s46, s46, s44
	v_lshl_add_u64 v[188:189], v[186:187], 0, s[70:71]
	s_addc_u32 s47, s47, 0
	s_add_i32 s18, s21, s27
	global_load_lds_dwordx4 v[188:189], off
	v_lshl_add_u64 v[208:209], s[46:47], 0, v[184:185]
	s_mov_b32 m0, s18
	v_lshl_add_u64 v[210:211], v[208:209], 0, s[70:71]
	global_load_lds_dwordx4 v[208:209], off
	s_add_i32 m0, s18, 0x2000
	v_lshl_add_u64 v[212:213], s[14:15], 0, v[194:195]
	global_load_lds_dwordx4 v[210:211], off
	s_mov_b32 m0, s28
	v_lshl_add_u64 v[214:215], v[212:213], 0, s[70:71]
	global_load_lds_dwordx4 v[212:213], off
	s_mov_b32 m0, s29
	s_nop 0
	global_load_lds_dwordx4 v[214:215], off
	s_waitcnt vmcnt(8)
	s_waitcnt lgkmcnt(0)
	s_barrier
	s_setprio 1
	v_mfma_f32_16x16x32_bf16 v[60:63], v[128:131], v[160:163], 0
	v_mfma_f32_16x16x32_bf16 v[56:59], v[136:139], v[160:163], 0
	v_mfma_f32_16x16x32_bf16 v[44:47], v[128:131], v[168:171], 0
	v_mfma_f32_16x16x32_bf16 v[40:43], v[136:139], v[168:171], 0
	v_mfma_f32_16x16x32_bf16 v[28:31], v[128:131], v[176:179], 0
	v_mfma_f32_16x16x32_bf16 v[24:27], v[136:139], v[176:179], 0
	v_mfma_f32_16x16x32_bf16 v[12:15], v[128:131], v[200:203], 0
	v_mfma_f32_16x16x32_bf16 v[8:11], v[136:139], v[200:203], 0
	v_mfma_f32_16x16x32_bf16 v[60:63], v[132:135], v[164:167], v[60:63]
	v_mfma_f32_16x16x32_bf16 v[56:59], v[140:143], v[164:167], v[56:59]
	v_mfma_f32_16x16x32_bf16 v[44:47], v[132:135], v[172:175], v[44:47]
	v_mfma_f32_16x16x32_bf16 v[40:43], v[140:143], v[172:175], v[40:43]
	v_mfma_f32_16x16x32_bf16 v[28:31], v[132:135], v[180:183], v[28:31]
	v_mfma_f32_16x16x32_bf16 v[24:27], v[140:143], v[180:183], v[24:27]
	v_mfma_f32_16x16x32_bf16 v[12:15], v[132:135], v[204:207], v[12:15]
	v_mfma_f32_16x16x32_bf16 v[8:11], v[140:143], v[204:207], v[8:11]
	v_mfma_f32_16x16x32_bf16 v[52:55], v[144:147], v[160:163], 0
	v_mfma_f32_16x16x32_bf16 v[48:51], v[152:155], v[160:163], 0
	v_mfma_f32_16x16x32_bf16 v[36:39], v[144:147], v[168:171], 0
	v_mfma_f32_16x16x32_bf16 v[32:35], v[152:155], v[168:171], 0
	v_mfma_f32_16x16x32_bf16 v[20:23], v[144:147], v[176:179], 0
	v_mfma_f32_16x16x32_bf16 v[16:19], v[152:155], v[176:179], 0
	v_mfma_f32_16x16x32_bf16 v[4:7], v[144:147], v[200:203], 0
	v_mfma_f32_16x16x32_bf16 v[0:3], v[152:155], v[200:203], 0
	v_mfma_f32_16x16x32_bf16 v[52:55], v[148:151], v[164:167], v[52:55]
	v_mfma_f32_16x16x32_bf16 v[48:51], v[156:159], v[164:167], v[48:51]
	v_mfma_f32_16x16x32_bf16 v[36:39], v[148:151], v[172:175], v[36:39]
	v_mfma_f32_16x16x32_bf16 v[32:35], v[156:159], v[172:175], v[32:35]
	v_mfma_f32_16x16x32_bf16 v[20:23], v[148:151], v[180:183], v[20:23]
	v_mfma_f32_16x16x32_bf16 v[16:19], v[156:159], v[180:183], v[16:19]
	v_mfma_f32_16x16x32_bf16 v[4:7], v[148:151], v[204:207], v[4:7]
	v_mfma_f32_16x16x32_bf16 v[0:3], v[156:159], v[204:207], v[0:3]
	s_setprio 0
	s_barrier
	s_add_i32 s18, 0, 0x18000
	s_add_i32 s21, 0, 0x1c000
	v_add_u32_e32 v140, s18, v223
	v_add_u32_e32 v156, s21, v223
	ds_read_b128 v[128:131], v140
	ds_read_b128 v[132:135], v140 offset:1024
	ds_read_b128 v[136:139], v140 offset:2048
	ds_read_b128 v[140:143], v140 offset:3072
	ds_read_b128 v[144:147], v156
	ds_read_b128 v[148:151], v156 offset:1024
	ds_read_b128 v[152:155], v156 offset:2048
	ds_read_b128 v[156:159], v156 offset:3072
	s_add_u32 s14, s14, s44
	s_addc_u32 s15, s15, 0
	s_mov_b32 m0, s30
	v_lshl_add_u64 v[216:217], s[14:15], 0, v[194:195]
	ds_read_b128 v[160:163], v225 offset:32768
	ds_read_b128 v[164:167], v225 offset:33792
	ds_read_b128 v[168:171], v225 offset:34816
	ds_read_b128 v[172:175], v225 offset:35840
	ds_read_b128 v[176:179], v225 offset:36864
	ds_read_b128 v[180:183], v225 offset:37888
	ds_read_b128 v[200:203], v225 offset:38912
	ds_read_b128 v[204:207], v225 offset:39936
	global_load_lds_dwordx4 v[216:217], off
	v_lshl_add_u64 v[216:217], v[216:217], 0, s[70:71]
	s_mov_b32 m0, s31
	s_nop 0
	global_load_lds_dwordx4 v[216:217], off
	s_waitcnt vmcnt(8)
	s_waitcnt lgkmcnt(0)
	s_barrier
	s_setprio 1
	v_mfma_f32_16x16x32_bf16 v[124:127], v[128:131], v[160:163], v[124:127]
	v_mfma_f32_16x16x32_bf16 v[120:123], v[136:139], v[160:163], v[120:123]
	v_mfma_f32_16x16x32_bf16 v[108:111], v[128:131], v[168:171], v[108:111]
	v_mfma_f32_16x16x32_bf16 v[104:107], v[136:139], v[168:171], v[104:107]
	v_mfma_f32_16x16x32_bf16 v[92:95], v[128:131], v[176:179], v[92:95]
	v_mfma_f32_16x16x32_bf16 v[88:91], v[136:139], v[176:179], v[88:91]
	v_mfma_f32_16x16x32_bf16 v[76:79], v[128:131], v[200:203], v[76:79]
	v_mfma_f32_16x16x32_bf16 v[72:75], v[136:139], v[200:203], v[72:75]
	v_mfma_f32_16x16x32_bf16 v[124:127], v[132:135], v[164:167], v[124:127]
	v_mfma_f32_16x16x32_bf16 v[120:123], v[140:143], v[164:167], v[120:123]
	v_mfma_f32_16x16x32_bf16 v[108:111], v[132:135], v[172:175], v[108:111]
	v_mfma_f32_16x16x32_bf16 v[104:107], v[140:143], v[172:175], v[104:107]
	v_mfma_f32_16x16x32_bf16 v[92:95], v[132:135], v[180:183], v[92:95]
	v_mfma_f32_16x16x32_bf16 v[88:91], v[140:143], v[180:183], v[88:91]
	v_mfma_f32_16x16x32_bf16 v[76:79], v[132:135], v[204:207], v[76:79]
	v_mfma_f32_16x16x32_bf16 v[72:75], v[140:143], v[204:207], v[72:75]
	v_mfma_f32_16x16x32_bf16 v[116:119], v[144:147], v[160:163], v[116:119]
	v_mfma_f32_16x16x32_bf16 v[112:115], v[152:155], v[160:163], v[112:115]
	v_mfma_f32_16x16x32_bf16 v[100:103], v[144:147], v[168:171], v[100:103]
	v_mfma_f32_16x16x32_bf16 v[96:99], v[152:155], v[168:171], v[96:99]
	v_mfma_f32_16x16x32_bf16 v[84:87], v[144:147], v[176:179], v[84:87]
	v_mfma_f32_16x16x32_bf16 v[80:83], v[152:155], v[176:179], v[80:83]
	v_mfma_f32_16x16x32_bf16 v[68:71], v[144:147], v[200:203], v[68:71]
	v_mfma_f32_16x16x32_bf16 v[64:67], v[152:155], v[200:203], v[64:67]
	v_mfma_f32_16x16x32_bf16 v[116:119], v[148:151], v[164:167], v[116:119]
	v_mfma_f32_16x16x32_bf16 v[112:115], v[156:159], v[164:167], v[112:115]
	v_mfma_f32_16x16x32_bf16 v[100:103], v[148:151], v[172:175], v[100:103]
	v_mfma_f32_16x16x32_bf16 v[96:99], v[156:159], v[172:175], v[96:99]
	v_mfma_f32_16x16x32_bf16 v[84:87], v[148:151], v[180:183], v[84:87]
	v_mfma_f32_16x16x32_bf16 v[80:83], v[156:159], v[180:183], v[80:83]
	v_mfma_f32_16x16x32_bf16 v[68:71], v[148:151], v[204:207], v[68:71]
	v_mfma_f32_16x16x32_bf16 v[64:67], v[156:159], v[204:207], v[64:67]
	s_setprio 0
	s_barrier
	s_add_i32 s14, s18, s27
	v_lshl_add_u64 v[186:187], v[186:187], 0, s[56:57]
	s_mov_b32 m0, s14
	ds_read_b128 v[160:163], v225 offset:49152
	ds_read_b128 v[164:167], v225 offset:50176
	ds_read_b128 v[168:171], v225 offset:51200
	ds_read_b128 v[172:175], v225 offset:52224
	ds_read_b128 v[176:179], v225 offset:53248
	ds_read_b128 v[180:183], v225 offset:54272
	ds_read_b128 v[200:203], v225 offset:55296
	ds_read_b128 v[204:207], v225 offset:56320
	global_load_lds_dwordx4 v[186:187], off
	v_lshl_add_u64 v[186:187], v[188:189], 0, s[56:57]
	s_add_i32 m0, s14, 0x2000
	s_add_i32 s14, s21, s27
	global_load_lds_dwordx4 v[186:187], off
	v_lshl_add_u64 v[186:187], v[208:209], 0, s[56:57]
	s_mov_b32 m0, s14
	s_nop 0
	global_load_lds_dwordx4 v[186:187], off
	v_lshl_add_u64 v[186:187], v[210:211], 0, s[56:57]
	s_add_i32 m0, s14, 0x2000
	s_nop 0
	global_load_lds_dwordx4 v[186:187], off
	v_lshl_add_u64 v[186:187], v[212:213], 0, s[56:57]
	s_mov_b32 m0, s19
	s_nop 0
	global_load_lds_dwordx4 v[186:187], off
	v_lshl_add_u64 v[186:187], v[214:215], 0, s[56:57]
	s_mov_b32 m0, s20
	s_nop 0
	global_load_lds_dwordx4 v[186:187], off
	s_waitcnt vmcnt(8)
	s_waitcnt lgkmcnt(0)
	s_barrier
	s_setprio 1
	v_mfma_f32_16x16x32_bf16 v[60:63], v[128:131], v[160:163], v[60:63]
	v_mfma_f32_16x16x32_bf16 v[56:59], v[136:139], v[160:163], v[56:59]
	v_mfma_f32_16x16x32_bf16 v[44:47], v[128:131], v[168:171], v[44:47]
	v_mfma_f32_16x16x32_bf16 v[40:43], v[136:139], v[168:171], v[40:43]
	v_mfma_f32_16x16x32_bf16 v[28:31], v[128:131], v[176:179], v[28:31]
	v_mfma_f32_16x16x32_bf16 v[24:27], v[136:139], v[176:179], v[24:27]
	v_mfma_f32_16x16x32_bf16 v[12:15], v[128:131], v[200:203], v[12:15]
	v_mfma_f32_16x16x32_bf16 v[8:11], v[136:139], v[200:203], v[8:11]
	v_mfma_f32_16x16x32_bf16 v[60:63], v[132:135], v[164:167], v[60:63]
	v_mfma_f32_16x16x32_bf16 v[56:59], v[140:143], v[164:167], v[56:59]
	v_mfma_f32_16x16x32_bf16 v[44:47], v[132:135], v[172:175], v[44:47]
	v_mfma_f32_16x16x32_bf16 v[40:43], v[140:143], v[172:175], v[40:43]
	v_mfma_f32_16x16x32_bf16 v[28:31], v[132:135], v[180:183], v[28:31]
	v_mfma_f32_16x16x32_bf16 v[24:27], v[140:143], v[180:183], v[24:27]
	v_mfma_f32_16x16x32_bf16 v[12:15], v[132:135], v[204:207], v[12:15]
	v_mfma_f32_16x16x32_bf16 v[8:11], v[140:143], v[204:207], v[8:11]
	v_mfma_f32_16x16x32_bf16 v[52:55], v[144:147], v[160:163], v[52:55]
	v_mfma_f32_16x16x32_bf16 v[48:51], v[152:155], v[160:163], v[48:51]
	v_mfma_f32_16x16x32_bf16 v[36:39], v[144:147], v[168:171], v[36:39]
	v_mfma_f32_16x16x32_bf16 v[32:35], v[152:155], v[168:171], v[32:35]
	v_mfma_f32_16x16x32_bf16 v[20:23], v[144:147], v[176:179], v[20:23]
	v_mfma_f32_16x16x32_bf16 v[16:19], v[152:155], v[176:179], v[16:19]
	v_mfma_f32_16x16x32_bf16 v[4:7], v[144:147], v[200:203], v[4:7]
	v_mfma_f32_16x16x32_bf16 v[0:3], v[152:155], v[200:203], v[0:3]
	v_mfma_f32_16x16x32_bf16 v[52:55], v[148:151], v[164:167], v[52:55]
	v_mfma_f32_16x16x32_bf16 v[48:51], v[156:159], v[164:167], v[48:51]
	v_mfma_f32_16x16x32_bf16 v[36:39], v[148:151], v[172:175], v[36:39]
	v_mfma_f32_16x16x32_bf16 v[32:35], v[156:159], v[172:175], v[32:35]
	v_mfma_f32_16x16x32_bf16 v[20:23], v[148:151], v[180:183], v[20:23]
	v_mfma_f32_16x16x32_bf16 v[16:19], v[156:159], v[180:183], v[16:19]
	v_mfma_f32_16x16x32_bf16 v[4:7], v[148:151], v[204:207], v[4:7]
	v_mfma_f32_16x16x32_bf16 v[0:3], v[156:159], v[204:207], v[0:3]
	s_setprio 0
	s_barrier
	s_add_u32 vcc_lo, vcc_lo, 0x100
	s_addc_u32 vcc_hi, vcc_hi, 0
	s_add_u32 s16, s16, 0x100
	s_addc_u32 s17, s17, 0
	s_cmp_ge_u32 s24, s84
	s_mov_b32 s14, s24
.LBB0_362:
	s_add_i32 s24, s14, 2
	s_add_u32 s46, vcc_lo, 0x80
	s_addc_u32 s15, vcc_hi, 0
	s_add_i32 s18, 0, 0x10000
	s_cmp_eq_u32 s6, s14
	s_cselect_b32 s15, s1, s15
	s_cselect_b32 s14, s0, s46
	s_cselect_b32 s47, s13, s17
	s_cselect_b32 s46, s12, s16
	s_add_i32 s21, 0, 0x14000
	v_add_u32_e32 v140, s18, v223
	v_add_u32_e32 v156, s21, v223
	s_waitcnt lgkmcnt(0)
	ds_read_b128 v[128:131], v140
	ds_read_b128 v[132:135], v140 offset:1024
	ds_read_b128 v[136:139], v140 offset:2048
	ds_read_b128 v[140:143], v140 offset:3072
	ds_read_b128 v[144:147], v156
	ds_read_b128 v[148:151], v156 offset:1024
	ds_read_b128 v[152:155], v156 offset:2048
	ds_read_b128 v[156:159], v156 offset:3072
	v_lshl_add_u64 v[186:187], vcc, 0, v[196:197]
	s_add_i32 m0, s28, 0xc000
	ds_read_b128 v[160:163], v225
	ds_read_b128 v[164:167], v225 offset:1024
	ds_read_b128 v[168:171], v225 offset:2048
	ds_read_b128 v[172:175], v225 offset:3072
	ds_read_b128 v[176:179], v225 offset:4096
	ds_read_b128 v[180:183], v225 offset:5120
	ds_read_b128 v[200:203], v225 offset:6144
	ds_read_b128 v[204:207], v225 offset:7168
	global_load_lds_dwordx4 v[186:187], off
	v_lshl_add_u64 v[186:187], vcc, 0, v[198:199]
	s_add_i32 m0, s28, 0xe000
	s_nop 0
	global_load_lds_dwordx4 v[186:187], off
	s_waitcnt vmcnt(8)
	s_waitcnt lgkmcnt(0)
	s_barrier
	s_setprio 1
	v_mfma_f32_16x16x32_bf16 v[124:127], v[128:131], v[160:163], v[124:127]
	v_mfma_f32_16x16x32_bf16 v[120:123], v[136:139], v[160:163], v[120:123]
	v_mfma_f32_16x16x32_bf16 v[108:111], v[128:131], v[168:171], v[108:111]
	v_mfma_f32_16x16x32_bf16 v[104:107], v[136:139], v[168:171], v[104:107]
	v_mfma_f32_16x16x32_bf16 v[92:95], v[128:131], v[176:179], v[92:95]
	v_mfma_f32_16x16x32_bf16 v[88:91], v[136:139], v[176:179], v[88:91]
	v_mfma_f32_16x16x32_bf16 v[76:79], v[128:131], v[200:203], v[76:79]
	v_mfma_f32_16x16x32_bf16 v[72:75], v[136:139], v[200:203], v[72:75]
	v_mfma_f32_16x16x32_bf16 v[124:127], v[132:135], v[164:167], v[124:127]
	v_mfma_f32_16x16x32_bf16 v[120:123], v[140:143], v[164:167], v[120:123]
	v_mfma_f32_16x16x32_bf16 v[108:111], v[132:135], v[172:175], v[108:111]
	v_mfma_f32_16x16x32_bf16 v[104:107], v[140:143], v[172:175], v[104:107]
	v_mfma_f32_16x16x32_bf16 v[92:95], v[132:135], v[180:183], v[92:95]
	v_mfma_f32_16x16x32_bf16 v[88:91], v[140:143], v[180:183], v[88:91]
	v_mfma_f32_16x16x32_bf16 v[76:79], v[132:135], v[204:207], v[76:79]
	v_mfma_f32_16x16x32_bf16 v[72:75], v[140:143], v[204:207], v[72:75]
	v_mfma_f32_16x16x32_bf16 v[116:119], v[144:147], v[160:163], v[116:119]
	v_mfma_f32_16x16x32_bf16 v[112:115], v[152:155], v[160:163], v[112:115]
	v_mfma_f32_16x16x32_bf16 v[100:103], v[144:147], v[168:171], v[100:103]
	v_mfma_f32_16x16x32_bf16 v[96:99], v[152:155], v[168:171], v[96:99]
	v_mfma_f32_16x16x32_bf16 v[84:87], v[144:147], v[176:179], v[84:87]
	v_mfma_f32_16x16x32_bf16 v[80:83], v[152:155], v[176:179], v[80:83]
	v_mfma_f32_16x16x32_bf16 v[68:71], v[144:147], v[200:203], v[68:71]
	v_mfma_f32_16x16x32_bf16 v[64:67], v[152:155], v[200:203], v[64:67]
	v_mfma_f32_16x16x32_bf16 v[116:119], v[148:151], v[164:167], v[116:119]
	v_mfma_f32_16x16x32_bf16 v[112:115], v[156:159], v[164:167], v[112:115]
	v_mfma_f32_16x16x32_bf16 v[100:103], v[148:151], v[172:175], v[100:103]
	v_mfma_f32_16x16x32_bf16 v[96:99], v[156:159], v[172:175], v[96:99]
	v_mfma_f32_16x16x32_bf16 v[84:87], v[148:151], v[180:183], v[84:87]
	v_mfma_f32_16x16x32_bf16 v[80:83], v[156:159], v[180:183], v[80:83]
	v_mfma_f32_16x16x32_bf16 v[68:71], v[148:151], v[204:207], v[68:71]
	v_mfma_f32_16x16x32_bf16 v[64:67], v[156:159], v[204:207], v[64:67]
	s_setprio 0
	s_barrier
	s_add_i32 s18, s18, s27
	v_lshl_add_u64 v[186:187], s[46:47], 0, v[184:185]
	s_mov_b32 m0, s18
	ds_read_b128 v[160:163], v225 offset:16384
	ds_read_b128 v[164:167], v225 offset:17408
	ds_read_b128 v[168:171], v225 offset:18432
	ds_read_b128 v[172:175], v225 offset:19456
	ds_read_b128 v[176:179], v225 offset:20480
	ds_read_b128 v[180:183], v225 offset:21504
	ds_read_b128 v[200:203], v225 offset:22528
	ds_read_b128 v[204:207], v225 offset:23552
	global_load_lds_dwordx4 v[186:187], off
	s_add_i32 m0, s18, 0x2000
	s_add_u32 s46, s46, s44
	v_lshl_add_u64 v[188:189], v[186:187], 0, s[70:71]
	s_addc_u32 s47, s47, 0
	s_add_i32 s18, s21, s27
	global_load_lds_dwordx4 v[188:189], off
	v_lshl_add_u64 v[208:209], s[46:47], 0, v[184:185]
	s_mov_b32 m0, s18
	v_lshl_add_u64 v[210:211], v[208:209], 0, s[70:71]
	global_load_lds_dwordx4 v[208:209], off
	s_add_i32 m0, s18, 0x2000
	v_lshl_add_u64 v[212:213], s[14:15], 0, v[194:195]
	global_load_lds_dwordx4 v[210:211], off
	s_mov_b32 m0, s28
	v_lshl_add_u64 v[214:215], v[212:213], 0, s[70:71]
	global_load_lds_dwordx4 v[212:213], off
	s_mov_b32 m0, s29
	s_nop 0
	global_load_lds_dwordx4 v[214:215], off
	s_waitcnt vmcnt(8)
	s_waitcnt lgkmcnt(0)
	s_barrier
	s_setprio 1
	v_mfma_f32_16x16x32_bf16 v[60:63], v[128:131], v[160:163], v[60:63]
	v_mfma_f32_16x16x32_bf16 v[56:59], v[136:139], v[160:163], v[56:59]
	v_mfma_f32_16x16x32_bf16 v[44:47], v[128:131], v[168:171], v[44:47]
	v_mfma_f32_16x16x32_bf16 v[40:43], v[136:139], v[168:171], v[40:43]
	v_mfma_f32_16x16x32_bf16 v[28:31], v[128:131], v[176:179], v[28:31]
	v_mfma_f32_16x16x32_bf16 v[24:27], v[136:139], v[176:179], v[24:27]
	v_mfma_f32_16x16x32_bf16 v[12:15], v[128:131], v[200:203], v[12:15]
	v_mfma_f32_16x16x32_bf16 v[8:11], v[136:139], v[200:203], v[8:11]
	v_mfma_f32_16x16x32_bf16 v[60:63], v[132:135], v[164:167], v[60:63]
	v_mfma_f32_16x16x32_bf16 v[56:59], v[140:143], v[164:167], v[56:59]
	v_mfma_f32_16x16x32_bf16 v[44:47], v[132:135], v[172:175], v[44:47]
	v_mfma_f32_16x16x32_bf16 v[40:43], v[140:143], v[172:175], v[40:43]
	v_mfma_f32_16x16x32_bf16 v[28:31], v[132:135], v[180:183], v[28:31]
	v_mfma_f32_16x16x32_bf16 v[24:27], v[140:143], v[180:183], v[24:27]
	v_mfma_f32_16x16x32_bf16 v[12:15], v[132:135], v[204:207], v[12:15]
	v_mfma_f32_16x16x32_bf16 v[8:11], v[140:143], v[204:207], v[8:11]
	v_mfma_f32_16x16x32_bf16 v[52:55], v[144:147], v[160:163], v[52:55]
	v_mfma_f32_16x16x32_bf16 v[48:51], v[152:155], v[160:163], v[48:51]
	v_mfma_f32_16x16x32_bf16 v[36:39], v[144:147], v[168:171], v[36:39]
	v_mfma_f32_16x16x32_bf16 v[32:35], v[152:155], v[168:171], v[32:35]
	v_mfma_f32_16x16x32_bf16 v[20:23], v[144:147], v[176:179], v[20:23]
	v_mfma_f32_16x16x32_bf16 v[16:19], v[152:155], v[176:179], v[16:19]
	v_mfma_f32_16x16x32_bf16 v[4:7], v[144:147], v[200:203], v[4:7]
	v_mfma_f32_16x16x32_bf16 v[0:3], v[152:155], v[200:203], v[0:3]
	v_mfma_f32_16x16x32_bf16 v[52:55], v[148:151], v[164:167], v[52:55]
	v_mfma_f32_16x16x32_bf16 v[48:51], v[156:159], v[164:167], v[48:51]
	v_mfma_f32_16x16x32_bf16 v[36:39], v[148:151], v[172:175], v[36:39]
	v_mfma_f32_16x16x32_bf16 v[32:35], v[156:159], v[172:175], v[32:35]
	v_mfma_f32_16x16x32_bf16 v[20:23], v[148:151], v[180:183], v[20:23]
	v_mfma_f32_16x16x32_bf16 v[16:19], v[156:159], v[180:183], v[16:19]
	v_mfma_f32_16x16x32_bf16 v[4:7], v[148:151], v[204:207], v[4:7]
	v_mfma_f32_16x16x32_bf16 v[0:3], v[156:159], v[204:207], v[0:3]
	s_setprio 0
	s_barrier
	s_add_i32 s18, 0, 0x18000
	s_add_i32 s21, 0, 0x1c000
	v_add_u32_e32 v140, s18, v223
	v_add_u32_e32 v156, s21, v223
	ds_read_b128 v[128:131], v140
	ds_read_b128 v[132:135], v140 offset:1024
	ds_read_b128 v[136:139], v140 offset:2048
	ds_read_b128 v[140:143], v140 offset:3072
	ds_read_b128 v[144:147], v156
	ds_read_b128 v[148:151], v156 offset:1024
	ds_read_b128 v[152:155], v156 offset:2048
	ds_read_b128 v[156:159], v156 offset:3072
	s_add_u32 s14, s14, s44
	s_addc_u32 s15, s15, 0
	s_mov_b32 m0, s30
	v_lshl_add_u64 v[216:217], s[14:15], 0, v[194:195]
	ds_read_b128 v[160:163], v225 offset:32768
	ds_read_b128 v[164:167], v225 offset:33792
	ds_read_b128 v[168:171], v225 offset:34816
	ds_read_b128 v[172:175], v225 offset:35840
	ds_read_b128 v[176:179], v225 offset:36864
	ds_read_b128 v[180:183], v225 offset:37888
	ds_read_b128 v[200:203], v225 offset:38912
	ds_read_b128 v[204:207], v225 offset:39936
	global_load_lds_dwordx4 v[216:217], off
	v_lshl_add_u64 v[216:217], v[216:217], 0, s[70:71]
	s_mov_b32 m0, s31
	s_nop 0
	global_load_lds_dwordx4 v[216:217], off
	s_waitcnt vmcnt(8)
	s_waitcnt lgkmcnt(0)
	s_barrier
	s_setprio 1
	v_mfma_f32_16x16x32_bf16 v[124:127], v[128:131], v[160:163], v[124:127]
	v_mfma_f32_16x16x32_bf16 v[120:123], v[136:139], v[160:163], v[120:123]
	v_mfma_f32_16x16x32_bf16 v[108:111], v[128:131], v[168:171], v[108:111]
	v_mfma_f32_16x16x32_bf16 v[104:107], v[136:139], v[168:171], v[104:107]
	v_mfma_f32_16x16x32_bf16 v[92:95], v[128:131], v[176:179], v[92:95]
	v_mfma_f32_16x16x32_bf16 v[88:91], v[136:139], v[176:179], v[88:91]
	v_mfma_f32_16x16x32_bf16 v[76:79], v[128:131], v[200:203], v[76:79]
	v_mfma_f32_16x16x32_bf16 v[72:75], v[136:139], v[200:203], v[72:75]
	v_mfma_f32_16x16x32_bf16 v[124:127], v[132:135], v[164:167], v[124:127]
	v_mfma_f32_16x16x32_bf16 v[120:123], v[140:143], v[164:167], v[120:123]
	v_mfma_f32_16x16x32_bf16 v[108:111], v[132:135], v[172:175], v[108:111]
	v_mfma_f32_16x16x32_bf16 v[104:107], v[140:143], v[172:175], v[104:107]
	v_mfma_f32_16x16x32_bf16 v[92:95], v[132:135], v[180:183], v[92:95]
	v_mfma_f32_16x16x32_bf16 v[88:91], v[140:143], v[180:183], v[88:91]
	v_mfma_f32_16x16x32_bf16 v[76:79], v[132:135], v[204:207], v[76:79]
	v_mfma_f32_16x16x32_bf16 v[72:75], v[140:143], v[204:207], v[72:75]
	v_mfma_f32_16x16x32_bf16 v[116:119], v[144:147], v[160:163], v[116:119]
	v_mfma_f32_16x16x32_bf16 v[112:115], v[152:155], v[160:163], v[112:115]
	v_mfma_f32_16x16x32_bf16 v[100:103], v[144:147], v[168:171], v[100:103]
	v_mfma_f32_16x16x32_bf16 v[96:99], v[152:155], v[168:171], v[96:99]
	v_mfma_f32_16x16x32_bf16 v[84:87], v[144:147], v[176:179], v[84:87]
	v_mfma_f32_16x16x32_bf16 v[80:83], v[152:155], v[176:179], v[80:83]
	v_mfma_f32_16x16x32_bf16 v[68:71], v[144:147], v[200:203], v[68:71]
	v_mfma_f32_16x16x32_bf16 v[64:67], v[152:155], v[200:203], v[64:67]
	v_mfma_f32_16x16x32_bf16 v[116:119], v[148:151], v[164:167], v[116:119]
	v_mfma_f32_16x16x32_bf16 v[112:115], v[156:159], v[164:167], v[112:115]
	v_mfma_f32_16x16x32_bf16 v[100:103], v[148:151], v[172:175], v[100:103]
	v_mfma_f32_16x16x32_bf16 v[96:99], v[156:159], v[172:175], v[96:99]
	v_mfma_f32_16x16x32_bf16 v[84:87], v[148:151], v[180:183], v[84:87]
	v_mfma_f32_16x16x32_bf16 v[80:83], v[156:159], v[180:183], v[80:83]
	v_mfma_f32_16x16x32_bf16 v[68:71], v[148:151], v[204:207], v[68:71]
	v_mfma_f32_16x16x32_bf16 v[64:67], v[156:159], v[204:207], v[64:67]
	s_setprio 0
	s_barrier
	s_add_i32 s14, s18, s27
	v_lshl_add_u64 v[186:187], v[186:187], 0, s[56:57]
	s_mov_b32 m0, s14
	ds_read_b128 v[160:163], v225 offset:49152
	ds_read_b128 v[164:167], v225 offset:50176
	ds_read_b128 v[168:171], v225 offset:51200
	ds_read_b128 v[172:175], v225 offset:52224
	ds_read_b128 v[176:179], v225 offset:53248
	ds_read_b128 v[180:183], v225 offset:54272
	ds_read_b128 v[200:203], v225 offset:55296
	ds_read_b128 v[204:207], v225 offset:56320
	global_load_lds_dwordx4 v[186:187], off
	v_lshl_add_u64 v[186:187], v[188:189], 0, s[56:57]
	s_add_i32 m0, s14, 0x2000
	s_add_i32 s14, s21, s27
	global_load_lds_dwordx4 v[186:187], off
	v_lshl_add_u64 v[186:187], v[208:209], 0, s[56:57]
	s_mov_b32 m0, s14
	s_nop 0
	global_load_lds_dwordx4 v[186:187], off
	v_lshl_add_u64 v[186:187], v[210:211], 0, s[56:57]
	s_add_i32 m0, s14, 0x2000
	s_nop 0
	global_load_lds_dwordx4 v[186:187], off
	v_lshl_add_u64 v[186:187], v[212:213], 0, s[56:57]
	s_mov_b32 m0, s19
	s_nop 0
	global_load_lds_dwordx4 v[186:187], off
	v_lshl_add_u64 v[186:187], v[214:215], 0, s[56:57]
	s_mov_b32 m0, s20
	s_nop 0
	global_load_lds_dwordx4 v[186:187], off
	s_waitcnt vmcnt(8)
	s_waitcnt lgkmcnt(0)
	s_barrier
	s_setprio 1
	v_mfma_f32_16x16x32_bf16 v[60:63], v[128:131], v[160:163], v[60:63]
	v_mfma_f32_16x16x32_bf16 v[56:59], v[136:139], v[160:163], v[56:59]
	v_mfma_f32_16x16x32_bf16 v[44:47], v[128:131], v[168:171], v[44:47]
	v_mfma_f32_16x16x32_bf16 v[40:43], v[136:139], v[168:171], v[40:43]
	v_mfma_f32_16x16x32_bf16 v[28:31], v[128:131], v[176:179], v[28:31]
	v_mfma_f32_16x16x32_bf16 v[24:27], v[136:139], v[176:179], v[24:27]
	v_mfma_f32_16x16x32_bf16 v[12:15], v[128:131], v[200:203], v[12:15]
	v_mfma_f32_16x16x32_bf16 v[8:11], v[136:139], v[200:203], v[8:11]
	v_mfma_f32_16x16x32_bf16 v[60:63], v[132:135], v[164:167], v[60:63]
	v_mfma_f32_16x16x32_bf16 v[56:59], v[140:143], v[164:167], v[56:59]
	v_mfma_f32_16x16x32_bf16 v[44:47], v[132:135], v[172:175], v[44:47]
	v_mfma_f32_16x16x32_bf16 v[40:43], v[140:143], v[172:175], v[40:43]
	v_mfma_f32_16x16x32_bf16 v[28:31], v[132:135], v[180:183], v[28:31]
	v_mfma_f32_16x16x32_bf16 v[24:27], v[140:143], v[180:183], v[24:27]
	v_mfma_f32_16x16x32_bf16 v[12:15], v[132:135], v[204:207], v[12:15]
	v_mfma_f32_16x16x32_bf16 v[8:11], v[140:143], v[204:207], v[8:11]
	v_mfma_f32_16x16x32_bf16 v[52:55], v[144:147], v[160:163], v[52:55]
	v_mfma_f32_16x16x32_bf16 v[48:51], v[152:155], v[160:163], v[48:51]
	v_mfma_f32_16x16x32_bf16 v[36:39], v[144:147], v[168:171], v[36:39]
	v_mfma_f32_16x16x32_bf16 v[32:35], v[152:155], v[168:171], v[32:35]
	v_mfma_f32_16x16x32_bf16 v[20:23], v[144:147], v[176:179], v[20:23]
	v_mfma_f32_16x16x32_bf16 v[16:19], v[152:155], v[176:179], v[16:19]
	v_mfma_f32_16x16x32_bf16 v[4:7], v[144:147], v[200:203], v[4:7]
	v_mfma_f32_16x16x32_bf16 v[0:3], v[152:155], v[200:203], v[0:3]
	v_mfma_f32_16x16x32_bf16 v[52:55], v[148:151], v[164:167], v[52:55]
	v_mfma_f32_16x16x32_bf16 v[48:51], v[156:159], v[164:167], v[48:51]
	v_mfma_f32_16x16x32_bf16 v[36:39], v[148:151], v[172:175], v[36:39]
	v_mfma_f32_16x16x32_bf16 v[32:35], v[156:159], v[172:175], v[32:35]
	v_mfma_f32_16x16x32_bf16 v[20:23], v[148:151], v[180:183], v[20:23]
	v_mfma_f32_16x16x32_bf16 v[16:19], v[156:159], v[180:183], v[16:19]
	v_mfma_f32_16x16x32_bf16 v[4:7], v[148:151], v[204:207], v[4:7]
	v_mfma_f32_16x16x32_bf16 v[0:3], v[156:159], v[204:207], v[0:3]
	s_setprio 0
	s_barrier
	s_add_u32 vcc_lo, vcc_lo, 0x100
	s_addc_u32 vcc_hi, vcc_hi, 0
	s_add_u32 s16, s16, 0x100
	s_addc_u32 s17, s17, 0
	s_cmp_ge_u32 s24, s84
	s_mov_b32 s14, s24
	s_cbranch_scc0 .LBB0_362
	s_and_b64 vcc, exec, s[60:61]
	s_cbranch_vccz .LBB0_365
	s_barrier

.LBB0_421:
	s_add_u32 s44, s16, 0x80
	s_addc_u32 s45, s17, 0
	s_add_u32 s16, s14, 0x100
	s_addc_u32 s17, s15, 0
	s_mov_b32 s14, 0
	s_waitcnt lgkmcnt(0)
	s_add_i32 s23, s14, 2
	s_add_u32 s24, s44, 0x80
	s_addc_u32 s15, s45, 0
	s_add_i32 s49, 0, 0x10000
	s_cmp_eq_u32 s31, s14
	s_cselect_b32 s15, s1, s15
	s_cselect_b32 s14, s0, s24
	s_cselect_b32 s51, s43, s17
	s_cselect_b32 s50, s42, s16
	s_add_i32 s24, 0, 0x14000
	v_add_u32_e32 v108, s49, v249
	v_add_u32_e32 v140, s24, v249
	ds_read_b128 v[80:83], v108
	ds_read_b128 v[84:87], v108 offset:1024
	ds_read_b128 v[104:107], v108 offset:2048
	ds_read_b128 v[108:111], v108 offset:3072
	ds_read_b128 v[124:127], v140
	ds_read_b128 v[132:135], v140 offset:1024
	ds_read_b128 v[136:139], v140 offset:2048
	ds_read_b128 v[140:143], v140 offset:3072
	v_lshl_add_u64 v[208:209], s[44:45], 0, v[196:197]
	s_add_i32 m0, s20, 0xc000
	ds_read_b128 v[144:147], v251
	ds_read_b128 v[148:151], v251 offset:1024
	ds_read_b128 v[152:155], v251 offset:2048
	ds_read_b128 v[156:159], v251 offset:3072
	ds_read_b128 v[160:163], v251 offset:4096
	ds_read_b128 v[164:167], v251 offset:5120
	ds_read_b128 v[200:203], v251 offset:6144
	ds_read_b128 v[204:207], v251 offset:7168
	global_load_lds_dwordx4 v[208:209], off
	v_lshl_add_u64 v[208:209], s[44:45], 0, v[198:199]
	s_add_i32 m0, s20, 0xe000
	s_nop 0
	global_load_lds_dwordx4 v[208:209], off
	s_waitcnt vmcnt(8)
	s_waitcnt lgkmcnt(0)
	s_barrier
	s_setprio 1
	v_mfma_f32_16x16x32_bf16 v[180:183], v[80:83], v[144:147], 0
	v_mfma_f32_16x16x32_bf16 v[176:179], v[104:107], v[144:147], 0
	v_mfma_f32_16x16x32_bf16 v[128:131], v[80:83], v[152:155], 0
	v_mfma_f32_16x16x32_bf16 v[120:123], v[104:107], v[152:155], 0
	v_mfma_f32_16x16x32_bf16 v[100:103], v[80:83], v[160:163], 0
	v_mfma_f32_16x16x32_bf16 v[96:99], v[104:107], v[160:163], 0
	v_mfma_f32_16x16x32_bf16 v[76:79], v[80:83], v[200:203], 0
	v_mfma_f32_16x16x32_bf16 v[72:75], v[104:107], v[200:203], 0
	v_mfma_f32_16x16x32_bf16 v[180:183], v[84:87], v[148:151], v[180:183]
	v_mfma_f32_16x16x32_bf16 v[176:179], v[108:111], v[148:151], v[176:179]
	v_mfma_f32_16x16x32_bf16 v[128:131], v[84:87], v[156:159], v[128:131]
	v_mfma_f32_16x16x32_bf16 v[120:123], v[108:111], v[156:159], v[120:123]
	v_mfma_f32_16x16x32_bf16 v[100:103], v[84:87], v[164:167], v[100:103]
	v_mfma_f32_16x16x32_bf16 v[96:99], v[108:111], v[164:167], v[96:99]
	v_mfma_f32_16x16x32_bf16 v[76:79], v[84:87], v[204:207], v[76:79]
	v_mfma_f32_16x16x32_bf16 v[72:75], v[108:111], v[204:207], v[72:75]
	v_mfma_f32_16x16x32_bf16 v[172:175], v[124:127], v[144:147], 0
	v_mfma_f32_16x16x32_bf16 v[116:119], v[124:127], v[152:155], 0
	v_mfma_f32_16x16x32_bf16 v[112:115], v[136:139], v[152:155], 0
	v_mfma_f32_16x16x32_bf16 v[92:95], v[124:127], v[160:163], 0
	v_mfma_f32_16x16x32_bf16 v[88:91], v[136:139], v[160:163], 0
	v_mfma_f32_16x16x32_bf16 v[68:71], v[124:127], v[200:203], 0
	v_mfma_f32_16x16x32_bf16 v[64:67], v[136:139], v[200:203], 0
	v_mfma_f32_16x16x32_bf16 v[172:175], v[132:135], v[148:151], v[172:175]
	v_mfma_f32_16x16x32_bf16 v[144:147], v[136:139], v[144:147], 0
	v_mfma_f32_16x16x32_bf16 v[116:119], v[132:135], v[156:159], v[116:119]
	v_mfma_f32_16x16x32_bf16 v[112:115], v[140:143], v[156:159], v[112:115]
	v_mfma_f32_16x16x32_bf16 v[92:95], v[132:135], v[164:167], v[92:95]
	v_mfma_f32_16x16x32_bf16 v[88:91], v[140:143], v[164:167], v[88:91]
	v_mfma_f32_16x16x32_bf16 v[68:71], v[132:135], v[204:207], v[68:71]
	v_mfma_f32_16x16x32_bf16 v[64:67], v[140:143], v[204:207], v[64:67]
	v_mfma_f32_16x16x32_bf16 v[144:147], v[140:143], v[148:151], v[144:147]
	s_setprio 0
	s_barrier
	s_add_i32 s49, s49, s19
	v_lshl_add_u64 v[212:213], s[50:51], 0, v[184:185]
	s_mov_b32 m0, s49
	ds_read_b128 v[148:151], v251 offset:16384
	ds_read_b128 v[152:155], v251 offset:17408
	ds_read_b128 v[156:159], v251 offset:18432
	ds_read_b128 v[160:163], v251 offset:19456
	ds_read_b128 v[164:167], v251 offset:20480
	ds_read_b128 v[168:171], v251 offset:21504
	ds_read_b128 v[200:203], v251 offset:22528
	ds_read_b128 v[204:207], v251 offset:23552
	global_load_lds_dwordx4 v[212:213], off
	s_add_i32 m0, s49, 0x2000
	s_add_u32 s50, s50, s8
	v_lshl_add_u64 v[214:215], v[212:213], 0, s[70:71]
	s_addc_u32 s51, s51, 0
	s_add_i32 s24, s24, s19
	global_load_lds_dwordx4 v[214:215], off
	v_lshl_add_u64 v[216:217], s[50:51], 0, v[184:185]
	s_mov_b32 m0, s24
	v_lshl_add_u64 v[218:219], v[216:217], 0, s[70:71]
	global_load_lds_dwordx4 v[216:217], off
	s_add_i32 m0, s24, 0x2000
	v_lshl_add_u64 v[220:221], s[14:15], 0, v[194:195]
	global_load_lds_dwordx4 v[218:219], off
	s_mov_b32 m0, s20
	v_lshl_add_u64 v[222:223], v[220:221], 0, s[70:71]
	global_load_lds_dwordx4 v[220:221], off
	s_mov_b32 m0, s25
	s_nop 0
	global_load_lds_dwordx4 v[222:223], off
	s_waitcnt vmcnt(8)
	s_waitcnt lgkmcnt(0)
	s_barrier
	s_setprio 1
	v_mfma_f32_16x16x32_bf16 v[60:63], v[80:83], v[148:151], 0
	v_mfma_f32_16x16x32_bf16 v[56:59], v[104:107], v[148:151], 0
	v_mfma_f32_16x16x32_bf16 v[44:47], v[80:83], v[156:159], 0
	v_mfma_f32_16x16x32_bf16 v[40:43], v[104:107], v[156:159], 0
	v_mfma_f32_16x16x32_bf16 v[28:31], v[80:83], v[164:167], 0
	v_mfma_f32_16x16x32_bf16 v[24:27], v[104:107], v[164:167], 0
	v_mfma_f32_16x16x32_bf16 v[12:15], v[80:83], v[200:203], 0
	v_mfma_f32_16x16x32_bf16 v[8:11], v[104:107], v[200:203], 0
	v_mfma_f32_16x16x32_bf16 v[60:63], v[84:87], v[152:155], v[60:63]
	v_mfma_f32_16x16x32_bf16 v[56:59], v[108:111], v[152:155], v[56:59]
	v_mfma_f32_16x16x32_bf16 v[44:47], v[84:87], v[160:163], v[44:47]
	v_mfma_f32_16x16x32_bf16 v[40:43], v[108:111], v[160:163], v[40:43]
	v_mfma_f32_16x16x32_bf16 v[28:31], v[84:87], v[168:171], v[28:31]
	v_mfma_f32_16x16x32_bf16 v[24:27], v[108:111], v[168:171], v[24:27]
	v_mfma_f32_16x16x32_bf16 v[12:15], v[84:87], v[204:207], v[12:15]
	v_mfma_f32_16x16x32_bf16 v[8:11], v[108:111], v[204:207], v[8:11]
	v_mfma_f32_16x16x32_bf16 v[52:55], v[124:127], v[148:151], 0
	v_mfma_f32_16x16x32_bf16 v[48:51], v[136:139], v[148:151], 0
	v_mfma_f32_16x16x32_bf16 v[36:39], v[124:127], v[156:159], 0
	v_mfma_f32_16x16x32_bf16 v[32:35], v[136:139], v[156:159], 0
	v_mfma_f32_16x16x32_bf16 v[20:23], v[124:127], v[164:167], 0
	v_mfma_f32_16x16x32_bf16 v[16:19], v[136:139], v[164:167], 0
	v_mfma_f32_16x16x32_bf16 v[4:7], v[124:127], v[200:203], 0
	v_mfma_f32_16x16x32_bf16 v[0:3], v[136:139], v[200:203], 0
	v_mfma_f32_16x16x32_bf16 v[52:55], v[132:135], v[152:155], v[52:55]
	v_mfma_f32_16x16x32_bf16 v[48:51], v[140:143], v[152:155], v[48:51]
	v_mfma_f32_16x16x32_bf16 v[36:39], v[132:135], v[160:163], v[36:39]
	v_mfma_f32_16x16x32_bf16 v[32:35], v[140:143], v[160:163], v[32:35]
	v_mfma_f32_16x16x32_bf16 v[20:23], v[132:135], v[168:171], v[20:23]
	v_mfma_f32_16x16x32_bf16 v[16:19], v[140:143], v[168:171], v[16:19]
	v_mfma_f32_16x16x32_bf16 v[4:7], v[132:135], v[204:207], v[4:7]
	v_mfma_f32_16x16x32_bf16 v[0:3], v[140:143], v[204:207], v[0:3]
	s_setprio 0
	s_barrier
	s_add_i32 s24, 0, 0x18000
	s_add_i32 s49, 0, 0x1c000
	v_add_u32_e32 v108, s24, v249
	v_add_u32_e32 v140, s49, v249
	ds_read_b128 v[80:83], v108
	ds_read_b128 v[84:87], v108 offset:1024
	ds_read_b128 v[104:107], v108 offset:2048
	ds_read_b128 v[108:111], v108 offset:3072
	ds_read_b128 v[124:127], v140
	ds_read_b128 v[132:135], v140 offset:1024
	ds_read_b128 v[136:139], v140 offset:2048
	ds_read_b128 v[140:143], v140 offset:3072
	s_add_u32 s14, s14, s8
	s_addc_u32 s15, s15, 0
	s_mov_b32 m0, s26
	v_lshl_add_u64 v[168:169], s[14:15], 0, v[194:195]
	ds_read_b128 v[148:151], v251 offset:32768
	ds_read_b128 v[152:155], v251 offset:33792
	ds_read_b128 v[156:159], v251 offset:34816
	ds_read_b128 v[160:163], v251 offset:35840
	ds_read_b128 v[164:167], v251 offset:36864
	ds_read_b128 v[200:203], v251 offset:37888
	ds_read_b128 v[204:207], v251 offset:38912
	ds_read_b128 v[208:211], v251 offset:39936
	global_load_lds_dwordx4 v[168:169], off
	v_lshl_add_u64 v[168:169], v[168:169], 0, s[70:71]
	s_mov_b32 m0, s27
	s_nop 0
	global_load_lds_dwordx4 v[168:169], off
	s_waitcnt vmcnt(8)
	s_waitcnt lgkmcnt(0)
	s_barrier
	s_setprio 1
	v_mfma_f32_16x16x32_bf16 v[168:171], v[80:83], v[148:151], v[180:183]
	v_mfma_f32_16x16x32_bf16 v[180:183], v[84:87], v[152:155], v[168:171]
	v_mfma_f32_16x16x32_bf16 v[168:171], v[104:107], v[148:151], v[176:179]
	v_mfma_f32_16x16x32_bf16 v[128:131], v[80:83], v[156:159], v[128:131]
	v_mfma_f32_16x16x32_bf16 v[120:123], v[104:107], v[156:159], v[120:123]
	v_mfma_f32_16x16x32_bf16 v[100:103], v[80:83], v[164:167], v[100:103]
	v_mfma_f32_16x16x32_bf16 v[96:99], v[104:107], v[164:167], v[96:99]
	v_mfma_f32_16x16x32_bf16 v[76:79], v[80:83], v[204:207], v[76:79]
	v_mfma_f32_16x16x32_bf16 v[72:75], v[104:107], v[204:207], v[72:75]
	v_mfma_f32_16x16x32_bf16 v[176:179], v[108:111], v[152:155], v[168:171]
	v_mfma_f32_16x16x32_bf16 v[128:131], v[84:87], v[160:163], v[128:131]
	v_mfma_f32_16x16x32_bf16 v[120:123], v[108:111], v[160:163], v[120:123]
	v_mfma_f32_16x16x32_bf16 v[100:103], v[84:87], v[200:203], v[100:103]
	v_mfma_f32_16x16x32_bf16 v[96:99], v[108:111], v[200:203], v[96:99]
	v_mfma_f32_16x16x32_bf16 v[76:79], v[84:87], v[208:211], v[76:79]
	v_mfma_f32_16x16x32_bf16 v[72:75], v[108:111], v[208:211], v[72:75]
	v_mfma_f32_16x16x32_bf16 v[168:171], v[124:127], v[148:151], v[172:175]
	v_mfma_f32_16x16x32_bf16 v[144:147], v[136:139], v[148:151], v[144:147]
	v_mfma_f32_16x16x32_bf16 v[116:119], v[124:127], v[156:159], v[116:119]
	v_mfma_f32_16x16x32_bf16 v[112:115], v[136:139], v[156:159], v[112:115]
	v_mfma_f32_16x16x32_bf16 v[92:95], v[124:127], v[164:167], v[92:95]
	v_mfma_f32_16x16x32_bf16 v[88:91], v[136:139], v[164:167], v[88:91]
	v_mfma_f32_16x16x32_bf16 v[68:71], v[124:127], v[204:207], v[68:71]
	v_mfma_f32_16x16x32_bf16 v[64:67], v[136:139], v[204:207], v[64:67]
	v_mfma_f32_16x16x32_bf16 v[172:175], v[132:135], v[152:155], v[168:171]
	v_mfma_f32_16x16x32_bf16 v[168:171], v[140:143], v[152:155], v[144:147]
	v_mfma_f32_16x16x32_bf16 v[116:119], v[132:135], v[160:163], v[116:119]
	v_mfma_f32_16x16x32_bf16 v[112:115], v[140:143], v[160:163], v[112:115]
	v_mfma_f32_16x16x32_bf16 v[92:95], v[132:135], v[200:203], v[92:95]
	v_mfma_f32_16x16x32_bf16 v[88:91], v[140:143], v[200:203], v[88:91]
	v_mfma_f32_16x16x32_bf16 v[68:71], v[132:135], v[208:211], v[68:71]
	v_mfma_f32_16x16x32_bf16 v[64:67], v[140:143], v[208:211], v[64:67]
	s_setprio 0
	s_barrier
	s_add_i32 s14, s24, s19
	v_lshl_add_u64 v[208:209], v[212:213], 0, s[56:57]
	s_mov_b32 m0, s14
	ds_read_b128 v[144:147], v251 offset:49152
	ds_read_b128 v[148:151], v251 offset:50176
	ds_read_b128 v[152:155], v251 offset:51200
	ds_read_b128 v[156:159], v251 offset:52224
	ds_read_b128 v[160:163], v251 offset:53248
	ds_read_b128 v[164:167], v251 offset:54272
	ds_read_b128 v[200:203], v251 offset:55296
	ds_read_b128 v[204:207], v251 offset:56320
	global_load_lds_dwordx4 v[208:209], off
	v_lshl_add_u64 v[208:209], v[214:215], 0, s[56:57]
	s_add_i32 m0, s14, 0x2000
	s_add_i32 s14, s49, s19
	global_load_lds_dwordx4 v[208:209], off
	v_lshl_add_u64 v[208:209], v[216:217], 0, s[56:57]
	s_mov_b32 m0, s14
	s_nop 0
	global_load_lds_dwordx4 v[208:209], off
	v_lshl_add_u64 v[208:209], v[218:219], 0, s[56:57]
	s_add_i32 m0, s14, 0x2000
	s_nop 0
	global_load_lds_dwordx4 v[208:209], off
	v_lshl_add_u64 v[208:209], v[220:221], 0, s[56:57]
	s_mov_b32 m0, s29
	s_nop 0
	global_load_lds_dwordx4 v[208:209], off
	v_lshl_add_u64 v[208:209], v[222:223], 0, s[56:57]
	s_mov_b32 m0, s30
	s_nop 0
	global_load_lds_dwordx4 v[208:209], off
	s_waitcnt vmcnt(8)
	s_waitcnt lgkmcnt(0)
	s_barrier
	s_setprio 1
	v_mfma_f32_16x16x32_bf16 v[60:63], v[80:83], v[144:147], v[60:63]
	v_mfma_f32_16x16x32_bf16 v[56:59], v[104:107], v[144:147], v[56:59]
	v_mfma_f32_16x16x32_bf16 v[44:47], v[80:83], v[152:155], v[44:47]
	v_mfma_f32_16x16x32_bf16 v[40:43], v[104:107], v[152:155], v[40:43]
	v_mfma_f32_16x16x32_bf16 v[28:31], v[80:83], v[160:163], v[28:31]
	v_mfma_f32_16x16x32_bf16 v[24:27], v[104:107], v[160:163], v[24:27]
	v_mfma_f32_16x16x32_bf16 v[12:15], v[80:83], v[200:203], v[12:15]
	v_mfma_f32_16x16x32_bf16 v[8:11], v[104:107], v[200:203], v[8:11]
	v_mfma_f32_16x16x32_bf16 v[60:63], v[84:87], v[148:151], v[60:63]
	v_mfma_f32_16x16x32_bf16 v[56:59], v[108:111], v[148:151], v[56:59]
	v_mfma_f32_16x16x32_bf16 v[44:47], v[84:87], v[156:159], v[44:47]
	v_mfma_f32_16x16x32_bf16 v[40:43], v[108:111], v[156:159], v[40:43]
	v_mfma_f32_16x16x32_bf16 v[28:31], v[84:87], v[164:167], v[28:31]
	v_mfma_f32_16x16x32_bf16 v[24:27], v[108:111], v[164:167], v[24:27]
	v_mfma_f32_16x16x32_bf16 v[12:15], v[84:87], v[204:207], v[12:15]
	v_mfma_f32_16x16x32_bf16 v[8:11], v[108:111], v[204:207], v[8:11]
	v_mfma_f32_16x16x32_bf16 v[52:55], v[124:127], v[144:147], v[52:55]
	v_mfma_f32_16x16x32_bf16 v[48:51], v[136:139], v[144:147], v[48:51]
	v_mfma_f32_16x16x32_bf16 v[36:39], v[124:127], v[152:155], v[36:39]
	v_mfma_f32_16x16x32_bf16 v[32:35], v[136:139], v[152:155], v[32:35]
	v_mfma_f32_16x16x32_bf16 v[20:23], v[124:127], v[160:163], v[20:23]
	v_mfma_f32_16x16x32_bf16 v[16:19], v[136:139], v[160:163], v[16:19]
	v_mfma_f32_16x16x32_bf16 v[4:7], v[124:127], v[200:203], v[4:7]
	v_mfma_f32_16x16x32_bf16 v[0:3], v[136:139], v[200:203], v[0:3]
	v_mfma_f32_16x16x32_bf16 v[52:55], v[132:135], v[148:151], v[52:55]
	v_mfma_f32_16x16x32_bf16 v[48:51], v[140:143], v[148:151], v[48:51]
	v_mfma_f32_16x16x32_bf16 v[36:39], v[132:135], v[156:159], v[36:39]
	v_mfma_f32_16x16x32_bf16 v[32:35], v[140:143], v[156:159], v[32:35]
	v_mfma_f32_16x16x32_bf16 v[20:23], v[132:135], v[164:167], v[20:23]
	v_mfma_f32_16x16x32_bf16 v[16:19], v[140:143], v[164:167], v[16:19]
	v_mfma_f32_16x16x32_bf16 v[4:7], v[132:135], v[204:207], v[4:7]
	v_mfma_f32_16x16x32_bf16 v[0:3], v[140:143], v[204:207], v[0:3]
	s_setprio 0
	s_barrier
	s_add_u32 s44, s44, 0x100
	s_addc_u32 s45, s45, 0
	s_add_u32 s16, s16, 0x100
	s_addc_u32 s17, s17, 0
	s_cmp_ge_u32 s23, s28
	s_mov_b32 s14, s23
.LBB0_422:
	s_add_i32 s23, s14, 2
	s_add_u32 s24, s44, 0x80
	s_addc_u32 s15, s45, 0
	s_add_i32 s49, 0, 0x10000
	s_cmp_eq_u32 s31, s14
	s_cselect_b32 s15, s1, s15
	s_cselect_b32 s14, s0, s24
	s_cselect_b32 s51, s43, s17
	s_cselect_b32 s50, s42, s16
	s_add_i32 s24, 0, 0x14000
	v_add_u32_e32 v108, s49, v249
	v_add_u32_e32 v140, s24, v249
	ds_read_b128 v[80:83], v108
	ds_read_b128 v[84:87], v108 offset:1024
	ds_read_b128 v[104:107], v108 offset:2048
	ds_read_b128 v[108:111], v108 offset:3072
	ds_read_b128 v[124:127], v140
	ds_read_b128 v[132:135], v140 offset:1024
	ds_read_b128 v[136:139], v140 offset:2048
	ds_read_b128 v[140:143], v140 offset:3072
	v_lshl_add_u64 v[208:209], s[44:45], 0, v[196:197]
	s_add_i32 m0, s20, 0xc000
	ds_read_b128 v[144:147], v251
	ds_read_b128 v[148:151], v251 offset:1024
	ds_read_b128 v[152:155], v251 offset:2048
	ds_read_b128 v[156:159], v251 offset:3072
	ds_read_b128 v[160:163], v251 offset:4096
	ds_read_b128 v[164:167], v251 offset:5120
	ds_read_b128 v[200:203], v251 offset:6144
	ds_read_b128 v[204:207], v251 offset:7168
	global_load_lds_dwordx4 v[208:209], off
	v_lshl_add_u64 v[208:209], s[44:45], 0, v[198:199]
	s_add_i32 m0, s20, 0xe000
	s_nop 0
	global_load_lds_dwordx4 v[208:209], off
	s_waitcnt vmcnt(8)
	s_waitcnt lgkmcnt(0)
	s_barrier
	s_setprio 1
	v_mfma_f32_16x16x32_bf16 v[180:183], v[80:83], v[144:147], v[180:183]
	v_mfma_f32_16x16x32_bf16 v[176:179], v[104:107], v[144:147], v[176:179]
	v_mfma_f32_16x16x32_bf16 v[128:131], v[80:83], v[152:155], v[128:131]
	v_mfma_f32_16x16x32_bf16 v[120:123], v[104:107], v[152:155], v[120:123]
	v_mfma_f32_16x16x32_bf16 v[100:103], v[80:83], v[160:163], v[100:103]
	v_mfma_f32_16x16x32_bf16 v[96:99], v[104:107], v[160:163], v[96:99]
	v_mfma_f32_16x16x32_bf16 v[76:79], v[80:83], v[200:203], v[76:79]
	v_mfma_f32_16x16x32_bf16 v[72:75], v[104:107], v[200:203], v[72:75]
	v_mfma_f32_16x16x32_bf16 v[180:183], v[84:87], v[148:151], v[180:183]
	v_mfma_f32_16x16x32_bf16 v[176:179], v[108:111], v[148:151], v[176:179]
	v_mfma_f32_16x16x32_bf16 v[128:131], v[84:87], v[156:159], v[128:131]
	v_mfma_f32_16x16x32_bf16 v[120:123], v[108:111], v[156:159], v[120:123]
	v_mfma_f32_16x16x32_bf16 v[100:103], v[84:87], v[164:167], v[100:103]
	v_mfma_f32_16x16x32_bf16 v[96:99], v[108:111], v[164:167], v[96:99]
	v_mfma_f32_16x16x32_bf16 v[76:79], v[84:87], v[204:207], v[76:79]
	v_mfma_f32_16x16x32_bf16 v[72:75], v[108:111], v[204:207], v[72:75]
	v_mfma_f32_16x16x32_bf16 v[172:175], v[124:127], v[144:147], v[172:175]
	v_mfma_f32_16x16x32_bf16 v[116:119], v[124:127], v[152:155], v[116:119]
	v_mfma_f32_16x16x32_bf16 v[112:115], v[136:139], v[152:155], v[112:115]
	v_mfma_f32_16x16x32_bf16 v[92:95], v[124:127], v[160:163], v[92:95]
	v_mfma_f32_16x16x32_bf16 v[88:91], v[136:139], v[160:163], v[88:91]
	v_mfma_f32_16x16x32_bf16 v[68:71], v[124:127], v[200:203], v[68:71]
	v_mfma_f32_16x16x32_bf16 v[64:67], v[136:139], v[200:203], v[64:67]
	v_mfma_f32_16x16x32_bf16 v[172:175], v[132:135], v[148:151], v[172:175]
	v_mfma_f32_16x16x32_bf16 v[144:147], v[136:139], v[144:147], v[168:171]
	v_mfma_f32_16x16x32_bf16 v[116:119], v[132:135], v[156:159], v[116:119]
	v_mfma_f32_16x16x32_bf16 v[112:115], v[140:143], v[156:159], v[112:115]
	v_mfma_f32_16x16x32_bf16 v[92:95], v[132:135], v[164:167], v[92:95]
	v_mfma_f32_16x16x32_bf16 v[88:91], v[140:143], v[164:167], v[88:91]
	v_mfma_f32_16x16x32_bf16 v[68:71], v[132:135], v[204:207], v[68:71]
	v_mfma_f32_16x16x32_bf16 v[64:67], v[140:143], v[204:207], v[64:67]
	v_mfma_f32_16x16x32_bf16 v[144:147], v[140:143], v[148:151], v[144:147]
	s_setprio 0
	s_barrier
	s_add_i32 s49, s49, s19
	v_lshl_add_u64 v[212:213], s[50:51], 0, v[184:185]
	s_mov_b32 m0, s49
	ds_read_b128 v[148:151], v251 offset:16384
	ds_read_b128 v[152:155], v251 offset:17408
	ds_read_b128 v[156:159], v251 offset:18432
	ds_read_b128 v[160:163], v251 offset:19456
	ds_read_b128 v[164:167], v251 offset:20480
	ds_read_b128 v[168:171], v251 offset:21504
	ds_read_b128 v[200:203], v251 offset:22528
	ds_read_b128 v[204:207], v251 offset:23552
	global_load_lds_dwordx4 v[212:213], off
	s_add_i32 m0, s49, 0x2000
	s_add_u32 s50, s50, s8
	v_lshl_add_u64 v[214:215], v[212:213], 0, s[70:71]
	s_addc_u32 s51, s51, 0
	s_add_i32 s24, s24, s19
	global_load_lds_dwordx4 v[214:215], off
	v_lshl_add_u64 v[216:217], s[50:51], 0, v[184:185]
	s_mov_b32 m0, s24
	v_lshl_add_u64 v[218:219], v[216:217], 0, s[70:71]
	global_load_lds_dwordx4 v[216:217], off
	s_add_i32 m0, s24, 0x2000
	v_lshl_add_u64 v[220:221], s[14:15], 0, v[194:195]
	global_load_lds_dwordx4 v[218:219], off
	s_mov_b32 m0, s20
	v_lshl_add_u64 v[222:223], v[220:221], 0, s[70:71]
	global_load_lds_dwordx4 v[220:221], off
	s_mov_b32 m0, s25
	s_nop 0
	global_load_lds_dwordx4 v[222:223], off
	s_waitcnt vmcnt(8)
	s_waitcnt lgkmcnt(0)
	s_barrier
	s_setprio 1
	v_mfma_f32_16x16x32_bf16 v[60:63], v[80:83], v[148:151], v[60:63]
	v_mfma_f32_16x16x32_bf16 v[56:59], v[104:107], v[148:151], v[56:59]
	v_mfma_f32_16x16x32_bf16 v[44:47], v[80:83], v[156:159], v[44:47]
	v_mfma_f32_16x16x32_bf16 v[40:43], v[104:107], v[156:159], v[40:43]
	v_mfma_f32_16x16x32_bf16 v[28:31], v[80:83], v[164:167], v[28:31]
	v_mfma_f32_16x16x32_bf16 v[24:27], v[104:107], v[164:167], v[24:27]
	v_mfma_f32_16x16x32_bf16 v[12:15], v[80:83], v[200:203], v[12:15]
	v_mfma_f32_16x16x32_bf16 v[8:11], v[104:107], v[200:203], v[8:11]
	v_mfma_f32_16x16x32_bf16 v[60:63], v[84:87], v[152:155], v[60:63]
	v_mfma_f32_16x16x32_bf16 v[56:59], v[108:111], v[152:155], v[56:59]
	v_mfma_f32_16x16x32_bf16 v[44:47], v[84:87], v[160:163], v[44:47]
	v_mfma_f32_16x16x32_bf16 v[40:43], v[108:111], v[160:163], v[40:43]
	v_mfma_f32_16x16x32_bf16 v[28:31], v[84:87], v[168:171], v[28:31]
	v_mfma_f32_16x16x32_bf16 v[24:27], v[108:111], v[168:171], v[24:27]
	v_mfma_f32_16x16x32_bf16 v[12:15], v[84:87], v[204:207], v[12:15]
	v_mfma_f32_16x16x32_bf16 v[8:11], v[108:111], v[204:207], v[8:11]
	v_mfma_f32_16x16x32_bf16 v[52:55], v[124:127], v[148:151], v[52:55]
	v_mfma_f32_16x16x32_bf16 v[48:51], v[136:139], v[148:151], v[48:51]
	v_mfma_f32_16x16x32_bf16 v[36:39], v[124:127], v[156:159], v[36:39]
	v_mfma_f32_16x16x32_bf16 v[32:35], v[136:139], v[156:159], v[32:35]
	v_mfma_f32_16x16x32_bf16 v[20:23], v[124:127], v[164:167], v[20:23]
	v_mfma_f32_16x16x32_bf16 v[16:19], v[136:139], v[164:167], v[16:19]
	v_mfma_f32_16x16x32_bf16 v[4:7], v[124:127], v[200:203], v[4:7]
	v_mfma_f32_16x16x32_bf16 v[0:3], v[136:139], v[200:203], v[0:3]
	v_mfma_f32_16x16x32_bf16 v[52:55], v[132:135], v[152:155], v[52:55]
	v_mfma_f32_16x16x32_bf16 v[48:51], v[140:143], v[152:155], v[48:51]
	v_mfma_f32_16x16x32_bf16 v[36:39], v[132:135], v[160:163], v[36:39]
	v_mfma_f32_16x16x32_bf16 v[32:35], v[140:143], v[160:163], v[32:35]
	v_mfma_f32_16x16x32_bf16 v[20:23], v[132:135], v[168:171], v[20:23]
	v_mfma_f32_16x16x32_bf16 v[16:19], v[140:143], v[168:171], v[16:19]
	v_mfma_f32_16x16x32_bf16 v[4:7], v[132:135], v[204:207], v[4:7]
	v_mfma_f32_16x16x32_bf16 v[0:3], v[140:143], v[204:207], v[0:3]
	s_setprio 0
	s_barrier
	s_add_i32 s24, 0, 0x18000
	s_add_i32 s49, 0, 0x1c000
	v_add_u32_e32 v108, s24, v249
	v_add_u32_e32 v140, s49, v249
	ds_read_b128 v[80:83], v108
	ds_read_b128 v[84:87], v108 offset:1024
	ds_read_b128 v[104:107], v108 offset:2048
	ds_read_b128 v[108:111], v108 offset:3072
	ds_read_b128 v[124:127], v140
	ds_read_b128 v[132:135], v140 offset:1024
	ds_read_b128 v[136:139], v140 offset:2048
	ds_read_b128 v[140:143], v140 offset:3072
	s_add_u32 s14, s14, s8
	s_addc_u32 s15, s15, 0
	s_mov_b32 m0, s26
	v_lshl_add_u64 v[168:169], s[14:15], 0, v[194:195]
	ds_read_b128 v[148:151], v251 offset:32768
	ds_read_b128 v[152:155], v251 offset:33792
	ds_read_b128 v[156:159], v251 offset:34816
	ds_read_b128 v[160:163], v251 offset:35840
	ds_read_b128 v[164:167], v251 offset:36864
	ds_read_b128 v[200:203], v251 offset:37888
	ds_read_b128 v[204:207], v251 offset:38912
	ds_read_b128 v[208:211], v251 offset:39936
	global_load_lds_dwordx4 v[168:169], off
	v_lshl_add_u64 v[168:169], v[168:169], 0, s[70:71]
	s_mov_b32 m0, s27
	s_nop 0
	global_load_lds_dwordx4 v[168:169], off
	s_waitcnt vmcnt(8)
	s_waitcnt lgkmcnt(0)
	s_barrier
	s_setprio 1
	v_mfma_f32_16x16x32_bf16 v[168:171], v[80:83], v[148:151], v[180:183]
	v_mfma_f32_16x16x32_bf16 v[180:183], v[84:87], v[152:155], v[168:171]
	v_mfma_f32_16x16x32_bf16 v[168:171], v[104:107], v[148:151], v[176:179]
	v_mfma_f32_16x16x32_bf16 v[128:131], v[80:83], v[156:159], v[128:131]
	v_mfma_f32_16x16x32_bf16 v[120:123], v[104:107], v[156:159], v[120:123]
	v_mfma_f32_16x16x32_bf16 v[100:103], v[80:83], v[164:167], v[100:103]
	v_mfma_f32_16x16x32_bf16 v[96:99], v[104:107], v[164:167], v[96:99]
	v_mfma_f32_16x16x32_bf16 v[76:79], v[80:83], v[204:207], v[76:79]
	v_mfma_f32_16x16x32_bf16 v[72:75], v[104:107], v[204:207], v[72:75]
	v_mfma_f32_16x16x32_bf16 v[176:179], v[108:111], v[152:155], v[168:171]
	v_mfma_f32_16x16x32_bf16 v[128:131], v[84:87], v[160:163], v[128:131]
	v_mfma_f32_16x16x32_bf16 v[120:123], v[108:111], v[160:163], v[120:123]
	v_mfma_f32_16x16x32_bf16 v[100:103], v[84:87], v[200:203], v[100:103]
	v_mfma_f32_16x16x32_bf16 v[96:99], v[108:111], v[200:203], v[96:99]
	v_mfma_f32_16x16x32_bf16 v[76:79], v[84:87], v[208:211], v[76:79]
	v_mfma_f32_16x16x32_bf16 v[72:75], v[108:111], v[208:211], v[72:75]
	v_mfma_f32_16x16x32_bf16 v[168:171], v[124:127], v[148:151], v[172:175]
	v_mfma_f32_16x16x32_bf16 v[144:147], v[136:139], v[148:151], v[144:147]
	v_mfma_f32_16x16x32_bf16 v[116:119], v[124:127], v[156:159], v[116:119]
	v_mfma_f32_16x16x32_bf16 v[112:115], v[136:139], v[156:159], v[112:115]
	v_mfma_f32_16x16x32_bf16 v[92:95], v[124:127], v[164:167], v[92:95]
	v_mfma_f32_16x16x32_bf16 v[88:91], v[136:139], v[164:167], v[88:91]
	v_mfma_f32_16x16x32_bf16 v[68:71], v[124:127], v[204:207], v[68:71]
	v_mfma_f32_16x16x32_bf16 v[64:67], v[136:139], v[204:207], v[64:67]
	v_mfma_f32_16x16x32_bf16 v[172:175], v[132:135], v[152:155], v[168:171]
	v_mfma_f32_16x16x32_bf16 v[168:171], v[140:143], v[152:155], v[144:147]
	v_mfma_f32_16x16x32_bf16 v[116:119], v[132:135], v[160:163], v[116:119]
	v_mfma_f32_16x16x32_bf16 v[112:115], v[140:143], v[160:163], v[112:115]
	v_mfma_f32_16x16x32_bf16 v[92:95], v[132:135], v[200:203], v[92:95]
	v_mfma_f32_16x16x32_bf16 v[88:91], v[140:143], v[200:203], v[88:91]
	v_mfma_f32_16x16x32_bf16 v[68:71], v[132:135], v[208:211], v[68:71]
	v_mfma_f32_16x16x32_bf16 v[64:67], v[140:143], v[208:211], v[64:67]
	s_setprio 0
	s_barrier
	s_add_i32 s14, s24, s19
	v_lshl_add_u64 v[208:209], v[212:213], 0, s[56:57]
	s_mov_b32 m0, s14
	ds_read_b128 v[144:147], v251 offset:49152
	ds_read_b128 v[148:151], v251 offset:50176
	ds_read_b128 v[152:155], v251 offset:51200
	ds_read_b128 v[156:159], v251 offset:52224
	ds_read_b128 v[160:163], v251 offset:53248
	ds_read_b128 v[164:167], v251 offset:54272
	ds_read_b128 v[200:203], v251 offset:55296
	ds_read_b128 v[204:207], v251 offset:56320
	global_load_lds_dwordx4 v[208:209], off
	v_lshl_add_u64 v[208:209], v[214:215], 0, s[56:57]
	s_add_i32 m0, s14, 0x2000
	s_add_i32 s14, s49, s19
	global_load_lds_dwordx4 v[208:209], off
	v_lshl_add_u64 v[208:209], v[216:217], 0, s[56:57]
	s_mov_b32 m0, s14
	s_nop 0
	global_load_lds_dwordx4 v[208:209], off
	v_lshl_add_u64 v[208:209], v[218:219], 0, s[56:57]
	s_add_i32 m0, s14, 0x2000
	s_nop 0
	global_load_lds_dwordx4 v[208:209], off
	v_lshl_add_u64 v[208:209], v[220:221], 0, s[56:57]
	s_mov_b32 m0, s29
	s_nop 0
	global_load_lds_dwordx4 v[208:209], off
	v_lshl_add_u64 v[208:209], v[222:223], 0, s[56:57]
	s_mov_b32 m0, s30
	s_nop 0
	global_load_lds_dwordx4 v[208:209], off
	s_waitcnt vmcnt(8)
	s_waitcnt lgkmcnt(0)
	s_barrier
	s_setprio 1
	v_mfma_f32_16x16x32_bf16 v[60:63], v[80:83], v[144:147], v[60:63]
	v_mfma_f32_16x16x32_bf16 v[56:59], v[104:107], v[144:147], v[56:59]
	v_mfma_f32_16x16x32_bf16 v[44:47], v[80:83], v[152:155], v[44:47]
	v_mfma_f32_16x16x32_bf16 v[40:43], v[104:107], v[152:155], v[40:43]
	v_mfma_f32_16x16x32_bf16 v[28:31], v[80:83], v[160:163], v[28:31]
	v_mfma_f32_16x16x32_bf16 v[24:27], v[104:107], v[160:163], v[24:27]
	v_mfma_f32_16x16x32_bf16 v[12:15], v[80:83], v[200:203], v[12:15]
	v_mfma_f32_16x16x32_bf16 v[8:11], v[104:107], v[200:203], v[8:11]
	v_mfma_f32_16x16x32_bf16 v[60:63], v[84:87], v[148:151], v[60:63]
	v_mfma_f32_16x16x32_bf16 v[56:59], v[108:111], v[148:151], v[56:59]
	v_mfma_f32_16x16x32_bf16 v[44:47], v[84:87], v[156:159], v[44:47]
	v_mfma_f32_16x16x32_bf16 v[40:43], v[108:111], v[156:159], v[40:43]
	v_mfma_f32_16x16x32_bf16 v[28:31], v[84:87], v[164:167], v[28:31]
	v_mfma_f32_16x16x32_bf16 v[24:27], v[108:111], v[164:167], v[24:27]
	v_mfma_f32_16x16x32_bf16 v[12:15], v[84:87], v[204:207], v[12:15]
	v_mfma_f32_16x16x32_bf16 v[8:11], v[108:111], v[204:207], v[8:11]
	v_mfma_f32_16x16x32_bf16 v[52:55], v[124:127], v[144:147], v[52:55]
	v_mfma_f32_16x16x32_bf16 v[48:51], v[136:139], v[144:147], v[48:51]
	v_mfma_f32_16x16x32_bf16 v[36:39], v[124:127], v[152:155], v[36:39]
	v_mfma_f32_16x16x32_bf16 v[32:35], v[136:139], v[152:155], v[32:35]
	v_mfma_f32_16x16x32_bf16 v[20:23], v[124:127], v[160:163], v[20:23]
	v_mfma_f32_16x16x32_bf16 v[16:19], v[136:139], v[160:163], v[16:19]
	v_mfma_f32_16x16x32_bf16 v[4:7], v[124:127], v[200:203], v[4:7]
	v_mfma_f32_16x16x32_bf16 v[0:3], v[136:139], v[200:203], v[0:3]
	v_mfma_f32_16x16x32_bf16 v[52:55], v[132:135], v[148:151], v[52:55]
	v_mfma_f32_16x16x32_bf16 v[48:51], v[140:143], v[148:151], v[48:51]
	v_mfma_f32_16x16x32_bf16 v[36:39], v[132:135], v[156:159], v[36:39]
	v_mfma_f32_16x16x32_bf16 v[32:35], v[140:143], v[156:159], v[32:35]
	v_mfma_f32_16x16x32_bf16 v[20:23], v[132:135], v[164:167], v[20:23]
	v_mfma_f32_16x16x32_bf16 v[16:19], v[140:143], v[164:167], v[16:19]
	v_mfma_f32_16x16x32_bf16 v[4:7], v[132:135], v[204:207], v[4:7]
	v_mfma_f32_16x16x32_bf16 v[0:3], v[140:143], v[204:207], v[0:3]
	s_setprio 0
	s_barrier
	s_add_u32 s44, s44, 0x100
	s_addc_u32 s45, s45, 0
	s_add_u32 s16, s16, 0x100
	s_addc_u32 s17, s17, 0
	s_cmp_ge_u32 s23, s28
	s_mov_b32 s14, s23
	s_cbranch_scc0 .LBB0_422
	s_and_b64 vcc, exec, s[12:13]
	s_cbranch_vccz .LBB0_425
	s_barrier

.LBB0_458:
	s_ashr_i32 s43, s42, 31
	s_lshl_b64 s[44:45], s[42:43], 19
	s_add_u32 s44, s64, s44
	s_addc_u32 s45, s65, s45
	s_and_b64 s[46:47], s[40:41], exec
	s_cselect_b32 s31, s45, s17
	s_cselect_b32 s43, s44, s16
	s_ashr_i32 s13, s12, 31
	s_lshl_b64 s[46:47], s[12:13], 19
	s_add_u32 s46, s22, s46
	s_addc_u32 s47, s23, s47
	s_and_b64 s[48:49], s[40:41], exec
	s_cselect_b32 s13, s47, s15
	s_cselect_b32 s50, s46, s14
	s_add_u32 s48, s16, 0x40080
	s_addc_u32 s49, s17, 0
	s_add_u32 s16, s14, 0x100
	s_addc_u32 s17, s15, 0
	s_mov_b32 s51, -2
	s_add_u32 s14, s48, 0xfffc0080
	s_addc_u32 s15, s49, -1
	s_add_i32 s70, 0, 0x10000
	s_cmp_eq_u32 s51, 12
	s_cselect_b32 s15, s31, s15
	s_cselect_b32 s14, s43, s14
	v_add_u32_e32 v138, s70, v142
	s_cselect_b32 s61, s13, s17
	s_cselect_b32 s60, s50, s16
	s_add_i32 s84, 0, 0x14000
	ds_read_b128 v[134:137], v138
	ds_read_b128 v[148:151], v138 offset:1024
	ds_read_b128 v[152:155], v138 offset:2048
	ds_read_b128 v[156:159], v138 offset:3072
	v_add_u32_e32 v138, s84, v142
	ds_read_b128 v[160:163], v138
	ds_read_b128 v[164:167], v138 offset:1024
	ds_read_b128 v[168:171], v138 offset:2048
	ds_read_b128 v[172:175], v138 offset:3072
	v_lshl_add_u64 v[138:139], s[48:49], 0, v[132:133]
	s_add_i32 m0, s19, 0xc000
	ds_read_b128 v[176:179], v146
	ds_read_b128 v[180:183], v146 offset:1024
	ds_read_b128 v[194:197], v146 offset:2048
	ds_read_b128 v[198:201], v146 offset:3072
	ds_read_b128 v[202:205], v146 offset:4096
	ds_read_b128 v[206:209], v146 offset:5120
	ds_read_b128 v[210:213], v146 offset:6144
	ds_read_b128 v[214:217], v146 offset:7168
	global_load_lds_dwordx4 v[138:139], off
	v_lshl_add_u64 v[138:139], v[138:139], 0, s[34:35]
	s_add_i32 m0, s19, 0xe000
	s_nop 0
	global_load_lds_dwordx4 v[138:139], off
	s_waitcnt vmcnt(8)
	s_waitcnt lgkmcnt(0)
	s_barrier
	s_setprio 1
	v_mfma_f32_16x16x32_bf16 v[124:127], v[134:137], v[176:179], 0
	v_mfma_f32_16x16x32_bf16 v[116:119], v[152:155], v[176:179], 0
	v_mfma_f32_16x16x32_bf16 v[108:111], v[134:137], v[194:197], 0
	v_mfma_f32_16x16x32_bf16 v[100:103], v[152:155], v[194:197], 0
	v_mfma_f32_16x16x32_bf16 v[92:95], v[134:137], v[202:205], 0
	v_mfma_f32_16x16x32_bf16 v[84:87], v[152:155], v[202:205], 0
	v_mfma_f32_16x16x32_bf16 v[76:79], v[134:137], v[210:213], 0
	v_mfma_f32_16x16x32_bf16 v[68:71], v[152:155], v[210:213], 0
	v_mfma_f32_16x16x32_bf16 v[124:127], v[148:151], v[180:183], v[124:127]
	v_mfma_f32_16x16x32_bf16 v[116:119], v[156:159], v[180:183], v[116:119]
	v_mfma_f32_16x16x32_bf16 v[108:111], v[148:151], v[198:201], v[108:111]
	v_mfma_f32_16x16x32_bf16 v[100:103], v[156:159], v[198:201], v[100:103]
	v_mfma_f32_16x16x32_bf16 v[92:95], v[148:151], v[206:209], v[92:95]
	v_mfma_f32_16x16x32_bf16 v[84:87], v[156:159], v[206:209], v[84:87]
	v_mfma_f32_16x16x32_bf16 v[76:79], v[148:151], v[214:217], v[76:79]
	v_mfma_f32_16x16x32_bf16 v[68:71], v[156:159], v[214:217], v[68:71]
	v_mfma_f32_16x16x32_bf16 v[120:123], v[160:163], v[176:179], 0
	v_mfma_f32_16x16x32_bf16 v[112:115], v[168:171], v[176:179], 0
	v_mfma_f32_16x16x32_bf16 v[104:107], v[160:163], v[194:197], 0
	v_mfma_f32_16x16x32_bf16 v[96:99], v[168:171], v[194:197], 0
	v_mfma_f32_16x16x32_bf16 v[88:91], v[160:163], v[202:205], 0
	v_mfma_f32_16x16x32_bf16 v[80:83], v[168:171], v[202:205], 0
	v_mfma_f32_16x16x32_bf16 v[72:75], v[160:163], v[210:213], 0
	v_mfma_f32_16x16x32_bf16 v[64:67], v[168:171], v[210:213], 0
	v_mfma_f32_16x16x32_bf16 v[120:123], v[164:167], v[180:183], v[120:123]
	v_mfma_f32_16x16x32_bf16 v[112:115], v[172:175], v[180:183], v[112:115]
	v_mfma_f32_16x16x32_bf16 v[104:107], v[164:167], v[198:201], v[104:107]
	v_mfma_f32_16x16x32_bf16 v[96:99], v[172:175], v[198:201], v[96:99]
	v_mfma_f32_16x16x32_bf16 v[88:91], v[164:167], v[206:209], v[88:91]
	v_mfma_f32_16x16x32_bf16 v[80:83], v[172:175], v[206:209], v[80:83]
	v_mfma_f32_16x16x32_bf16 v[72:75], v[164:167], v[214:217], v[72:75]
	v_mfma_f32_16x16x32_bf16 v[64:67], v[172:175], v[214:217], v[64:67]
	s_setprio 0
	s_barrier
	v_lshl_add_u64 v[138:139], s[60:61], 0, v[184:185]
	s_add_i32 s60, s70, s6
	s_mov_b32 m0, s60
	ds_read_b128 v[176:179], v146 offset:16384
	ds_read_b128 v[180:183], v146 offset:17408
	ds_read_b128 v[194:197], v146 offset:18432
	ds_read_b128 v[198:201], v146 offset:19456
	ds_read_b128 v[202:205], v146 offset:20480
	ds_read_b128 v[206:209], v146 offset:21504
	ds_read_b128 v[210:213], v146 offset:22528
	ds_read_b128 v[214:217], v146 offset:23552
	global_load_lds_dwordx4 v[138:139], off
	v_lshl_add_u64 v[218:219], v[138:139], 0, s[34:35]
	s_add_i32 m0, s60, 0x2000
	s_add_i32 s60, s84, s6
	global_load_lds_dwordx4 v[218:219], off
	v_lshl_add_u64 v[218:219], v[138:139], 0, s[92:93]
	s_mov_b32 m0, s60
	s_nop 0
	global_load_lds_dwordx4 v[218:219], off
	v_lshl_add_u64 v[218:219], v[138:139], 0, s[52:53]
	s_add_i32 m0, s60, 0x2000
	s_nop 0
	global_load_lds_dwordx4 v[218:219], off
	v_lshl_add_u64 v[218:219], s[14:15], 0, v[128:129]
	s_mov_b32 m0, s19
	v_lshl_add_u64 v[220:221], v[218:219], 0, s[34:35]
	global_load_lds_dwordx4 v[218:219], off
	s_mov_b32 m0, s20
	s_nop 0
	global_load_lds_dwordx4 v[220:221], off
	s_waitcnt vmcnt(8)
	s_waitcnt lgkmcnt(0)
	s_barrier
	s_setprio 1
	v_mfma_f32_16x16x32_bf16 v[60:63], v[134:137], v[176:179], 0
	v_mfma_f32_16x16x32_bf16 v[52:55], v[152:155], v[176:179], 0
	v_mfma_f32_16x16x32_bf16 v[44:47], v[134:137], v[194:197], 0
	v_mfma_f32_16x16x32_bf16 v[36:39], v[152:155], v[194:197], 0
	v_mfma_f32_16x16x32_bf16 v[28:31], v[134:137], v[202:205], 0
	v_mfma_f32_16x16x32_bf16 v[20:23], v[152:155], v[202:205], 0
	v_mfma_f32_16x16x32_bf16 v[12:15], v[134:137], v[210:213], 0
	v_mfma_f32_16x16x32_bf16 v[4:7], v[152:155], v[210:213], 0
	v_mfma_f32_16x16x32_bf16 v[60:63], v[148:151], v[180:183], v[60:63]
	v_mfma_f32_16x16x32_bf16 v[52:55], v[156:159], v[180:183], v[52:55]
	v_mfma_f32_16x16x32_bf16 v[44:47], v[148:151], v[198:201], v[44:47]
	v_mfma_f32_16x16x32_bf16 v[36:39], v[156:159], v[198:201], v[36:39]
	v_mfma_f32_16x16x32_bf16 v[28:31], v[148:151], v[206:209], v[28:31]
	v_mfma_f32_16x16x32_bf16 v[20:23], v[156:159], v[206:209], v[20:23]
	v_mfma_f32_16x16x32_bf16 v[12:15], v[148:151], v[214:217], v[12:15]
	v_mfma_f32_16x16x32_bf16 v[4:7], v[156:159], v[214:217], v[4:7]
	v_mfma_f32_16x16x32_bf16 v[56:59], v[160:163], v[176:179], 0
	v_mfma_f32_16x16x32_bf16 v[48:51], v[168:171], v[176:179], 0
	v_mfma_f32_16x16x32_bf16 v[40:43], v[160:163], v[194:197], 0
	v_mfma_f32_16x16x32_bf16 v[32:35], v[168:171], v[194:197], 0
	v_mfma_f32_16x16x32_bf16 v[24:27], v[160:163], v[202:205], 0
	v_mfma_f32_16x16x32_bf16 v[16:19], v[168:171], v[202:205], 0
	v_mfma_f32_16x16x32_bf16 v[8:11], v[160:163], v[210:213], 0
	v_mfma_f32_16x16x32_bf16 v[0:3], v[168:171], v[210:213], 0
	v_mfma_f32_16x16x32_bf16 v[56:59], v[164:167], v[180:183], v[56:59]
	v_mfma_f32_16x16x32_bf16 v[48:51], v[172:175], v[180:183], v[48:51]
	v_mfma_f32_16x16x32_bf16 v[40:43], v[164:167], v[198:201], v[40:43]
	v_mfma_f32_16x16x32_bf16 v[32:35], v[172:175], v[198:201], v[32:35]
	v_mfma_f32_16x16x32_bf16 v[24:27], v[164:167], v[206:209], v[24:27]
	v_mfma_f32_16x16x32_bf16 v[16:19], v[172:175], v[206:209], v[16:19]
	v_mfma_f32_16x16x32_bf16 v[8:11], v[164:167], v[214:217], v[8:11]
	v_mfma_f32_16x16x32_bf16 v[0:3], v[172:175], v[214:217], v[0:3]
	s_setprio 0
	s_barrier
	s_add_i32 s14, 0, 0x18000
	v_add_u32_e32 v147, s14, v142
	s_add_i32 s15, 0, 0x1c000
	ds_read_b128 v[134:137], v147
	ds_read_b128 v[148:151], v147 offset:1024
	ds_read_b128 v[152:155], v147 offset:2048
	ds_read_b128 v[156:159], v147 offset:3072
	v_add_u32_e32 v147, s15, v142
	ds_read_b128 v[160:163], v147
	ds_read_b128 v[164:167], v147 offset:1024
	ds_read_b128 v[168:171], v147 offset:2048
	ds_read_b128 v[172:175], v147 offset:3072
	s_mov_b32 m0, s24
	v_lshl_add_u64 v[220:221], v[218:219], 0, s[92:93]
	ds_read_b128 v[176:179], v146 offset:32768
	ds_read_b128 v[180:183], v146 offset:33792
	ds_read_b128 v[194:197], v146 offset:34816
	ds_read_b128 v[198:201], v146 offset:35840
	ds_read_b128 v[202:205], v146 offset:36864
	ds_read_b128 v[206:209], v146 offset:37888
	ds_read_b128 v[210:213], v146 offset:38912
	ds_read_b128 v[214:217], v146 offset:39936
	global_load_lds_dwordx4 v[220:221], off
	v_lshl_add_u64 v[220:221], v[218:219], 0, s[52:53]
	s_mov_b32 m0, s25
	s_nop 0
	global_load_lds_dwordx4 v[220:221], off
	s_waitcnt vmcnt(8)
	s_waitcnt lgkmcnt(0)
	s_barrier
	s_setprio 1
	v_mfma_f32_16x16x32_bf16 v[124:127], v[134:137], v[176:179], v[124:127]
	v_mfma_f32_16x16x32_bf16 v[116:119], v[152:155], v[176:179], v[116:119]
	v_mfma_f32_16x16x32_bf16 v[108:111], v[134:137], v[194:197], v[108:111]
	v_mfma_f32_16x16x32_bf16 v[100:103], v[152:155], v[194:197], v[100:103]
	v_mfma_f32_16x16x32_bf16 v[92:95], v[134:137], v[202:205], v[92:95]
	v_mfma_f32_16x16x32_bf16 v[84:87], v[152:155], v[202:205], v[84:87]
	v_mfma_f32_16x16x32_bf16 v[76:79], v[134:137], v[210:213], v[76:79]
	v_mfma_f32_16x16x32_bf16 v[68:71], v[152:155], v[210:213], v[68:71]
	v_mfma_f32_16x16x32_bf16 v[124:127], v[148:151], v[180:183], v[124:127]
	v_mfma_f32_16x16x32_bf16 v[116:119], v[156:159], v[180:183], v[116:119]
	v_mfma_f32_16x16x32_bf16 v[108:111], v[148:151], v[198:201], v[108:111]
	v_mfma_f32_16x16x32_bf16 v[100:103], v[156:159], v[198:201], v[100:103]
	v_mfma_f32_16x16x32_bf16 v[92:95], v[148:151], v[206:209], v[92:95]
	v_mfma_f32_16x16x32_bf16 v[84:87], v[156:159], v[206:209], v[84:87]
	v_mfma_f32_16x16x32_bf16 v[76:79], v[148:151], v[214:217], v[76:79]
	v_mfma_f32_16x16x32_bf16 v[68:71], v[156:159], v[214:217], v[68:71]
	v_mfma_f32_16x16x32_bf16 v[120:123], v[160:163], v[176:179], v[120:123]
	v_mfma_f32_16x16x32_bf16 v[112:115], v[168:171], v[176:179], v[112:115]
	v_mfma_f32_16x16x32_bf16 v[104:107], v[160:163], v[194:197], v[104:107]
	v_mfma_f32_16x16x32_bf16 v[96:99], v[168:171], v[194:197], v[96:99]
	v_mfma_f32_16x16x32_bf16 v[88:91], v[160:163], v[202:205], v[88:91]
	v_mfma_f32_16x16x32_bf16 v[80:83], v[168:171], v[202:205], v[80:83]
	v_mfma_f32_16x16x32_bf16 v[72:75], v[160:163], v[210:213], v[72:75]
	v_mfma_f32_16x16x32_bf16 v[64:67], v[168:171], v[210:213], v[64:67]
	v_mfma_f32_16x16x32_bf16 v[120:123], v[164:167], v[180:183], v[120:123]
	v_mfma_f32_16x16x32_bf16 v[112:115], v[172:175], v[180:183], v[112:115]
	v_mfma_f32_16x16x32_bf16 v[104:107], v[164:167], v[198:201], v[104:107]
	v_mfma_f32_16x16x32_bf16 v[96:99], v[172:175], v[198:201], v[96:99]
	v_mfma_f32_16x16x32_bf16 v[88:91], v[164:167], v[206:209], v[88:91]
	v_mfma_f32_16x16x32_bf16 v[80:83], v[172:175], v[206:209], v[80:83]
	v_mfma_f32_16x16x32_bf16 v[72:75], v[164:167], v[214:217], v[72:75]
	v_mfma_f32_16x16x32_bf16 v[64:67], v[172:175], v[214:217], v[64:67]
	s_setprio 0
	s_barrier
	s_add_i32 s14, s14, s6
	v_lshl_add_u64 v[220:221], v[138:139], 0, s[56:57]
	s_mov_b32 m0, s14
	ds_read_b128 v[176:179], v146 offset:49152
	ds_read_b128 v[180:183], v146 offset:50176
	ds_read_b128 v[194:197], v146 offset:51200
	ds_read_b128 v[198:201], v146 offset:52224
	ds_read_b128 v[202:205], v146 offset:53248
	ds_read_b128 v[206:209], v146 offset:54272
	ds_read_b128 v[210:213], v146 offset:55296
	ds_read_b128 v[214:217], v146 offset:56320
	global_load_lds_dwordx4 v[220:221], off
	v_lshl_add_u64 v[220:221], v[138:139], 0, s[96:97]
	s_add_i32 m0, s14, 0x2000
	s_add_i32 s14, s15, s6
	global_load_lds_dwordx4 v[220:221], off
	v_lshl_add_u64 v[220:221], v[138:139], 0, s[88:89]
	s_mov_b32 m0, s14
	v_lshl_add_u64 v[138:139], v[138:139], 0, s[68:69]
	global_load_lds_dwordx4 v[220:221], off
	s_add_i32 m0, s14, 0x2000
	s_nop 0
	global_load_lds_dwordx4 v[138:139], off
	v_lshl_add_u64 v[138:139], v[218:219], 0, s[56:57]
	s_mov_b32 m0, s26
	s_nop 0
	global_load_lds_dwordx4 v[138:139], off
	v_lshl_add_u64 v[138:139], v[218:219], 0, s[96:97]
	s_mov_b32 m0, s27
	s_nop 0
	global_load_lds_dwordx4 v[138:139], off
	s_waitcnt vmcnt(8)
	s_waitcnt lgkmcnt(0)
	s_barrier
	s_setprio 1
	v_mfma_f32_16x16x32_bf16 v[60:63], v[134:137], v[176:179], v[60:63]
	v_mfma_f32_16x16x32_bf16 v[52:55], v[152:155], v[176:179], v[52:55]
	v_mfma_f32_16x16x32_bf16 v[44:47], v[134:137], v[194:197], v[44:47]
	v_mfma_f32_16x16x32_bf16 v[36:39], v[152:155], v[194:197], v[36:39]
	v_mfma_f32_16x16x32_bf16 v[28:31], v[134:137], v[202:205], v[28:31]
	v_mfma_f32_16x16x32_bf16 v[20:23], v[152:155], v[202:205], v[20:23]
	v_mfma_f32_16x16x32_bf16 v[12:15], v[134:137], v[210:213], v[12:15]
	v_mfma_f32_16x16x32_bf16 v[4:7], v[152:155], v[210:213], v[4:7]
	v_mfma_f32_16x16x32_bf16 v[60:63], v[148:151], v[180:183], v[60:63]
	v_mfma_f32_16x16x32_bf16 v[52:55], v[156:159], v[180:183], v[52:55]
	v_mfma_f32_16x16x32_bf16 v[44:47], v[148:151], v[198:201], v[44:47]
	v_mfma_f32_16x16x32_bf16 v[36:39], v[156:159], v[198:201], v[36:39]
	v_mfma_f32_16x16x32_bf16 v[28:31], v[148:151], v[206:209], v[28:31]
	v_mfma_f32_16x16x32_bf16 v[20:23], v[156:159], v[206:209], v[20:23]
	v_mfma_f32_16x16x32_bf16 v[12:15], v[148:151], v[214:217], v[12:15]
	v_mfma_f32_16x16x32_bf16 v[4:7], v[156:159], v[214:217], v[4:7]
	v_mfma_f32_16x16x32_bf16 v[56:59], v[160:163], v[176:179], v[56:59]
	v_mfma_f32_16x16x32_bf16 v[48:51], v[168:171], v[176:179], v[48:51]
	v_mfma_f32_16x16x32_bf16 v[40:43], v[160:163], v[194:197], v[40:43]
	v_mfma_f32_16x16x32_bf16 v[32:35], v[168:171], v[194:197], v[32:35]
	v_mfma_f32_16x16x32_bf16 v[24:27], v[160:163], v[202:205], v[24:27]
	v_mfma_f32_16x16x32_bf16 v[16:19], v[168:171], v[202:205], v[16:19]
	v_mfma_f32_16x16x32_bf16 v[8:11], v[160:163], v[210:213], v[8:11]
	v_mfma_f32_16x16x32_bf16 v[0:3], v[168:171], v[210:213], v[0:3]
	v_mfma_f32_16x16x32_bf16 v[56:59], v[164:167], v[180:183], v[56:59]
	v_mfma_f32_16x16x32_bf16 v[48:51], v[172:175], v[180:183], v[48:51]
	v_mfma_f32_16x16x32_bf16 v[40:43], v[164:167], v[198:201], v[40:43]
	v_mfma_f32_16x16x32_bf16 v[32:35], v[172:175], v[198:201], v[32:35]
	v_mfma_f32_16x16x32_bf16 v[24:27], v[164:167], v[206:209], v[24:27]
	v_mfma_f32_16x16x32_bf16 v[16:19], v[172:175], v[206:209], v[16:19]
	v_mfma_f32_16x16x32_bf16 v[8:11], v[164:167], v[214:217], v[8:11]
	v_mfma_f32_16x16x32_bf16 v[0:3], v[172:175], v[214:217], v[0:3]
	s_setprio 0
	s_barrier
	s_add_i32 s51, s51, 2
	s_add_u32 s48, s48, 0x100
	s_addc_u32 s49, s49, 0
	s_add_u32 s16, s16, 0x100
	s_addc_u32 s17, s17, 0
	s_cmp_gt_u32 s51, 13
.LBB0_459:
	s_add_u32 s14, s48, 0xfffc0080
	s_addc_u32 s15, s49, -1
	s_add_i32 s70, 0, 0x10000
	s_cmp_eq_u32 s51, 12
	s_cselect_b32 s15, s31, s15
	s_cselect_b32 s14, s43, s14
	v_add_u32_e32 v138, s70, v142
	s_cselect_b32 s61, s13, s17
	s_cselect_b32 s60, s50, s16
	s_add_i32 s84, 0, 0x14000
	ds_read_b128 v[134:137], v138
	ds_read_b128 v[148:151], v138 offset:1024
	ds_read_b128 v[152:155], v138 offset:2048
	ds_read_b128 v[156:159], v138 offset:3072
	v_add_u32_e32 v138, s84, v142
	ds_read_b128 v[160:163], v138
	ds_read_b128 v[164:167], v138 offset:1024
	ds_read_b128 v[168:171], v138 offset:2048
	ds_read_b128 v[172:175], v138 offset:3072
	v_lshl_add_u64 v[138:139], s[48:49], 0, v[132:133]
	s_add_i32 m0, s19, 0xc000
	ds_read_b128 v[176:179], v146
	ds_read_b128 v[180:183], v146 offset:1024
	ds_read_b128 v[194:197], v146 offset:2048
	ds_read_b128 v[198:201], v146 offset:3072
	ds_read_b128 v[202:205], v146 offset:4096
	ds_read_b128 v[206:209], v146 offset:5120
	ds_read_b128 v[210:213], v146 offset:6144
	ds_read_b128 v[214:217], v146 offset:7168
	global_load_lds_dwordx4 v[138:139], off
	v_lshl_add_u64 v[138:139], v[138:139], 0, s[34:35]
	s_add_i32 m0, s19, 0xe000
	s_nop 0
	global_load_lds_dwordx4 v[138:139], off
	s_waitcnt vmcnt(8)
	s_waitcnt lgkmcnt(0)
	s_barrier
	s_setprio 1
	v_mfma_f32_16x16x32_bf16 v[124:127], v[134:137], v[176:179], v[124:127]
	v_mfma_f32_16x16x32_bf16 v[116:119], v[152:155], v[176:179], v[116:119]
	v_mfma_f32_16x16x32_bf16 v[108:111], v[134:137], v[194:197], v[108:111]
	v_mfma_f32_16x16x32_bf16 v[100:103], v[152:155], v[194:197], v[100:103]
	v_mfma_f32_16x16x32_bf16 v[92:95], v[134:137], v[202:205], v[92:95]
	v_mfma_f32_16x16x32_bf16 v[84:87], v[152:155], v[202:205], v[84:87]
	v_mfma_f32_16x16x32_bf16 v[76:79], v[134:137], v[210:213], v[76:79]
	v_mfma_f32_16x16x32_bf16 v[68:71], v[152:155], v[210:213], v[68:71]
	v_mfma_f32_16x16x32_bf16 v[124:127], v[148:151], v[180:183], v[124:127]
	v_mfma_f32_16x16x32_bf16 v[116:119], v[156:159], v[180:183], v[116:119]
	v_mfma_f32_16x16x32_bf16 v[108:111], v[148:151], v[198:201], v[108:111]
	v_mfma_f32_16x16x32_bf16 v[100:103], v[156:159], v[198:201], v[100:103]
	v_mfma_f32_16x16x32_bf16 v[92:95], v[148:151], v[206:209], v[92:95]
	v_mfma_f32_16x16x32_bf16 v[84:87], v[156:159], v[206:209], v[84:87]
	v_mfma_f32_16x16x32_bf16 v[76:79], v[148:151], v[214:217], v[76:79]
	v_mfma_f32_16x16x32_bf16 v[68:71], v[156:159], v[214:217], v[68:71]
	v_mfma_f32_16x16x32_bf16 v[120:123], v[160:163], v[176:179], v[120:123]
	v_mfma_f32_16x16x32_bf16 v[112:115], v[168:171], v[176:179], v[112:115]
	v_mfma_f32_16x16x32_bf16 v[104:107], v[160:163], v[194:197], v[104:107]
	v_mfma_f32_16x16x32_bf16 v[96:99], v[168:171], v[194:197], v[96:99]
	v_mfma_f32_16x16x32_bf16 v[88:91], v[160:163], v[202:205], v[88:91]
	v_mfma_f32_16x16x32_bf16 v[80:83], v[168:171], v[202:205], v[80:83]
	v_mfma_f32_16x16x32_bf16 v[72:75], v[160:163], v[210:213], v[72:75]
	v_mfma_f32_16x16x32_bf16 v[64:67], v[168:171], v[210:213], v[64:67]
	v_mfma_f32_16x16x32_bf16 v[120:123], v[164:167], v[180:183], v[120:123]
	v_mfma_f32_16x16x32_bf16 v[112:115], v[172:175], v[180:183], v[112:115]
	v_mfma_f32_16x16x32_bf16 v[104:107], v[164:167], v[198:201], v[104:107]
	v_mfma_f32_16x16x32_bf16 v[96:99], v[172:175], v[198:201], v[96:99]
	v_mfma_f32_16x16x32_bf16 v[88:91], v[164:167], v[206:209], v[88:91]
	v_mfma_f32_16x16x32_bf16 v[80:83], v[172:175], v[206:209], v[80:83]
	v_mfma_f32_16x16x32_bf16 v[72:75], v[164:167], v[214:217], v[72:75]
	v_mfma_f32_16x16x32_bf16 v[64:67], v[172:175], v[214:217], v[64:67]
	s_setprio 0
	s_barrier
	v_lshl_add_u64 v[138:139], s[60:61], 0, v[184:185]
	s_add_i32 s60, s70, s6
	s_mov_b32 m0, s60
	ds_read_b128 v[176:179], v146 offset:16384
	ds_read_b128 v[180:183], v146 offset:17408
	ds_read_b128 v[194:197], v146 offset:18432
	ds_read_b128 v[198:201], v146 offset:19456
	ds_read_b128 v[202:205], v146 offset:20480
	ds_read_b128 v[206:209], v146 offset:21504
	ds_read_b128 v[210:213], v146 offset:22528
	ds_read_b128 v[214:217], v146 offset:23552
	global_load_lds_dwordx4 v[138:139], off
	v_lshl_add_u64 v[218:219], v[138:139], 0, s[34:35]
	s_add_i32 m0, s60, 0x2000
	s_add_i32 s60, s84, s6
	global_load_lds_dwordx4 v[218:219], off
	v_lshl_add_u64 v[218:219], v[138:139], 0, s[92:93]
	s_mov_b32 m0, s60
	s_nop 0
	global_load_lds_dwordx4 v[218:219], off
	v_lshl_add_u64 v[218:219], v[138:139], 0, s[52:53]
	s_add_i32 m0, s60, 0x2000
	s_nop 0
	global_load_lds_dwordx4 v[218:219], off
	v_lshl_add_u64 v[218:219], s[14:15], 0, v[128:129]
	s_mov_b32 m0, s19
	v_lshl_add_u64 v[220:221], v[218:219], 0, s[34:35]
	global_load_lds_dwordx4 v[218:219], off
	s_mov_b32 m0, s20
	s_nop 0
	global_load_lds_dwordx4 v[220:221], off
	s_waitcnt vmcnt(8)
	s_waitcnt lgkmcnt(0)
	s_barrier
	s_setprio 1
	v_mfma_f32_16x16x32_bf16 v[60:63], v[134:137], v[176:179], v[60:63]
	v_mfma_f32_16x16x32_bf16 v[52:55], v[152:155], v[176:179], v[52:55]
	v_mfma_f32_16x16x32_bf16 v[44:47], v[134:137], v[194:197], v[44:47]
	v_mfma_f32_16x16x32_bf16 v[36:39], v[152:155], v[194:197], v[36:39]
	v_mfma_f32_16x16x32_bf16 v[28:31], v[134:137], v[202:205], v[28:31]
	v_mfma_f32_16x16x32_bf16 v[20:23], v[152:155], v[202:205], v[20:23]
	v_mfma_f32_16x16x32_bf16 v[12:15], v[134:137], v[210:213], v[12:15]
	v_mfma_f32_16x16x32_bf16 v[4:7], v[152:155], v[210:213], v[4:7]
	v_mfma_f32_16x16x32_bf16 v[60:63], v[148:151], v[180:183], v[60:63]
	v_mfma_f32_16x16x32_bf16 v[52:55], v[156:159], v[180:183], v[52:55]
	v_mfma_f32_16x16x32_bf16 v[44:47], v[148:151], v[198:201], v[44:47]
	v_mfma_f32_16x16x32_bf16 v[36:39], v[156:159], v[198:201], v[36:39]
	v_mfma_f32_16x16x32_bf16 v[28:31], v[148:151], v[206:209], v[28:31]
	v_mfma_f32_16x16x32_bf16 v[20:23], v[156:159], v[206:209], v[20:23]
	v_mfma_f32_16x16x32_bf16 v[12:15], v[148:151], v[214:217], v[12:15]
	v_mfma_f32_16x16x32_bf16 v[4:7], v[156:159], v[214:217], v[4:7]
	v_mfma_f32_16x16x32_bf16 v[56:59], v[160:163], v[176:179], v[56:59]
	v_mfma_f32_16x16x32_bf16 v[48:51], v[168:171], v[176:179], v[48:51]
	v_mfma_f32_16x16x32_bf16 v[40:43], v[160:163], v[194:197], v[40:43]
	v_mfma_f32_16x16x32_bf16 v[32:35], v[168:171], v[194:197], v[32:35]
	v_mfma_f32_16x16x32_bf16 v[24:27], v[160:163], v[202:205], v[24:27]
	v_mfma_f32_16x16x32_bf16 v[16:19], v[168:171], v[202:205], v[16:19]
	v_mfma_f32_16x16x32_bf16 v[8:11], v[160:163], v[210:213], v[8:11]
	v_mfma_f32_16x16x32_bf16 v[0:3], v[168:171], v[210:213], v[0:3]
	v_mfma_f32_16x16x32_bf16 v[56:59], v[164:167], v[180:183], v[56:59]
	v_mfma_f32_16x16x32_bf16 v[48:51], v[172:175], v[180:183], v[48:51]
	v_mfma_f32_16x16x32_bf16 v[40:43], v[164:167], v[198:201], v[40:43]
	v_mfma_f32_16x16x32_bf16 v[32:35], v[172:175], v[198:201], v[32:35]
	v_mfma_f32_16x16x32_bf16 v[24:27], v[164:167], v[206:209], v[24:27]
	v_mfma_f32_16x16x32_bf16 v[16:19], v[172:175], v[206:209], v[16:19]
	v_mfma_f32_16x16x32_bf16 v[8:11], v[164:167], v[214:217], v[8:11]
	v_mfma_f32_16x16x32_bf16 v[0:3], v[172:175], v[214:217], v[0:3]
	s_setprio 0
	s_barrier
	s_add_i32 s14, 0, 0x18000
	v_add_u32_e32 v147, s14, v142
	s_add_i32 s15, 0, 0x1c000
	ds_read_b128 v[134:137], v147
	ds_read_b128 v[148:151], v147 offset:1024
	ds_read_b128 v[152:155], v147 offset:2048
	ds_read_b128 v[156:159], v147 offset:3072
	v_add_u32_e32 v147, s15, v142
	ds_read_b128 v[160:163], v147
	ds_read_b128 v[164:167], v147 offset:1024
	ds_read_b128 v[168:171], v147 offset:2048
	ds_read_b128 v[172:175], v147 offset:3072
	s_mov_b32 m0, s24
	v_lshl_add_u64 v[220:221], v[218:219], 0, s[92:93]
	ds_read_b128 v[176:179], v146 offset:32768
	ds_read_b128 v[180:183], v146 offset:33792
	ds_read_b128 v[194:197], v146 offset:34816
	ds_read_b128 v[198:201], v146 offset:35840
	ds_read_b128 v[202:205], v146 offset:36864
	ds_read_b128 v[206:209], v146 offset:37888
	ds_read_b128 v[210:213], v146 offset:38912
	ds_read_b128 v[214:217], v146 offset:39936
	global_load_lds_dwordx4 v[220:221], off
	v_lshl_add_u64 v[220:221], v[218:219], 0, s[52:53]
	s_mov_b32 m0, s25
	s_nop 0
	global_load_lds_dwordx4 v[220:221], off
	s_waitcnt vmcnt(8)
	s_waitcnt lgkmcnt(0)
	s_barrier
	s_setprio 1
	v_mfma_f32_16x16x32_bf16 v[124:127], v[134:137], v[176:179], v[124:127]
	v_mfma_f32_16x16x32_bf16 v[116:119], v[152:155], v[176:179], v[116:119]
	v_mfma_f32_16x16x32_bf16 v[108:111], v[134:137], v[194:197], v[108:111]
	v_mfma_f32_16x16x32_bf16 v[100:103], v[152:155], v[194:197], v[100:103]
	v_mfma_f32_16x16x32_bf16 v[92:95], v[134:137], v[202:205], v[92:95]
	v_mfma_f32_16x16x32_bf16 v[84:87], v[152:155], v[202:205], v[84:87]
	v_mfma_f32_16x16x32_bf16 v[76:79], v[134:137], v[210:213], v[76:79]
	v_mfma_f32_16x16x32_bf16 v[68:71], v[152:155], v[210:213], v[68:71]
	v_mfma_f32_16x16x32_bf16 v[124:127], v[148:151], v[180:183], v[124:127]
	v_mfma_f32_16x16x32_bf16 v[116:119], v[156:159], v[180:183], v[116:119]
	v_mfma_f32_16x16x32_bf16 v[108:111], v[148:151], v[198:201], v[108:111]
	v_mfma_f32_16x16x32_bf16 v[100:103], v[156:159], v[198:201], v[100:103]
	v_mfma_f32_16x16x32_bf16 v[92:95], v[148:151], v[206:209], v[92:95]
	v_mfma_f32_16x16x32_bf16 v[84:87], v[156:159], v[206:209], v[84:87]
	v_mfma_f32_16x16x32_bf16 v[76:79], v[148:151], v[214:217], v[76:79]
	v_mfma_f32_16x16x32_bf16 v[68:71], v[156:159], v[214:217], v[68:71]
	v_mfma_f32_16x16x32_bf16 v[120:123], v[160:163], v[176:179], v[120:123]
	v_mfma_f32_16x16x32_bf16 v[112:115], v[168:171], v[176:179], v[112:115]
	v_mfma_f32_16x16x32_bf16 v[104:107], v[160:163], v[194:197], v[104:107]
	v_mfma_f32_16x16x32_bf16 v[96:99], v[168:171], v[194:197], v[96:99]
	v_mfma_f32_16x16x32_bf16 v[88:91], v[160:163], v[202:205], v[88:91]
	v_mfma_f32_16x16x32_bf16 v[80:83], v[168:171], v[202:205], v[80:83]
	v_mfma_f32_16x16x32_bf16 v[72:75], v[160:163], v[210:213], v[72:75]
	v_mfma_f32_16x16x32_bf16 v[64:67], v[168:171], v[210:213], v[64:67]
	v_mfma_f32_16x16x32_bf16 v[120:123], v[164:167], v[180:183], v[120:123]
	v_mfma_f32_16x16x32_bf16 v[112:115], v[172:175], v[180:183], v[112:115]
	v_mfma_f32_16x16x32_bf16 v[104:107], v[164:167], v[198:201], v[104:107]
	v_mfma_f32_16x16x32_bf16 v[96:99], v[172:175], v[198:201], v[96:99]
	v_mfma_f32_16x16x32_bf16 v[88:91], v[164:167], v[206:209], v[88:91]
	v_mfma_f32_16x16x32_bf16 v[80:83], v[172:175], v[206:209], v[80:83]
	v_mfma_f32_16x16x32_bf16 v[72:75], v[164:167], v[214:217], v[72:75]
	v_mfma_f32_16x16x32_bf16 v[64:67], v[172:175], v[214:217], v[64:67]
	s_setprio 0
	s_barrier
	s_add_i32 s14, s14, s6
	v_lshl_add_u64 v[220:221], v[138:139], 0, s[56:57]
	s_mov_b32 m0, s14
	ds_read_b128 v[176:179], v146 offset:49152
	ds_read_b128 v[180:183], v146 offset:50176
	ds_read_b128 v[194:197], v146 offset:51200
	ds_read_b128 v[198:201], v146 offset:52224
	ds_read_b128 v[202:205], v146 offset:53248
	ds_read_b128 v[206:209], v146 offset:54272
	ds_read_b128 v[210:213], v146 offset:55296
	ds_read_b128 v[214:217], v146 offset:56320
	global_load_lds_dwordx4 v[220:221], off
	v_lshl_add_u64 v[220:221], v[138:139], 0, s[96:97]
	s_add_i32 m0, s14, 0x2000
	s_add_i32 s14, s15, s6
	global_load_lds_dwordx4 v[220:221], off
	v_lshl_add_u64 v[220:221], v[138:139], 0, s[88:89]
	s_mov_b32 m0, s14
	v_lshl_add_u64 v[138:139], v[138:139], 0, s[68:69]
	global_load_lds_dwordx4 v[220:221], off
	s_add_i32 m0, s14, 0x2000
	s_nop 0
	global_load_lds_dwordx4 v[138:139], off
	v_lshl_add_u64 v[138:139], v[218:219], 0, s[56:57]
	s_mov_b32 m0, s26
	s_nop 0
	global_load_lds_dwordx4 v[138:139], off
	v_lshl_add_u64 v[138:139], v[218:219], 0, s[96:97]
	s_mov_b32 m0, s27
	s_nop 0
	global_load_lds_dwordx4 v[138:139], off
	s_waitcnt vmcnt(8)
	s_waitcnt lgkmcnt(0)
	s_barrier
	s_setprio 1
	v_mfma_f32_16x16x32_bf16 v[60:63], v[134:137], v[176:179], v[60:63]
	v_mfma_f32_16x16x32_bf16 v[52:55], v[152:155], v[176:179], v[52:55]
	v_mfma_f32_16x16x32_bf16 v[44:47], v[134:137], v[194:197], v[44:47]
	v_mfma_f32_16x16x32_bf16 v[36:39], v[152:155], v[194:197], v[36:39]
	v_mfma_f32_16x16x32_bf16 v[28:31], v[134:137], v[202:205], v[28:31]
	v_mfma_f32_16x16x32_bf16 v[20:23], v[152:155], v[202:205], v[20:23]
	v_mfma_f32_16x16x32_bf16 v[12:15], v[134:137], v[210:213], v[12:15]
	v_mfma_f32_16x16x32_bf16 v[4:7], v[152:155], v[210:213], v[4:7]
	v_mfma_f32_16x16x32_bf16 v[60:63], v[148:151], v[180:183], v[60:63]
	v_mfma_f32_16x16x32_bf16 v[52:55], v[156:159], v[180:183], v[52:55]
	v_mfma_f32_16x16x32_bf16 v[44:47], v[148:151], v[198:201], v[44:47]
	v_mfma_f32_16x16x32_bf16 v[36:39], v[156:159], v[198:201], v[36:39]
	v_mfma_f32_16x16x32_bf16 v[28:31], v[148:151], v[206:209], v[28:31]
	v_mfma_f32_16x16x32_bf16 v[20:23], v[156:159], v[206:209], v[20:23]
	v_mfma_f32_16x16x32_bf16 v[12:15], v[148:151], v[214:217], v[12:15]
	v_mfma_f32_16x16x32_bf16 v[4:7], v[156:159], v[214:217], v[4:7]
	v_mfma_f32_16x16x32_bf16 v[56:59], v[160:163], v[176:179], v[56:59]
	v_mfma_f32_16x16x32_bf16 v[48:51], v[168:171], v[176:179], v[48:51]
	v_mfma_f32_16x16x32_bf16 v[40:43], v[160:163], v[194:197], v[40:43]
	v_mfma_f32_16x16x32_bf16 v[32:35], v[168:171], v[194:197], v[32:35]
	v_mfma_f32_16x16x32_bf16 v[24:27], v[160:163], v[202:205], v[24:27]
	v_mfma_f32_16x16x32_bf16 v[16:19], v[168:171], v[202:205], v[16:19]
	v_mfma_f32_16x16x32_bf16 v[8:11], v[160:163], v[210:213], v[8:11]
	v_mfma_f32_16x16x32_bf16 v[0:3], v[168:171], v[210:213], v[0:3]
	v_mfma_f32_16x16x32_bf16 v[56:59], v[164:167], v[180:183], v[56:59]
	v_mfma_f32_16x16x32_bf16 v[48:51], v[172:175], v[180:183], v[48:51]
	v_mfma_f32_16x16x32_bf16 v[40:43], v[164:167], v[198:201], v[40:43]
	v_mfma_f32_16x16x32_bf16 v[32:35], v[172:175], v[198:201], v[32:35]
	v_mfma_f32_16x16x32_bf16 v[24:27], v[164:167], v[206:209], v[24:27]
	v_mfma_f32_16x16x32_bf16 v[16:19], v[172:175], v[206:209], v[16:19]
	v_mfma_f32_16x16x32_bf16 v[8:11], v[164:167], v[214:217], v[8:11]
	v_mfma_f32_16x16x32_bf16 v[0:3], v[172:175], v[214:217], v[0:3]
	s_setprio 0
	s_barrier
	s_add_i32 s51, s51, 2
	s_add_u32 s48, s48, 0x100
	s_addc_u32 s49, s49, 0
	s_add_u32 s16, s16, 0x100
	s_addc_u32 s17, s17, 0
	s_cmp_gt_u32 s51, 13
	s_cbranch_scc0 .LBB0_459
	s_and_b64 vcc, exec, s[10:11]
	s_cbranch_vccz .LBB0_462
	s_barrier

.LBB0_480:
	s_ashr_i32 s41, s40, 31
	s_lshl_b64 s[42:43], s[40:41], 19
	s_add_u32 s42, s64, s42
	s_addc_u32 s43, s65, s43
	s_and_b64 s[44:45], s[38:39], exec
	s_cselect_b32 s31, s43, s17
	s_cselect_b32 s41, s42, s16
	s_ashr_i32 s13, s12, 31
	s_lshl_b64 s[44:45], s[12:13], 19
	s_add_u32 s44, s22, s44
	s_addc_u32 s45, s23, s45
	s_and_b64 s[46:47], s[38:39], exec
	s_cselect_b32 s13, s45, s15
	s_cselect_b32 s48, s44, s14
	s_add_u32 s46, s16, 0x40080
	s_addc_u32 s47, s17, 0
	s_add_u32 s16, s14, 0x100
	s_addc_u32 s17, s15, 0
	s_mov_b32 s49, -2
	s_add_u32 s14, s46, 0xfffc0080
	s_addc_u32 s15, s47, -1
	s_add_i32 s60, 0, 0x10000
	s_cmp_eq_u32 s49, 12
	s_cselect_b32 s15, s31, s15
	s_cselect_b32 s14, s41, s14
	v_add_u32_e32 v135, s60, v143
	s_cselect_b32 s51, s13, s17
	s_cselect_b32 s50, s48, s16
	s_add_i32 s61, 0, 0x14000
	ds_read_b128 v[136:139], v135
	ds_read_b128 v[148:151], v135 offset:1024
	ds_read_b128 v[152:155], v135 offset:2048
	ds_read_b128 v[156:159], v135 offset:3072
	v_add_u32_e32 v135, s61, v143
	ds_read_b128 v[160:163], v135
	ds_read_b128 v[164:167], v135 offset:1024
	ds_read_b128 v[168:171], v135 offset:2048
	ds_read_b128 v[172:175], v135 offset:3072
	v_lshl_add_u64 v[140:141], s[46:47], 0, v[184:185]
	s_add_i32 m0, s19, 0xc000
	ds_read_b128 v[176:179], v147
	ds_read_b128 v[180:183], v147 offset:1024
	ds_read_b128 v[194:197], v147 offset:2048
	ds_read_b128 v[198:201], v147 offset:3072
	ds_read_b128 v[202:205], v147 offset:4096
	ds_read_b128 v[206:209], v147 offset:5120
	ds_read_b128 v[210:213], v147 offset:6144
	ds_read_b128 v[214:217], v147 offset:7168
	global_load_lds_dwordx4 v[140:141], off
	v_lshl_add_u64 v[140:141], v[140:141], 0, s[34:35]
	s_add_i32 m0, s19, 0xe000
	s_nop 0
	global_load_lds_dwordx4 v[140:141], off
	s_waitcnt vmcnt(8)
	s_waitcnt lgkmcnt(0)
	s_barrier
	s_setprio 1
	v_mfma_f32_16x16x32_bf16 v[124:127], v[136:139], v[176:179], 0
	v_mfma_f32_16x16x32_bf16 v[116:119], v[152:155], v[176:179], 0
	v_mfma_f32_16x16x32_bf16 v[108:111], v[136:139], v[194:197], 0
	v_mfma_f32_16x16x32_bf16 v[100:103], v[152:155], v[194:197], 0
	v_mfma_f32_16x16x32_bf16 v[92:95], v[136:139], v[202:205], 0
	v_mfma_f32_16x16x32_bf16 v[84:87], v[152:155], v[202:205], 0
	v_mfma_f32_16x16x32_bf16 v[76:79], v[136:139], v[210:213], 0
	v_mfma_f32_16x16x32_bf16 v[68:71], v[152:155], v[210:213], 0
	v_mfma_f32_16x16x32_bf16 v[124:127], v[148:151], v[180:183], v[124:127]
	v_mfma_f32_16x16x32_bf16 v[116:119], v[156:159], v[180:183], v[116:119]
	v_mfma_f32_16x16x32_bf16 v[108:111], v[148:151], v[198:201], v[108:111]
	v_mfma_f32_16x16x32_bf16 v[100:103], v[156:159], v[198:201], v[100:103]
	v_mfma_f32_16x16x32_bf16 v[92:95], v[148:151], v[206:209], v[92:95]
	v_mfma_f32_16x16x32_bf16 v[84:87], v[156:159], v[206:209], v[84:87]
	v_mfma_f32_16x16x32_bf16 v[76:79], v[148:151], v[214:217], v[76:79]
	v_mfma_f32_16x16x32_bf16 v[68:71], v[156:159], v[214:217], v[68:71]
	v_mfma_f32_16x16x32_bf16 v[120:123], v[160:163], v[176:179], 0
	v_mfma_f32_16x16x32_bf16 v[112:115], v[168:171], v[176:179], 0
	v_mfma_f32_16x16x32_bf16 v[104:107], v[160:163], v[194:197], 0
	v_mfma_f32_16x16x32_bf16 v[96:99], v[168:171], v[194:197], 0
	v_mfma_f32_16x16x32_bf16 v[88:91], v[160:163], v[202:205], 0
	v_mfma_f32_16x16x32_bf16 v[80:83], v[168:171], v[202:205], 0
	v_mfma_f32_16x16x32_bf16 v[72:75], v[160:163], v[210:213], 0
	v_mfma_f32_16x16x32_bf16 v[64:67], v[168:171], v[210:213], 0
	v_mfma_f32_16x16x32_bf16 v[120:123], v[164:167], v[180:183], v[120:123]
	v_mfma_f32_16x16x32_bf16 v[112:115], v[172:175], v[180:183], v[112:115]
	v_mfma_f32_16x16x32_bf16 v[104:107], v[164:167], v[198:201], v[104:107]
	v_mfma_f32_16x16x32_bf16 v[96:99], v[172:175], v[198:201], v[96:99]
	v_mfma_f32_16x16x32_bf16 v[88:91], v[164:167], v[206:209], v[88:91]
	v_mfma_f32_16x16x32_bf16 v[80:83], v[172:175], v[206:209], v[80:83]
	v_mfma_f32_16x16x32_bf16 v[72:75], v[164:167], v[214:217], v[72:75]
	v_mfma_f32_16x16x32_bf16 v[64:67], v[172:175], v[214:217], v[64:67]
	s_setprio 0
	s_barrier
	v_lshl_add_u64 v[140:141], s[50:51], 0, v[128:129]
	s_add_i32 s50, s60, s6
	s_mov_b32 m0, s50
	ds_read_b128 v[176:179], v147 offset:16384
	ds_read_b128 v[180:183], v147 offset:17408
	ds_read_b128 v[194:197], v147 offset:18432
	ds_read_b128 v[198:201], v147 offset:19456
	ds_read_b128 v[202:205], v147 offset:20480
	ds_read_b128 v[206:209], v147 offset:21504
	ds_read_b128 v[210:213], v147 offset:22528
	ds_read_b128 v[214:217], v147 offset:23552
	global_load_lds_dwordx4 v[140:141], off
	v_lshl_add_u64 v[218:219], v[140:141], 0, s[34:35]
	s_add_i32 m0, s50, 0x2000
	s_add_i32 s50, s61, s6
	global_load_lds_dwordx4 v[218:219], off
	v_lshl_add_u64 v[218:219], v[140:141], 0, s[92:93]
	s_mov_b32 m0, s50
	s_nop 0
	global_load_lds_dwordx4 v[218:219], off
	v_lshl_add_u64 v[218:219], v[140:141], 0, s[52:53]
	s_add_i32 m0, s50, 0x2000
	s_nop 0
	global_load_lds_dwordx4 v[218:219], off
	v_lshl_add_u64 v[218:219], s[14:15], 0, v[130:131]
	s_mov_b32 m0, s19
	v_lshl_add_u64 v[220:221], v[218:219], 0, s[34:35]
	global_load_lds_dwordx4 v[218:219], off
	s_mov_b32 m0, s20
	s_nop 0
	global_load_lds_dwordx4 v[220:221], off
	s_waitcnt vmcnt(8)
	s_waitcnt lgkmcnt(0)
	s_barrier
	s_setprio 1
	v_mfma_f32_16x16x32_bf16 v[60:63], v[136:139], v[176:179], 0
	v_mfma_f32_16x16x32_bf16 v[52:55], v[152:155], v[176:179], 0
	v_mfma_f32_16x16x32_bf16 v[44:47], v[136:139], v[194:197], 0
	v_mfma_f32_16x16x32_bf16 v[36:39], v[152:155], v[194:197], 0
	v_mfma_f32_16x16x32_bf16 v[28:31], v[136:139], v[202:205], 0
	v_mfma_f32_16x16x32_bf16 v[20:23], v[152:155], v[202:205], 0
	v_mfma_f32_16x16x32_bf16 v[12:15], v[136:139], v[210:213], 0
	v_mfma_f32_16x16x32_bf16 v[4:7], v[152:155], v[210:213], 0
	v_mfma_f32_16x16x32_bf16 v[60:63], v[148:151], v[180:183], v[60:63]
	v_mfma_f32_16x16x32_bf16 v[52:55], v[156:159], v[180:183], v[52:55]
	v_mfma_f32_16x16x32_bf16 v[44:47], v[148:151], v[198:201], v[44:47]
	v_mfma_f32_16x16x32_bf16 v[36:39], v[156:159], v[198:201], v[36:39]
	v_mfma_f32_16x16x32_bf16 v[28:31], v[148:151], v[206:209], v[28:31]
	v_mfma_f32_16x16x32_bf16 v[20:23], v[156:159], v[206:209], v[20:23]
	v_mfma_f32_16x16x32_bf16 v[12:15], v[148:151], v[214:217], v[12:15]
	v_mfma_f32_16x16x32_bf16 v[4:7], v[156:159], v[214:217], v[4:7]
	v_mfma_f32_16x16x32_bf16 v[56:59], v[160:163], v[176:179], 0
	v_mfma_f32_16x16x32_bf16 v[48:51], v[168:171], v[176:179], 0
	v_mfma_f32_16x16x32_bf16 v[40:43], v[160:163], v[194:197], 0
	v_mfma_f32_16x16x32_bf16 v[32:35], v[168:171], v[194:197], 0
	v_mfma_f32_16x16x32_bf16 v[24:27], v[160:163], v[202:205], 0
	v_mfma_f32_16x16x32_bf16 v[16:19], v[168:171], v[202:205], 0
	v_mfma_f32_16x16x32_bf16 v[8:11], v[160:163], v[210:213], 0
	v_mfma_f32_16x16x32_bf16 v[0:3], v[168:171], v[210:213], 0
	v_mfma_f32_16x16x32_bf16 v[56:59], v[164:167], v[180:183], v[56:59]
	v_mfma_f32_16x16x32_bf16 v[48:51], v[172:175], v[180:183], v[48:51]
	v_mfma_f32_16x16x32_bf16 v[40:43], v[164:167], v[198:201], v[40:43]
	v_mfma_f32_16x16x32_bf16 v[32:35], v[172:175], v[198:201], v[32:35]
	v_mfma_f32_16x16x32_bf16 v[24:27], v[164:167], v[206:209], v[24:27]
	v_mfma_f32_16x16x32_bf16 v[16:19], v[172:175], v[206:209], v[16:19]
	v_mfma_f32_16x16x32_bf16 v[8:11], v[164:167], v[214:217], v[8:11]
	v_mfma_f32_16x16x32_bf16 v[0:3], v[172:175], v[214:217], v[0:3]
	s_setprio 0
	s_barrier
	s_add_i32 s14, 0, 0x18000
	v_add_u32_e32 v135, s14, v143
	s_add_i32 s15, 0, 0x1c000
	ds_read_b128 v[136:139], v135
	ds_read_b128 v[148:151], v135 offset:1024
	ds_read_b128 v[152:155], v135 offset:2048
	ds_read_b128 v[156:159], v135 offset:3072
	v_add_u32_e32 v135, s15, v143
	ds_read_b128 v[160:163], v135
	ds_read_b128 v[164:167], v135 offset:1024
	ds_read_b128 v[168:171], v135 offset:2048
	ds_read_b128 v[172:175], v135 offset:3072
	s_mov_b32 m0, s24
	v_lshl_add_u64 v[220:221], v[218:219], 0, s[92:93]
	ds_read_b128 v[176:179], v147 offset:32768
	ds_read_b128 v[180:183], v147 offset:33792
	ds_read_b128 v[194:197], v147 offset:34816
	ds_read_b128 v[198:201], v147 offset:35840
	ds_read_b128 v[202:205], v147 offset:36864
	ds_read_b128 v[206:209], v147 offset:37888
	ds_read_b128 v[210:213], v147 offset:38912
	ds_read_b128 v[214:217], v147 offset:39936
	global_load_lds_dwordx4 v[220:221], off
	v_lshl_add_u64 v[220:221], v[218:219], 0, s[52:53]
	s_mov_b32 m0, s25
	s_nop 0
	global_load_lds_dwordx4 v[220:221], off
	s_waitcnt vmcnt(8)
	s_waitcnt lgkmcnt(0)
	s_barrier
	s_setprio 1
	v_mfma_f32_16x16x32_bf16 v[124:127], v[136:139], v[176:179], v[124:127]
	v_mfma_f32_16x16x32_bf16 v[116:119], v[152:155], v[176:179], v[116:119]
	v_mfma_f32_16x16x32_bf16 v[108:111], v[136:139], v[194:197], v[108:111]
	v_mfma_f32_16x16x32_bf16 v[100:103], v[152:155], v[194:197], v[100:103]
	v_mfma_f32_16x16x32_bf16 v[92:95], v[136:139], v[202:205], v[92:95]
	v_mfma_f32_16x16x32_bf16 v[84:87], v[152:155], v[202:205], v[84:87]
	v_mfma_f32_16x16x32_bf16 v[76:79], v[136:139], v[210:213], v[76:79]
	v_mfma_f32_16x16x32_bf16 v[68:71], v[152:155], v[210:213], v[68:71]
	v_mfma_f32_16x16x32_bf16 v[124:127], v[148:151], v[180:183], v[124:127]
	v_mfma_f32_16x16x32_bf16 v[116:119], v[156:159], v[180:183], v[116:119]
	v_mfma_f32_16x16x32_bf16 v[108:111], v[148:151], v[198:201], v[108:111]
	v_mfma_f32_16x16x32_bf16 v[100:103], v[156:159], v[198:201], v[100:103]
	v_mfma_f32_16x16x32_bf16 v[92:95], v[148:151], v[206:209], v[92:95]
	v_mfma_f32_16x16x32_bf16 v[84:87], v[156:159], v[206:209], v[84:87]
	v_mfma_f32_16x16x32_bf16 v[76:79], v[148:151], v[214:217], v[76:79]
	v_mfma_f32_16x16x32_bf16 v[68:71], v[156:159], v[214:217], v[68:71]
	v_mfma_f32_16x16x32_bf16 v[120:123], v[160:163], v[176:179], v[120:123]
	v_mfma_f32_16x16x32_bf16 v[112:115], v[168:171], v[176:179], v[112:115]
	v_mfma_f32_16x16x32_bf16 v[104:107], v[160:163], v[194:197], v[104:107]
	v_mfma_f32_16x16x32_bf16 v[96:99], v[168:171], v[194:197], v[96:99]
	v_mfma_f32_16x16x32_bf16 v[88:91], v[160:163], v[202:205], v[88:91]
	v_mfma_f32_16x16x32_bf16 v[80:83], v[168:171], v[202:205], v[80:83]
	v_mfma_f32_16x16x32_bf16 v[72:75], v[160:163], v[210:213], v[72:75]
	v_mfma_f32_16x16x32_bf16 v[64:67], v[168:171], v[210:213], v[64:67]
	v_mfma_f32_16x16x32_bf16 v[120:123], v[164:167], v[180:183], v[120:123]
	v_mfma_f32_16x16x32_bf16 v[112:115], v[172:175], v[180:183], v[112:115]
	v_mfma_f32_16x16x32_bf16 v[104:107], v[164:167], v[198:201], v[104:107]
	v_mfma_f32_16x16x32_bf16 v[96:99], v[172:175], v[198:201], v[96:99]
	v_mfma_f32_16x16x32_bf16 v[88:91], v[164:167], v[206:209], v[88:91]
	v_mfma_f32_16x16x32_bf16 v[80:83], v[172:175], v[206:209], v[80:83]
	v_mfma_f32_16x16x32_bf16 v[72:75], v[164:167], v[214:217], v[72:75]
	v_mfma_f32_16x16x32_bf16 v[64:67], v[172:175], v[214:217], v[64:67]
	s_setprio 0
	s_barrier
	s_add_i32 s14, s14, s6
	v_lshl_add_u64 v[220:221], v[140:141], 0, s[56:57]
	s_mov_b32 m0, s14
	ds_read_b128 v[176:179], v147 offset:49152
	ds_read_b128 v[180:183], v147 offset:50176
	ds_read_b128 v[194:197], v147 offset:51200
	ds_read_b128 v[198:201], v147 offset:52224
	ds_read_b128 v[202:205], v147 offset:53248
	ds_read_b128 v[206:209], v147 offset:54272
	ds_read_b128 v[210:213], v147 offset:55296
	ds_read_b128 v[214:217], v147 offset:56320
	global_load_lds_dwordx4 v[220:221], off
	v_lshl_add_u64 v[220:221], v[140:141], 0, s[96:97]
	s_add_i32 m0, s14, 0x2000
	s_add_i32 s14, s15, s6
	global_load_lds_dwordx4 v[220:221], off
	v_lshl_add_u64 v[220:221], v[140:141], 0, s[88:89]
	s_mov_b32 m0, s14
	v_lshl_add_u64 v[140:141], v[140:141], 0, s[68:69]
	global_load_lds_dwordx4 v[220:221], off
	s_add_i32 m0, s14, 0x2000
	s_nop 0
	global_load_lds_dwordx4 v[140:141], off
	v_lshl_add_u64 v[140:141], v[218:219], 0, s[56:57]
	s_mov_b32 m0, s26
	s_nop 0
	global_load_lds_dwordx4 v[140:141], off
	v_lshl_add_u64 v[140:141], v[218:219], 0, s[96:97]
	s_mov_b32 m0, s27
	s_nop 0
	global_load_lds_dwordx4 v[140:141], off
	s_waitcnt vmcnt(8)
	s_waitcnt lgkmcnt(0)
	s_barrier
	s_setprio 1
	v_mfma_f32_16x16x32_bf16 v[60:63], v[136:139], v[176:179], v[60:63]
	v_mfma_f32_16x16x32_bf16 v[52:55], v[152:155], v[176:179], v[52:55]
	v_mfma_f32_16x16x32_bf16 v[44:47], v[136:139], v[194:197], v[44:47]
	v_mfma_f32_16x16x32_bf16 v[36:39], v[152:155], v[194:197], v[36:39]
	v_mfma_f32_16x16x32_bf16 v[28:31], v[136:139], v[202:205], v[28:31]
	v_mfma_f32_16x16x32_bf16 v[20:23], v[152:155], v[202:205], v[20:23]
	v_mfma_f32_16x16x32_bf16 v[12:15], v[136:139], v[210:213], v[12:15]
	v_mfma_f32_16x16x32_bf16 v[4:7], v[152:155], v[210:213], v[4:7]
	v_mfma_f32_16x16x32_bf16 v[60:63], v[148:151], v[180:183], v[60:63]
	v_mfma_f32_16x16x32_bf16 v[52:55], v[156:159], v[180:183], v[52:55]
	v_mfma_f32_16x16x32_bf16 v[44:47], v[148:151], v[198:201], v[44:47]
	v_mfma_f32_16x16x32_bf16 v[36:39], v[156:159], v[198:201], v[36:39]
	v_mfma_f32_16x16x32_bf16 v[28:31], v[148:151], v[206:209], v[28:31]
	v_mfma_f32_16x16x32_bf16 v[20:23], v[156:159], v[206:209], v[20:23]
	v_mfma_f32_16x16x32_bf16 v[12:15], v[148:151], v[214:217], v[12:15]
	v_mfma_f32_16x16x32_bf16 v[4:7], v[156:159], v[214:217], v[4:7]
	v_mfma_f32_16x16x32_bf16 v[56:59], v[160:163], v[176:179], v[56:59]
	v_mfma_f32_16x16x32_bf16 v[48:51], v[168:171], v[176:179], v[48:51]
	v_mfma_f32_16x16x32_bf16 v[40:43], v[160:163], v[194:197], v[40:43]
	v_mfma_f32_16x16x32_bf16 v[32:35], v[168:171], v[194:197], v[32:35]
	v_mfma_f32_16x16x32_bf16 v[24:27], v[160:163], v[202:205], v[24:27]
	v_mfma_f32_16x16x32_bf16 v[16:19], v[168:171], v[202:205], v[16:19]
	v_mfma_f32_16x16x32_bf16 v[8:11], v[160:163], v[210:213], v[8:11]
	v_mfma_f32_16x16x32_bf16 v[0:3], v[168:171], v[210:213], v[0:3]
	v_mfma_f32_16x16x32_bf16 v[56:59], v[164:167], v[180:183], v[56:59]
	v_mfma_f32_16x16x32_bf16 v[48:51], v[172:175], v[180:183], v[48:51]
	v_mfma_f32_16x16x32_bf16 v[40:43], v[164:167], v[198:201], v[40:43]
	v_mfma_f32_16x16x32_bf16 v[32:35], v[172:175], v[198:201], v[32:35]
	v_mfma_f32_16x16x32_bf16 v[24:27], v[164:167], v[206:209], v[24:27]
	v_mfma_f32_16x16x32_bf16 v[16:19], v[172:175], v[206:209], v[16:19]
	v_mfma_f32_16x16x32_bf16 v[8:11], v[164:167], v[214:217], v[8:11]
	v_mfma_f32_16x16x32_bf16 v[0:3], v[172:175], v[214:217], v[0:3]
	s_setprio 0
	s_barrier
	s_add_i32 s49, s49, 2
	s_add_u32 s46, s46, 0x100
	s_addc_u32 s47, s47, 0
	s_add_u32 s16, s16, 0x100
	s_addc_u32 s17, s17, 0
	s_cmp_gt_u32 s49, 13
.LBB0_481:
	s_add_u32 s14, s46, 0xfffc0080
	s_addc_u32 s15, s47, -1
	s_add_i32 s60, 0, 0x10000
	s_cmp_eq_u32 s49, 12
	s_cselect_b32 s15, s31, s15
	s_cselect_b32 s14, s41, s14
	v_add_u32_e32 v135, s60, v143
	s_cselect_b32 s51, s13, s17
	s_cselect_b32 s50, s48, s16
	s_add_i32 s61, 0, 0x14000
	ds_read_b128 v[136:139], v135
	ds_read_b128 v[148:151], v135 offset:1024
	ds_read_b128 v[152:155], v135 offset:2048
	ds_read_b128 v[156:159], v135 offset:3072
	v_add_u32_e32 v135, s61, v143
	ds_read_b128 v[160:163], v135
	ds_read_b128 v[164:167], v135 offset:1024
	ds_read_b128 v[168:171], v135 offset:2048
	ds_read_b128 v[172:175], v135 offset:3072
	v_lshl_add_u64 v[140:141], s[46:47], 0, v[184:185]
	s_add_i32 m0, s19, 0xc000
	ds_read_b128 v[176:179], v147
	ds_read_b128 v[180:183], v147 offset:1024
	ds_read_b128 v[194:197], v147 offset:2048
	ds_read_b128 v[198:201], v147 offset:3072
	ds_read_b128 v[202:205], v147 offset:4096
	ds_read_b128 v[206:209], v147 offset:5120
	ds_read_b128 v[210:213], v147 offset:6144
	ds_read_b128 v[214:217], v147 offset:7168
	global_load_lds_dwordx4 v[140:141], off
	v_lshl_add_u64 v[140:141], v[140:141], 0, s[34:35]
	s_add_i32 m0, s19, 0xe000
	s_nop 0
	global_load_lds_dwordx4 v[140:141], off
	s_waitcnt vmcnt(8)
	s_waitcnt lgkmcnt(0)
	s_barrier
	s_setprio 1
	v_mfma_f32_16x16x32_bf16 v[124:127], v[136:139], v[176:179], v[124:127]
	v_mfma_f32_16x16x32_bf16 v[116:119], v[152:155], v[176:179], v[116:119]
	v_mfma_f32_16x16x32_bf16 v[108:111], v[136:139], v[194:197], v[108:111]
	v_mfma_f32_16x16x32_bf16 v[100:103], v[152:155], v[194:197], v[100:103]
	v_mfma_f32_16x16x32_bf16 v[92:95], v[136:139], v[202:205], v[92:95]
	v_mfma_f32_16x16x32_bf16 v[84:87], v[152:155], v[202:205], v[84:87]
	v_mfma_f32_16x16x32_bf16 v[76:79], v[136:139], v[210:213], v[76:79]
	v_mfma_f32_16x16x32_bf16 v[68:71], v[152:155], v[210:213], v[68:71]
	v_mfma_f32_16x16x32_bf16 v[124:127], v[148:151], v[180:183], v[124:127]
	v_mfma_f32_16x16x32_bf16 v[116:119], v[156:159], v[180:183], v[116:119]
	v_mfma_f32_16x16x32_bf16 v[108:111], v[148:151], v[198:201], v[108:111]
	v_mfma_f32_16x16x32_bf16 v[100:103], v[156:159], v[198:201], v[100:103]
	v_mfma_f32_16x16x32_bf16 v[92:95], v[148:151], v[206:209], v[92:95]
	v_mfma_f32_16x16x32_bf16 v[84:87], v[156:159], v[206:209], v[84:87]
	v_mfma_f32_16x16x32_bf16 v[76:79], v[148:151], v[214:217], v[76:79]
	v_mfma_f32_16x16x32_bf16 v[68:71], v[156:159], v[214:217], v[68:71]
	v_mfma_f32_16x16x32_bf16 v[120:123], v[160:163], v[176:179], v[120:123]
	v_mfma_f32_16x16x32_bf16 v[112:115], v[168:171], v[176:179], v[112:115]
	v_mfma_f32_16x16x32_bf16 v[104:107], v[160:163], v[194:197], v[104:107]
	v_mfma_f32_16x16x32_bf16 v[96:99], v[168:171], v[194:197], v[96:99]
	v_mfma_f32_16x16x32_bf16 v[88:91], v[160:163], v[202:205], v[88:91]
	v_mfma_f32_16x16x32_bf16 v[80:83], v[168:171], v[202:205], v[80:83]
	v_mfma_f32_16x16x32_bf16 v[72:75], v[160:163], v[210:213], v[72:75]
	v_mfma_f32_16x16x32_bf16 v[64:67], v[168:171], v[210:213], v[64:67]
	v_mfma_f32_16x16x32_bf16 v[120:123], v[164:167], v[180:183], v[120:123]
	v_mfma_f32_16x16x32_bf16 v[112:115], v[172:175], v[180:183], v[112:115]
	v_mfma_f32_16x16x32_bf16 v[104:107], v[164:167], v[198:201], v[104:107]
	v_mfma_f32_16x16x32_bf16 v[96:99], v[172:175], v[198:201], v[96:99]
	v_mfma_f32_16x16x32_bf16 v[88:91], v[164:167], v[206:209], v[88:91]
	v_mfma_f32_16x16x32_bf16 v[80:83], v[172:175], v[206:209], v[80:83]
	v_mfma_f32_16x16x32_bf16 v[72:75], v[164:167], v[214:217], v[72:75]
	v_mfma_f32_16x16x32_bf16 v[64:67], v[172:175], v[214:217], v[64:67]
	s_setprio 0
	s_barrier
	v_lshl_add_u64 v[140:141], s[50:51], 0, v[128:129]
	s_add_i32 s50, s60, s6
	s_mov_b32 m0, s50
	ds_read_b128 v[176:179], v147 offset:16384
	ds_read_b128 v[180:183], v147 offset:17408
	ds_read_b128 v[194:197], v147 offset:18432
	ds_read_b128 v[198:201], v147 offset:19456
	ds_read_b128 v[202:205], v147 offset:20480
	ds_read_b128 v[206:209], v147 offset:21504
	ds_read_b128 v[210:213], v147 offset:22528
	ds_read_b128 v[214:217], v147 offset:23552
	global_load_lds_dwordx4 v[140:141], off
	v_lshl_add_u64 v[218:219], v[140:141], 0, s[34:35]
	s_add_i32 m0, s50, 0x2000
	s_add_i32 s50, s61, s6
	global_load_lds_dwordx4 v[218:219], off
	v_lshl_add_u64 v[218:219], v[140:141], 0, s[92:93]
	s_mov_b32 m0, s50
	s_nop 0
	global_load_lds_dwordx4 v[218:219], off
	v_lshl_add_u64 v[218:219], v[140:141], 0, s[52:53]
	s_add_i32 m0, s50, 0x2000
	s_nop 0
	global_load_lds_dwordx4 v[218:219], off
	v_lshl_add_u64 v[218:219], s[14:15], 0, v[130:131]
	s_mov_b32 m0, s19
	v_lshl_add_u64 v[220:221], v[218:219], 0, s[34:35]
	global_load_lds_dwordx4 v[218:219], off
	s_mov_b32 m0, s20
	s_nop 0
	global_load_lds_dwordx4 v[220:221], off
	s_waitcnt vmcnt(8)
	s_waitcnt lgkmcnt(0)
	s_barrier
	s_setprio 1
	v_mfma_f32_16x16x32_bf16 v[60:63], v[136:139], v[176:179], v[60:63]
	v_mfma_f32_16x16x32_bf16 v[52:55], v[152:155], v[176:179], v[52:55]
	v_mfma_f32_16x16x32_bf16 v[44:47], v[136:139], v[194:197], v[44:47]
	v_mfma_f32_16x16x32_bf16 v[36:39], v[152:155], v[194:197], v[36:39]
	v_mfma_f32_16x16x32_bf16 v[28:31], v[136:139], v[202:205], v[28:31]
	v_mfma_f32_16x16x32_bf16 v[20:23], v[152:155], v[202:205], v[20:23]
	v_mfma_f32_16x16x32_bf16 v[12:15], v[136:139], v[210:213], v[12:15]
	v_mfma_f32_16x16x32_bf16 v[4:7], v[152:155], v[210:213], v[4:7]
	v_mfma_f32_16x16x32_bf16 v[60:63], v[148:151], v[180:183], v[60:63]
	v_mfma_f32_16x16x32_bf16 v[52:55], v[156:159], v[180:183], v[52:55]
	v_mfma_f32_16x16x32_bf16 v[44:47], v[148:151], v[198:201], v[44:47]
	v_mfma_f32_16x16x32_bf16 v[36:39], v[156:159], v[198:201], v[36:39]
	v_mfma_f32_16x16x32_bf16 v[28:31], v[148:151], v[206:209], v[28:31]
	v_mfma_f32_16x16x32_bf16 v[20:23], v[156:159], v[206:209], v[20:23]
	v_mfma_f32_16x16x32_bf16 v[12:15], v[148:151], v[214:217], v[12:15]
	v_mfma_f32_16x16x32_bf16 v[4:7], v[156:159], v[214:217], v[4:7]
	v_mfma_f32_16x16x32_bf16 v[56:59], v[160:163], v[176:179], v[56:59]
	v_mfma_f32_16x16x32_bf16 v[48:51], v[168:171], v[176:179], v[48:51]
	v_mfma_f32_16x16x32_bf16 v[40:43], v[160:163], v[194:197], v[40:43]
	v_mfma_f32_16x16x32_bf16 v[32:35], v[168:171], v[194:197], v[32:35]
	v_mfma_f32_16x16x32_bf16 v[24:27], v[160:163], v[202:205], v[24:27]
	v_mfma_f32_16x16x32_bf16 v[16:19], v[168:171], v[202:205], v[16:19]
	v_mfma_f32_16x16x32_bf16 v[8:11], v[160:163], v[210:213], v[8:11]
	v_mfma_f32_16x16x32_bf16 v[0:3], v[168:171], v[210:213], v[0:3]
	v_mfma_f32_16x16x32_bf16 v[56:59], v[164:167], v[180:183], v[56:59]
	v_mfma_f32_16x16x32_bf16 v[48:51], v[172:175], v[180:183], v[48:51]
	v_mfma_f32_16x16x32_bf16 v[40:43], v[164:167], v[198:201], v[40:43]
	v_mfma_f32_16x16x32_bf16 v[32:35], v[172:175], v[198:201], v[32:35]
	v_mfma_f32_16x16x32_bf16 v[24:27], v[164:167], v[206:209], v[24:27]
	v_mfma_f32_16x16x32_bf16 v[16:19], v[172:175], v[206:209], v[16:19]
	v_mfma_f32_16x16x32_bf16 v[8:11], v[164:167], v[214:217], v[8:11]
	v_mfma_f32_16x16x32_bf16 v[0:3], v[172:175], v[214:217], v[0:3]
	s_setprio 0
	s_barrier
	s_add_i32 s14, 0, 0x18000
	v_add_u32_e32 v135, s14, v143
	s_add_i32 s15, 0, 0x1c000
	ds_read_b128 v[136:139], v135
	ds_read_b128 v[148:151], v135 offset:1024
	ds_read_b128 v[152:155], v135 offset:2048
	ds_read_b128 v[156:159], v135 offset:3072
	v_add_u32_e32 v135, s15, v143
	ds_read_b128 v[160:163], v135
	ds_read_b128 v[164:167], v135 offset:1024
	ds_read_b128 v[168:171], v135 offset:2048
	ds_read_b128 v[172:175], v135 offset:3072
	s_mov_b32 m0, s24
	v_lshl_add_u64 v[220:221], v[218:219], 0, s[92:93]
	ds_read_b128 v[176:179], v147 offset:32768
	ds_read_b128 v[180:183], v147 offset:33792
	ds_read_b128 v[194:197], v147 offset:34816
	ds_read_b128 v[198:201], v147 offset:35840
	ds_read_b128 v[202:205], v147 offset:36864
	ds_read_b128 v[206:209], v147 offset:37888
	ds_read_b128 v[210:213], v147 offset:38912
	ds_read_b128 v[214:217], v147 offset:39936
	global_load_lds_dwordx4 v[220:221], off
	v_lshl_add_u64 v[220:221], v[218:219], 0, s[52:53]
	s_mov_b32 m0, s25
	s_nop 0
	global_load_lds_dwordx4 v[220:221], off
	s_waitcnt vmcnt(8)
	s_waitcnt lgkmcnt(0)
	s_barrier
	s_setprio 1
	v_mfma_f32_16x16x32_bf16 v[124:127], v[136:139], v[176:179], v[124:127]
	v_mfma_f32_16x16x32_bf16 v[116:119], v[152:155], v[176:179], v[116:119]
	v_mfma_f32_16x16x32_bf16 v[108:111], v[136:139], v[194:197], v[108:111]
	v_mfma_f32_16x16x32_bf16 v[100:103], v[152:155], v[194:197], v[100:103]
	v_mfma_f32_16x16x32_bf16 v[92:95], v[136:139], v[202:205], v[92:95]
	v_mfma_f32_16x16x32_bf16 v[84:87], v[152:155], v[202:205], v[84:87]
	v_mfma_f32_16x16x32_bf16 v[76:79], v[136:139], v[210:213], v[76:79]
	v_mfma_f32_16x16x32_bf16 v[68:71], v[152:155], v[210:213], v[68:71]
	v_mfma_f32_16x16x32_bf16 v[124:127], v[148:151], v[180:183], v[124:127]
	v_mfma_f32_16x16x32_bf16 v[116:119], v[156:159], v[180:183], v[116:119]
	v_mfma_f32_16x16x32_bf16 v[108:111], v[148:151], v[198:201], v[108:111]
	v_mfma_f32_16x16x32_bf16 v[100:103], v[156:159], v[198:201], v[100:103]
	v_mfma_f32_16x16x32_bf16 v[92:95], v[148:151], v[206:209], v[92:95]
	v_mfma_f32_16x16x32_bf16 v[84:87], v[156:159], v[206:209], v[84:87]
	v_mfma_f32_16x16x32_bf16 v[76:79], v[148:151], v[214:217], v[76:79]
	v_mfma_f32_16x16x32_bf16 v[68:71], v[156:159], v[214:217], v[68:71]
	v_mfma_f32_16x16x32_bf16 v[120:123], v[160:163], v[176:179], v[120:123]
	v_mfma_f32_16x16x32_bf16 v[112:115], v[168:171], v[176:179], v[112:115]
	v_mfma_f32_16x16x32_bf16 v[104:107], v[160:163], v[194:197], v[104:107]
	v_mfma_f32_16x16x32_bf16 v[96:99], v[168:171], v[194:197], v[96:99]
	v_mfma_f32_16x16x32_bf16 v[88:91], v[160:163], v[202:205], v[88:91]
	v_mfma_f32_16x16x32_bf16 v[80:83], v[168:171], v[202:205], v[80:83]
	v_mfma_f32_16x16x32_bf16 v[72:75], v[160:163], v[210:213], v[72:75]
	v_mfma_f32_16x16x32_bf16 v[64:67], v[168:171], v[210:213], v[64:67]
	v_mfma_f32_16x16x32_bf16 v[120:123], v[164:167], v[180:183], v[120:123]
	v_mfma_f32_16x16x32_bf16 v[112:115], v[172:175], v[180:183], v[112:115]
	v_mfma_f32_16x16x32_bf16 v[104:107], v[164:167], v[198:201], v[104:107]
	v_mfma_f32_16x16x32_bf16 v[96:99], v[172:175], v[198:201], v[96:99]
	v_mfma_f32_16x16x32_bf16 v[88:91], v[164:167], v[206:209], v[88:91]
	v_mfma_f32_16x16x32_bf16 v[80:83], v[172:175], v[206:209], v[80:83]
	v_mfma_f32_16x16x32_bf16 v[72:75], v[164:167], v[214:217], v[72:75]
	v_mfma_f32_16x16x32_bf16 v[64:67], v[172:175], v[214:217], v[64:67]
	s_setprio 0
	s_barrier
	s_add_i32 s14, s14, s6
	v_lshl_add_u64 v[220:221], v[140:141], 0, s[56:57]
	s_mov_b32 m0, s14
	ds_read_b128 v[176:179], v147 offset:49152
	ds_read_b128 v[180:183], v147 offset:50176
	ds_read_b128 v[194:197], v147 offset:51200
	ds_read_b128 v[198:201], v147 offset:52224
	ds_read_b128 v[202:205], v147 offset:53248
	ds_read_b128 v[206:209], v147 offset:54272
	ds_read_b128 v[210:213], v147 offset:55296
	ds_read_b128 v[214:217], v147 offset:56320
	global_load_lds_dwordx4 v[220:221], off
	v_lshl_add_u64 v[220:221], v[140:141], 0, s[96:97]
	s_add_i32 m0, s14, 0x2000
	s_add_i32 s14, s15, s6
	global_load_lds_dwordx4 v[220:221], off
	v_lshl_add_u64 v[220:221], v[140:141], 0, s[88:89]
	s_mov_b32 m0, s14
	v_lshl_add_u64 v[140:141], v[140:141], 0, s[68:69]
	global_load_lds_dwordx4 v[220:221], off
	s_add_i32 m0, s14, 0x2000
	s_nop 0
	global_load_lds_dwordx4 v[140:141], off
	v_lshl_add_u64 v[140:141], v[218:219], 0, s[56:57]
	s_mov_b32 m0, s26
	s_nop 0
	global_load_lds_dwordx4 v[140:141], off
	v_lshl_add_u64 v[140:141], v[218:219], 0, s[96:97]
	s_mov_b32 m0, s27
	s_nop 0
	global_load_lds_dwordx4 v[140:141], off
	s_waitcnt vmcnt(8)
	s_waitcnt lgkmcnt(0)
	s_barrier
	s_setprio 1
	v_mfma_f32_16x16x32_bf16 v[60:63], v[136:139], v[176:179], v[60:63]
	v_mfma_f32_16x16x32_bf16 v[52:55], v[152:155], v[176:179], v[52:55]
	v_mfma_f32_16x16x32_bf16 v[44:47], v[136:139], v[194:197], v[44:47]
	v_mfma_f32_16x16x32_bf16 v[36:39], v[152:155], v[194:197], v[36:39]
	v_mfma_f32_16x16x32_bf16 v[28:31], v[136:139], v[202:205], v[28:31]
	v_mfma_f32_16x16x32_bf16 v[20:23], v[152:155], v[202:205], v[20:23]
	v_mfma_f32_16x16x32_bf16 v[12:15], v[136:139], v[210:213], v[12:15]
	v_mfma_f32_16x16x32_bf16 v[4:7], v[152:155], v[210:213], v[4:7]
	v_mfma_f32_16x16x32_bf16 v[60:63], v[148:151], v[180:183], v[60:63]
	v_mfma_f32_16x16x32_bf16 v[52:55], v[156:159], v[180:183], v[52:55]
	v_mfma_f32_16x16x32_bf16 v[44:47], v[148:151], v[198:201], v[44:47]
	v_mfma_f32_16x16x32_bf16 v[36:39], v[156:159], v[198:201], v[36:39]
	v_mfma_f32_16x16x32_bf16 v[28:31], v[148:151], v[206:209], v[28:31]
	v_mfma_f32_16x16x32_bf16 v[20:23], v[156:159], v[206:209], v[20:23]
	v_mfma_f32_16x16x32_bf16 v[12:15], v[148:151], v[214:217], v[12:15]
	v_mfma_f32_16x16x32_bf16 v[4:7], v[156:159], v[214:217], v[4:7]
	v_mfma_f32_16x16x32_bf16 v[56:59], v[160:163], v[176:179], v[56:59]
	v_mfma_f32_16x16x32_bf16 v[48:51], v[168:171], v[176:179], v[48:51]
	v_mfma_f32_16x16x32_bf16 v[40:43], v[160:163], v[194:197], v[40:43]
	v_mfma_f32_16x16x32_bf16 v[32:35], v[168:171], v[194:197], v[32:35]
	v_mfma_f32_16x16x32_bf16 v[24:27], v[160:163], v[202:205], v[24:27]
	v_mfma_f32_16x16x32_bf16 v[16:19], v[168:171], v[202:205], v[16:19]
	v_mfma_f32_16x16x32_bf16 v[8:11], v[160:163], v[210:213], v[8:11]
	v_mfma_f32_16x16x32_bf16 v[0:3], v[168:171], v[210:213], v[0:3]
	v_mfma_f32_16x16x32_bf16 v[56:59], v[164:167], v[180:183], v[56:59]
	v_mfma_f32_16x16x32_bf16 v[48:51], v[172:175], v[180:183], v[48:51]
	v_mfma_f32_16x16x32_bf16 v[40:43], v[164:167], v[198:201], v[40:43]
	v_mfma_f32_16x16x32_bf16 v[32:35], v[172:175], v[198:201], v[32:35]
	v_mfma_f32_16x16x32_bf16 v[24:27], v[164:167], v[206:209], v[24:27]
	v_mfma_f32_16x16x32_bf16 v[16:19], v[172:175], v[206:209], v[16:19]
	v_mfma_f32_16x16x32_bf16 v[8:11], v[164:167], v[214:217], v[8:11]
	v_mfma_f32_16x16x32_bf16 v[0:3], v[172:175], v[214:217], v[0:3]
	s_setprio 0
	s_barrier
	s_add_i32 s49, s49, 2
	s_add_u32 s46, s46, 0x100
	s_addc_u32 s47, s47, 0
	s_add_u32 s16, s16, 0x100
	s_addc_u32 s17, s17, 0
	s_cmp_gt_u32 s49, 13
	s_cbranch_scc0 .LBB0_481
	s_and_b64 vcc, exec, s[10:11]
	s_cbranch_vccz .LBB0_484
	s_barrier
